# K-loop MFMA segments: setprio 1 hoisted in front of the opening barrier, redundant lgkmcnt(0) after it dropped, setprio 0 moved behind the closing barrier
# speedup vs baseline: 1.0132x; 1.0132x over previous
; #define PG8_STAGE(bufoff, gbase, voff) do { _Pragma("unroll") for (int _i = 0; _i < 2; ++_i) \
;         __builtin_amdgcn_global_load_lds((const unsigned*)((const char*)(gbase) + (voff)[_i]), (LAS unsigned*)(lds + (bufoff) + ldsw + _i * 8192), 16, 0, 0); } while (0)
; #define PG8_LDA(dst, b, h) do { _Pragma("unroll") for (int m = 0; m < 4; ++m) _Pragma("unroll") for (int k = 0; k < 2; ++k) dst[m][k] = *(const LAS bf16x8*)(lds + PG8_SA(b, h) + aoff + m * 2048 + k * 1024); } while (0)
; #define PG8_LDB(dst, b, h) do { _Pragma("unroll") for (int n = 0; n < 2; ++n) _Pragma("unroll") for (int k = 0; k < 2; ++k) dst[n][k] = *(const LAS bf16x8*)(lds + PG8_SB(b, h) + boff + n * 2048 + k * 1024); } while (0)
; #define PG8_MMA(ai, bj, At, Bt) do { __builtin_amdgcn_s_setprio(1); _Pragma("unroll") for (int m = 0; m < 4; ++m) _Pragma("unroll") for (int n = 0; n < 2; ++n) _Pragma("unroll") for (int k = 0; k < 2; ++k) \
;         acc[ai][bj][m][n] = __builtin_amdgcn_mfma_f32_16x16x32_bf16(Bt[n][k], At[m][k], acc[ai][bj][m][n], 0, 0, 0); __builtin_amdgcn_s_setprio(0); } while (0)
; #define PG8_WAIT_V(n) asm volatile("s_waitcnt vmcnt(" #n ")" ::: "memory")
; template <class Epi, class Sched>
; __device__ __forceinline__ void gemm_phase(LAS unsigned char* lds, const Gemm g, const Sched& S, const Epi& E) {
;     ...
;         for (int t = 0; t < nt; t += 2) {
;             if constexpr (Epi::HOOKS) { if (cur.kind == 3 && (t == 4 || t == 12)) { int fr_ = fr, fq_ = fq; asm volatile("" : "+v"(fr_), "+v"(fq_)); E.hook(acc, cur, t == 4 ? 0 : 1, wr, wc, fr_, fq_); } }
;             const bool last = (t == nt - 2);
;             const char* a1 = cA + (size_t)(t + 1) * kstep;
;             const char* a2 = last ? nA : cA + (size_t)(t + 2) * kstep; const char* b2 = last ? nB : cB + (size_t)(t + 2) * kstep;
;             const char* a3 = a2 + kstep; const char* b3 = b2 + kstep;
;             PG8_LDB(B0, 0, 0); PG8_LDB(B1, 0, 1); PG8_SCHED; PG8_LDA(At, 0, 0); PG8_STAGE(PG8_SA(1, 1), a1 + hstepA, voffA);
;             PG8_WAIT_V(8); PG8_WAIT_L(0); PG8_BAR; PG8_MMA(0, 0, At, B0); PG8_MMA(0, 1, At, B1); PG8_BAR; PG8_SCHED;
;             PG8_LDA(At, 0, 1); PG8_STAGE(PG8_SB(0, 0), b2, voffB); PG8_STAGE(PG8_SB(0, 1), b2 + hstepB, voffB); PG8_STAGE(PG8_SA(0, 0), a2, voffA);
;             PG8_WAIT_V(8); PG8_WAIT_L(0); PG8_BAR; PG8_MMA(1, 0, At, B0); PG8_MMA(1, 1, At, B1); PG8_BAR; PG8_SCHED;
.LBB0_101:
	s_add_i32 s68, s0, 2
	s_add_u32 s1, s20, 0xfff00080
	s_addc_u32 s42, s21, -1
	s_add_i32 s52, 0, 0x10000
	s_cmp_eq_u32 s72, s0
	s_cselect_b32 s43, s41, s42
	s_cselect_b32 s42, s48, s1
	s_cselect_b32 s1, s85, s94
	s_cselect_b32 s0, s87, s93
	s_add_i32 s53, 0, 0x14000
	v_add_u32_e32 v152, s52, v166
	v_add_u32_e32 v172, s53, v166
	ds_read_b128 v[130:133], v152
	ds_read_b128 v[134:137], v152 offset:1024
	ds_read_b128 v[138:141], v152 offset:2048
	ds_read_b128 v[152:155], v152 offset:3072
	ds_read_b128 v[156:159], v172
	ds_read_b128 v[160:163], v172 offset:1024
	ds_read_b128 v[168:171], v172 offset:2048
	ds_read_b128 v[172:175], v172 offset:3072
	v_lshl_add_u64 v[184:185], s[20:21], 0, v[150:151]
	s_add_i32 m0, s15, 0xc000
	ds_read_b128 v[176:179], v167
	ds_read_b128 v[180:183], v167 offset:1024
	ds_read_b128 v[196:199], v167 offset:2048
	ds_read_b128 v[200:203], v167 offset:3072
	ds_read_b128 v[204:207], v167 offset:4096
	ds_read_b128 v[208:211], v167 offset:5120
	ds_read_b128 v[212:215], v167 offset:6144
	ds_read_b128 v[216:219], v167 offset:7168
	global_load_lds_dwordx4 v[184:185], off
	v_lshl_add_u64 v[184:185], s[20:21], 0, v[148:149]
	s_add_i32 m0, s15, 0xe000
	s_nop 0
	global_load_lds_dwordx4 v[184:185], off
	s_waitcnt vmcnt(8)
	s_waitcnt lgkmcnt(0)
	s_setprio 1
	s_barrier
	v_mfma_f32_16x16x32_bf16 v[126:129], v[130:133], v[176:179], v[126:129]
	v_mfma_f32_16x16x32_bf16 v[122:125], v[138:141], v[176:179], v[122:125]
	v_mfma_f32_16x16x32_bf16 v[110:113], v[130:133], v[196:199], v[110:113]
	v_mfma_f32_16x16x32_bf16 v[106:109], v[138:141], v[196:199], v[106:109]
	v_mfma_f32_16x16x32_bf16 v[94:97], v[130:133], v[204:207], v[94:97]
	v_mfma_f32_16x16x32_bf16 v[90:93], v[138:141], v[204:207], v[90:93]
	v_mfma_f32_16x16x32_bf16 v[78:81], v[130:133], v[212:215], v[78:81]
	v_mfma_f32_16x16x32_bf16 v[74:77], v[138:141], v[212:215], v[74:77]
	v_mfma_f32_16x16x32_bf16 v[126:129], v[134:137], v[180:183], v[126:129]
	v_mfma_f32_16x16x32_bf16 v[122:125], v[152:155], v[180:183], v[122:125]
	v_mfma_f32_16x16x32_bf16 v[110:113], v[134:137], v[200:203], v[110:113]
	v_mfma_f32_16x16x32_bf16 v[106:109], v[152:155], v[200:203], v[106:109]
	v_mfma_f32_16x16x32_bf16 v[94:97], v[134:137], v[208:211], v[94:97]
	v_mfma_f32_16x16x32_bf16 v[90:93], v[152:155], v[208:211], v[90:93]
	v_mfma_f32_16x16x32_bf16 v[78:81], v[134:137], v[216:219], v[78:81]
	v_mfma_f32_16x16x32_bf16 v[74:77], v[152:155], v[216:219], v[74:77]
	v_mfma_f32_16x16x32_bf16 v[118:121], v[156:159], v[176:179], v[118:121]
	v_mfma_f32_16x16x32_bf16 v[114:117], v[168:171], v[176:179], v[114:117]
	v_mfma_f32_16x16x32_bf16 v[102:105], v[156:159], v[196:199], v[102:105]
	v_mfma_f32_16x16x32_bf16 v[98:101], v[168:171], v[196:199], v[98:101]
	v_mfma_f32_16x16x32_bf16 v[86:89], v[156:159], v[204:207], v[86:89]
	v_mfma_f32_16x16x32_bf16 v[82:85], v[168:171], v[204:207], v[82:85]
	v_mfma_f32_16x16x32_bf16 v[70:73], v[156:159], v[212:215], v[70:73]
	v_mfma_f32_16x16x32_bf16 v[66:69], v[168:171], v[212:215], v[66:69]
	v_mfma_f32_16x16x32_bf16 v[118:121], v[160:163], v[180:183], v[118:121]
	v_mfma_f32_16x16x32_bf16 v[114:117], v[172:175], v[180:183], v[114:117]
	v_mfma_f32_16x16x32_bf16 v[102:105], v[160:163], v[200:203], v[102:105]
	v_mfma_f32_16x16x32_bf16 v[98:101], v[172:175], v[200:203], v[98:101]
	v_mfma_f32_16x16x32_bf16 v[86:89], v[160:163], v[208:211], v[86:89]
	v_mfma_f32_16x16x32_bf16 v[82:85], v[172:175], v[208:211], v[82:85]
	v_mfma_f32_16x16x32_bf16 v[70:73], v[160:163], v[216:219], v[70:73]
	v_mfma_f32_16x16x32_bf16 v[66:69], v[172:175], v[216:219], v[66:69]
	s_barrier
	s_setprio 0
	s_add_i32 s52, s52, s14
	v_lshl_add_u64 v[184:185], s[0:1], 0, v[0:1]
	s_mov_b32 m0, s52
	ds_read_b128 v[176:179], v167 offset:16384
	ds_read_b128 v[180:183], v167 offset:17408
	ds_read_b128 v[196:199], v167 offset:18432
	ds_read_b128 v[200:203], v167 offset:19456
	ds_read_b128 v[204:207], v167 offset:20480
	ds_read_b128 v[208:211], v167 offset:21504
	ds_read_b128 v[212:215], v167 offset:22528
	ds_read_b128 v[216:219], v167 offset:23552
	global_load_lds_dwordx4 v[184:185], off
	s_add_i32 m0, s52, 0x2000
	s_add_u32 s96, s0, 0x100000
	v_lshl_add_u64 v[220:221], s[0:1], 0, v[146:147]
	s_addc_u32 s97, s1, 0
	s_add_i32 s52, s53, s14
	global_load_lds_dwordx4 v[220:221], off
	v_lshl_add_u64 v[232:233], s[96:97], 0, v[0:1]
	s_mov_b32 m0, s52
	v_lshl_add_u64 v[234:235], s[42:43], 0, v[144:145]
	global_load_lds_dwordx4 v[232:233], off
	v_lshl_add_u64 v[232:233], s[96:97], 0, v[146:147]
	s_add_i32 m0, s52, 0x2000
	s_nop 0
	global_load_lds_dwordx4 v[232:233], off
	v_lshl_add_u64 v[232:233], s[42:43], 0, v[142:143]
	s_mov_b32 m0, s15
	s_nop 0
	global_load_lds_dwordx4 v[232:233], off
	s_mov_b32 m0, s16
	s_nop 0
	global_load_lds_dwordx4 v[234:235], off
	s_waitcnt vmcnt(8)
	s_waitcnt lgkmcnt(0)
	s_setprio 1
	s_barrier
; #define PG8_STAGE(bufoff, gbase, voff) do { _Pragma("unroll") for (int _i = 0; _i < 2; ++_i) \
;         __builtin_amdgcn_global_load_lds((const unsigned*)((const char*)(gbase) + (voff)[_i]), (LAS unsigned*)(lds + (bufoff) + ldsw + _i * 8192), 16, 0, 0); } while (0)
; #define PG8_LDA(dst, b, h) do { _Pragma("unroll") for (int m = 0; m < 4; ++m) _Pragma("unroll") for (int k = 0; k < 2; ++k) dst[m][k] = *(const LAS bf16x8*)(lds + PG8_SA(b, h) + aoff + m * 2048 + k * 1024); } while (0)
; #define PG8_LDB(dst, b, h) do { _Pragma("unroll") for (int n = 0; n < 2; ++n) _Pragma("unroll") for (int k = 0; k < 2; ++k) dst[n][k] = *(const LAS bf16x8*)(lds + PG8_SB(b, h) + boff + n * 2048 + k * 1024); } while (0)
; #define PG8_MMA(ai, bj, At, Bt) do { __builtin_amdgcn_s_setprio(1); _Pragma("unroll") for (int m = 0; m < 4; ++m) _Pragma("unroll") for (int n = 0; n < 2; ++n) _Pragma("unroll") for (int k = 0; k < 2; ++k) \
;         acc[ai][bj][m][n] = __builtin_amdgcn_mfma_f32_16x16x32_bf16(Bt[n][k], At[m][k], acc[ai][bj][m][n], 0, 0, 0); __builtin_amdgcn_s_setprio(0); } while (0)
; #define PG8_WAIT_V(n) asm volatile("s_waitcnt vmcnt(" #n ")" ::: "memory")
; #define PG8_WAIT_L(n) asm volatile("s_waitcnt lgkmcnt(" #n ")" ::: "memory")
; #define PG8_BAR __builtin_amdgcn_s_barrier()
; #define PG8_SCHED __builtin_amdgcn_sched_barrier(0)
; template <class Epi, class Sched>
; __device__ __forceinline__ void gemm_phase(LAS unsigned char* lds, const Gemm g, const Sched& S, const Epi& E) {
;     ...
;             PG8_WAIT_V(8); PG8_WAIT_L(0); PG8_BAR; PG8_MMA(1, 0, At, B0); PG8_MMA(1, 1, At, B1); PG8_BAR; PG8_SCHED;
;             PG8_LDB(B0, 1, 0); PG8_LDB(B1, 1, 1); PG8_SCHED; PG8_LDA(At, 1, 0); PG8_STAGE(PG8_SA(0, 1), a2 + hstepA, voffA);
;             PG8_WAIT_V(8); PG8_WAIT_L(0); PG8_BAR; PG8_MMA(0, 0, At, B0); PG8_MMA(0, 1, At, B1); PG8_BAR; PG8_SCHED;
	v_mfma_f32_16x16x32_bf16 v[62:65], v[130:133], v[176:179], v[62:65]
	v_mfma_f32_16x16x32_bf16 v[58:61], v[138:141], v[176:179], v[58:61]
	v_mfma_f32_16x16x32_bf16 v[46:49], v[130:133], v[196:199], v[46:49]
	v_mfma_f32_16x16x32_bf16 v[42:45], v[138:141], v[196:199], v[42:45]
	v_mfma_f32_16x16x32_bf16 v[30:33], v[130:133], v[204:207], v[30:33]
	v_mfma_f32_16x16x32_bf16 v[26:29], v[138:141], v[204:207], v[26:29]
	v_mfma_f32_16x16x32_bf16 v[14:17], v[130:133], v[212:215], v[14:17]
	v_mfma_f32_16x16x32_bf16 v[10:13], v[138:141], v[212:215], v[10:13]
	v_mfma_f32_16x16x32_bf16 v[62:65], v[134:137], v[180:183], v[62:65]
	v_mfma_f32_16x16x32_bf16 v[58:61], v[152:155], v[180:183], v[58:61]
	v_mfma_f32_16x16x32_bf16 v[46:49], v[134:137], v[200:203], v[46:49]
	v_mfma_f32_16x16x32_bf16 v[42:45], v[152:155], v[200:203], v[42:45]
	v_mfma_f32_16x16x32_bf16 v[30:33], v[134:137], v[208:211], v[30:33]
	v_mfma_f32_16x16x32_bf16 v[26:29], v[152:155], v[208:211], v[26:29]
	v_mfma_f32_16x16x32_bf16 v[14:17], v[134:137], v[216:219], v[14:17]
	v_mfma_f32_16x16x32_bf16 v[10:13], v[152:155], v[216:219], v[10:13]
	v_mfma_f32_16x16x32_bf16 v[54:57], v[156:159], v[176:179], v[54:57]
	v_mfma_f32_16x16x32_bf16 v[50:53], v[168:171], v[176:179], v[50:53]
	v_mfma_f32_16x16x32_bf16 v[38:41], v[156:159], v[196:199], v[38:41]
	v_mfma_f32_16x16x32_bf16 v[34:37], v[168:171], v[196:199], v[34:37]
	v_mfma_f32_16x16x32_bf16 v[22:25], v[156:159], v[204:207], v[22:25]
	v_mfma_f32_16x16x32_bf16 v[18:21], v[168:171], v[204:207], v[18:21]
	v_mfma_f32_16x16x32_bf16 v[6:9], v[156:159], v[212:215], v[6:9]
	v_mfma_f32_16x16x32_bf16 v[2:5], v[168:171], v[212:215], v[2:5]
	v_mfma_f32_16x16x32_bf16 v[54:57], v[160:163], v[180:183], v[54:57]
	v_mfma_f32_16x16x32_bf16 v[50:53], v[172:175], v[180:183], v[50:53]
	v_mfma_f32_16x16x32_bf16 v[38:41], v[160:163], v[200:203], v[38:41]
	v_mfma_f32_16x16x32_bf16 v[34:37], v[172:175], v[200:203], v[34:37]
	v_mfma_f32_16x16x32_bf16 v[22:25], v[160:163], v[208:211], v[22:25]
	v_mfma_f32_16x16x32_bf16 v[18:21], v[172:175], v[208:211], v[18:21]
	v_mfma_f32_16x16x32_bf16 v[6:9], v[160:163], v[216:219], v[6:9]
	v_mfma_f32_16x16x32_bf16 v[2:5], v[172:175], v[216:219], v[2:5]
	s_barrier
	s_setprio 0
	s_add_i32 s52, 0, 0x18000
	s_add_i32 s53, 0, 0x1c000
	v_add_u32_e32 v152, s52, v166
	v_add_u32_e32 v172, s53, v166
	ds_read_b128 v[130:133], v152
	ds_read_b128 v[134:137], v152 offset:1024
	ds_read_b128 v[138:141], v152 offset:2048
	ds_read_b128 v[152:155], v152 offset:3072
	ds_read_b128 v[156:159], v172
	ds_read_b128 v[160:163], v172 offset:1024
	ds_read_b128 v[168:171], v172 offset:2048
	ds_read_b128 v[172:175], v172 offset:3072
	s_add_u32 s42, s42, 0x100000
	s_addc_u32 s43, s43, 0
	s_mov_b32 m0, s17
	v_lshl_add_u64 v[236:237], s[42:43], 0, v[142:143]
	ds_read_b128 v[176:179], v167 offset:32768
	ds_read_b128 v[180:183], v167 offset:33792
	ds_read_b128 v[196:199], v167 offset:34816
	ds_read_b128 v[200:203], v167 offset:35840
	ds_read_b128 v[204:207], v167 offset:36864
	ds_read_b128 v[208:211], v167 offset:37888
	ds_read_b128 v[212:215], v167 offset:38912
	ds_read_b128 v[216:219], v167 offset:39936
	global_load_lds_dwordx4 v[236:237], off
	v_lshl_add_u64 v[236:237], s[42:43], 0, v[144:145]
	s_mov_b32 m0, s19
	s_nop 0
	global_load_lds_dwordx4 v[236:237], off
	s_waitcnt vmcnt(8)
	s_waitcnt lgkmcnt(0)
	s_setprio 1
	s_barrier
	v_mfma_f32_16x16x32_bf16 v[126:129], v[130:133], v[176:179], v[126:129]
	v_mfma_f32_16x16x32_bf16 v[122:125], v[138:141], v[176:179], v[122:125]
	v_mfma_f32_16x16x32_bf16 v[110:113], v[130:133], v[196:199], v[110:113]
	v_mfma_f32_16x16x32_bf16 v[106:109], v[138:141], v[196:199], v[106:109]
	v_mfma_f32_16x16x32_bf16 v[94:97], v[130:133], v[204:207], v[94:97]
	v_mfma_f32_16x16x32_bf16 v[90:93], v[138:141], v[204:207], v[90:93]
	v_mfma_f32_16x16x32_bf16 v[78:81], v[130:133], v[212:215], v[78:81]
	v_mfma_f32_16x16x32_bf16 v[74:77], v[138:141], v[212:215], v[74:77]
	v_mfma_f32_16x16x32_bf16 v[126:129], v[134:137], v[180:183], v[126:129]
	v_mfma_f32_16x16x32_bf16 v[122:125], v[152:155], v[180:183], v[122:125]
	v_mfma_f32_16x16x32_bf16 v[110:113], v[134:137], v[200:203], v[110:113]
	v_mfma_f32_16x16x32_bf16 v[106:109], v[152:155], v[200:203], v[106:109]
	v_mfma_f32_16x16x32_bf16 v[94:97], v[134:137], v[208:211], v[94:97]
	v_mfma_f32_16x16x32_bf16 v[90:93], v[152:155], v[208:211], v[90:93]
	v_mfma_f32_16x16x32_bf16 v[78:81], v[134:137], v[216:219], v[78:81]
	v_mfma_f32_16x16x32_bf16 v[74:77], v[152:155], v[216:219], v[74:77]
	v_mfma_f32_16x16x32_bf16 v[118:121], v[156:159], v[176:179], v[118:121]
	v_mfma_f32_16x16x32_bf16 v[114:117], v[168:171], v[176:179], v[114:117]
	v_mfma_f32_16x16x32_bf16 v[102:105], v[156:159], v[196:199], v[102:105]
	v_mfma_f32_16x16x32_bf16 v[98:101], v[168:171], v[196:199], v[98:101]
	v_mfma_f32_16x16x32_bf16 v[86:89], v[156:159], v[204:207], v[86:89]
	v_mfma_f32_16x16x32_bf16 v[82:85], v[168:171], v[204:207], v[82:85]
	v_mfma_f32_16x16x32_bf16 v[70:73], v[156:159], v[212:215], v[70:73]
	v_mfma_f32_16x16x32_bf16 v[66:69], v[168:171], v[212:215], v[66:69]
	v_mfma_f32_16x16x32_bf16 v[118:121], v[160:163], v[180:183], v[118:121]
	v_mfma_f32_16x16x32_bf16 v[114:117], v[172:175], v[180:183], v[114:117]
	v_mfma_f32_16x16x32_bf16 v[102:105], v[160:163], v[200:203], v[102:105]
	v_mfma_f32_16x16x32_bf16 v[98:101], v[172:175], v[200:203], v[98:101]
	v_mfma_f32_16x16x32_bf16 v[86:89], v[160:163], v[208:211], v[86:89]
	v_mfma_f32_16x16x32_bf16 v[82:85], v[172:175], v[208:211], v[82:85]
	v_mfma_f32_16x16x32_bf16 v[70:73], v[160:163], v[216:219], v[70:73]
	v_mfma_f32_16x16x32_bf16 v[66:69], v[172:175], v[216:219], v[66:69]
	s_barrier
; #define PG8_STAGE(bufoff, gbase, voff) do { _Pragma("unroll") for (int _i = 0; _i < 2; ++_i) \
;         __builtin_amdgcn_global_load_lds((const unsigned*)((const char*)(gbase) + (voff)[_i]), (LAS unsigned*)(lds + (bufoff) + ldsw + _i * 8192), 16, 0, 0); } while (0)
; #define PG8_LDA(dst, b, h) do { _Pragma("unroll") for (int m = 0; m < 4; ++m) _Pragma("unroll") for (int k = 0; k < 2; ++k) dst[m][k] = *(const LAS bf16x8*)(lds + PG8_SA(b, h) + aoff + m * 2048 + k * 1024); } while (0)
; #define PG8_MMA(ai, bj, At, Bt) do { __builtin_amdgcn_s_setprio(1); _Pragma("unroll") for (int m = 0; m < 4; ++m) _Pragma("unroll") for (int n = 0; n < 2; ++n) _Pragma("unroll") for (int k = 0; k < 2; ++k) \
;         acc[ai][bj][m][n] = __builtin_amdgcn_mfma_f32_16x16x32_bf16(Bt[n][k], At[m][k], acc[ai][bj][m][n], 0, 0, 0); __builtin_amdgcn_s_setprio(0); } while (0)
; #define PG8_WAIT_V(n) asm volatile("s_waitcnt vmcnt(" #n ")" ::: "memory")
; #define PG8_WAIT_L(n) asm volatile("s_waitcnt lgkmcnt(" #n ")" ::: "memory")
; #define PG8_BAR __builtin_amdgcn_s_barrier()
; #define PG8_SCHED __builtin_amdgcn_sched_barrier(0)
; template <class Epi, class Sched>
; __device__ __forceinline__ void gemm_phase(LAS unsigned char* lds, const Gemm g, const Sched& S, const Epi& E) {
;     ...
;         for (int t = 0; t < nt; t += 2) {
;             if constexpr (Epi::HOOKS) { if (cur.kind == 3 && (t == 4 || t == 12)) { int fr_ = fr, fq_ = fq; asm volatile("" : "+v"(fr_), "+v"(fq_)); E.hook(acc, cur, t == 4 ? 0 : 1, wr, wc, fr_, fq_); } }
;             const bool last = (t == nt - 2);
;             const char* a1 = cA + (size_t)(t + 1) * kstep;
;             const char* a2 = last ? nA : cA + (size_t)(t + 2) * kstep; const char* b2 = last ? nB : cB + (size_t)(t + 2) * kstep;
;             const char* a3 = a2 + kstep; const char* b3 = b2 + kstep;
;     ...
;             PG8_LDA(At, 1, 1); PG8_STAGE(PG8_SB(1, 0), b3, voffB); PG8_STAGE(PG8_SB(1, 1), b3 + hstepB, voffB); PG8_STAGE(PG8_SA(1, 0), a3, voffA);
;             PG8_WAIT_V(8); PG8_WAIT_L(0); PG8_BAR; PG8_MMA(1, 0, At, B0); PG8_MMA(1, 1, At, B1); PG8_BAR; PG8_SCHED;
	s_setprio 0
	s_add_i32 s42, s52, s14
	v_lshl_add_u64 v[184:185], v[184:185], 0, s[26:27]
	s_mov_b32 m0, s42
	ds_read_b128 v[176:179], v167 offset:49152
	ds_read_b128 v[180:183], v167 offset:50176
	ds_read_b128 v[196:199], v167 offset:51200
	ds_read_b128 v[200:203], v167 offset:52224
	ds_read_b128 v[204:207], v167 offset:53248
	ds_read_b128 v[208:211], v167 offset:54272
	ds_read_b128 v[212:215], v167 offset:55296
	ds_read_b128 v[216:219], v167 offset:56320
	global_load_lds_dwordx4 v[184:185], off
	s_add_i32 m0, s42, 0x2000
	s_add_u32 s0, s0, 0x100080
	v_lshl_add_u64 v[184:185], v[220:221], 0, s[26:27]
	s_addc_u32 s1, s1, 0
	s_add_i32 s42, s53, s14
	global_load_lds_dwordx4 v[184:185], off
	v_lshl_add_u64 v[184:185], s[0:1], 0, v[0:1]
	s_mov_b32 m0, s42
	s_nop 0
	global_load_lds_dwordx4 v[184:185], off
	v_lshl_add_u64 v[184:185], s[0:1], 0, v[146:147]
	s_add_i32 m0, s42, 0x2000
	s_nop 0
	global_load_lds_dwordx4 v[184:185], off
	v_lshl_add_u64 v[184:185], v[232:233], 0, s[26:27]
	s_mov_b32 m0, s67
	s_nop 0
	global_load_lds_dwordx4 v[184:185], off
	v_lshl_add_u64 v[184:185], v[234:235], 0, s[26:27]
	s_mov_b32 m0, s69
	s_nop 0
	global_load_lds_dwordx4 v[184:185], off
	s_waitcnt vmcnt(8)
	s_waitcnt lgkmcnt(0)
	s_setprio 1
	s_barrier
	v_mfma_f32_16x16x32_bf16 v[62:65], v[130:133], v[176:179], v[62:65]
	v_mfma_f32_16x16x32_bf16 v[58:61], v[138:141], v[176:179], v[58:61]
	v_mfma_f32_16x16x32_bf16 v[46:49], v[130:133], v[196:199], v[46:49]
	v_mfma_f32_16x16x32_bf16 v[42:45], v[138:141], v[196:199], v[42:45]
	v_mfma_f32_16x16x32_bf16 v[30:33], v[130:133], v[204:207], v[30:33]
	v_mfma_f32_16x16x32_bf16 v[26:29], v[138:141], v[204:207], v[26:29]
	v_mfma_f32_16x16x32_bf16 v[14:17], v[130:133], v[212:215], v[14:17]
	v_mfma_f32_16x16x32_bf16 v[10:13], v[138:141], v[212:215], v[10:13]
	v_mfma_f32_16x16x32_bf16 v[62:65], v[134:137], v[180:183], v[62:65]
	v_mfma_f32_16x16x32_bf16 v[58:61], v[152:155], v[180:183], v[58:61]
	v_mfma_f32_16x16x32_bf16 v[46:49], v[134:137], v[200:203], v[46:49]
	v_mfma_f32_16x16x32_bf16 v[42:45], v[152:155], v[200:203], v[42:45]
	v_mfma_f32_16x16x32_bf16 v[30:33], v[134:137], v[208:211], v[30:33]
	v_mfma_f32_16x16x32_bf16 v[26:29], v[152:155], v[208:211], v[26:29]
	v_mfma_f32_16x16x32_bf16 v[14:17], v[134:137], v[216:219], v[14:17]
	v_mfma_f32_16x16x32_bf16 v[10:13], v[152:155], v[216:219], v[10:13]
	v_mfma_f32_16x16x32_bf16 v[54:57], v[156:159], v[176:179], v[54:57]
	v_mfma_f32_16x16x32_bf16 v[50:53], v[168:171], v[176:179], v[50:53]
	v_mfma_f32_16x16x32_bf16 v[38:41], v[156:159], v[196:199], v[38:41]
	v_mfma_f32_16x16x32_bf16 v[34:37], v[168:171], v[196:199], v[34:37]
	v_mfma_f32_16x16x32_bf16 v[22:25], v[156:159], v[204:207], v[22:25]
	v_mfma_f32_16x16x32_bf16 v[18:21], v[168:171], v[204:207], v[18:21]
	v_mfma_f32_16x16x32_bf16 v[6:9], v[156:159], v[212:215], v[6:9]
	v_mfma_f32_16x16x32_bf16 v[2:5], v[168:171], v[212:215], v[2:5]
	v_mfma_f32_16x16x32_bf16 v[54:57], v[160:163], v[180:183], v[54:57]
	v_mfma_f32_16x16x32_bf16 v[50:53], v[172:175], v[180:183], v[50:53]
	v_mfma_f32_16x16x32_bf16 v[38:41], v[160:163], v[200:203], v[38:41]
	v_mfma_f32_16x16x32_bf16 v[34:37], v[172:175], v[200:203], v[34:37]
	v_mfma_f32_16x16x32_bf16 v[22:25], v[160:163], v[208:211], v[22:25]
	v_mfma_f32_16x16x32_bf16 v[18:21], v[172:175], v[208:211], v[18:21]
	v_mfma_f32_16x16x32_bf16 v[6:9], v[160:163], v[216:219], v[6:9]
	v_mfma_f32_16x16x32_bf16 v[2:5], v[172:175], v[216:219], v[2:5]
	s_barrier
	s_setprio 0
	s_add_u32 s93, s93, 0x100
	s_addc_u32 s94, s94, 0
	s_add_u32 s20, s20, 0x100
	s_addc_u32 s21, s21, 0
	s_cmp_ge_i32 s68, s46
	s_mov_b32 s0, s68
	s_cbranch_scc0 .LBB0_101
	v_readlane_b32 s94, v255, 0
	v_readlane_b32 s95, v255, 1

; #define PG8_STAGE(bufoff, gbase, voff) do { _Pragma("unroll") for (int _i = 0; _i < 2; ++_i) \
;         __builtin_amdgcn_global_load_lds((const unsigned*)((const char*)(gbase) + (voff)[_i]), (LAS unsigned*)(lds + (bufoff) + ldsw + _i * 8192), 16, 0, 0); } while (0)
; #define PG8_LDA(dst, b, h) do { _Pragma("unroll") for (int m = 0; m < 4; ++m) _Pragma("unroll") for (int k = 0; k < 2; ++k) dst[m][k] = *(const LAS bf16x8*)(lds + PG8_SA(b, h) + aoff + m * 2048 + k * 1024); } while (0)
; #define PG8_LDB(dst, b, h) do { _Pragma("unroll") for (int n = 0; n < 2; ++n) _Pragma("unroll") for (int k = 0; k < 2; ++k) dst[n][k] = *(const LAS bf16x8*)(lds + PG8_SB(b, h) + boff + n * 2048 + k * 1024); } while (0)
; #define PG8_MMA(ai, bj, At, Bt) do { __builtin_amdgcn_s_setprio(1); _Pragma("unroll") for (int m = 0; m < 4; ++m) _Pragma("unroll") for (int n = 0; n < 2; ++n) _Pragma("unroll") for (int k = 0; k < 2; ++k) \
;         acc[ai][bj][m][n] = __builtin_amdgcn_mfma_f32_16x16x32_bf16(Bt[n][k], At[m][k], acc[ai][bj][m][n], 0, 0, 0); __builtin_amdgcn_s_setprio(0); } while (0)
; #define PG8_WAIT_V(n) asm volatile("s_waitcnt vmcnt(" #n ")" ::: "memory")
; template <class Epi, class Sched>
; __device__ __forceinline__ void gemm_phase(LAS unsigned char* lds, const Gemm g, const Sched& S, const Epi& E) {
;     ...
;         for (int t = 0; t < nt; t += 2) {
;             if constexpr (Epi::HOOKS) { if (cur.kind == 3 && (t == 4 || t == 12)) { int fr_ = fr, fq_ = fq; asm volatile("" : "+v"(fr_), "+v"(fq_)); E.hook(acc, cur, t == 4 ? 0 : 1, wr, wc, fr_, fq_); } }
;             const bool last = (t == nt - 2);
;             const char* a1 = cA + (size_t)(t + 1) * kstep;
;             const char* a2 = last ? nA : cA + (size_t)(t + 2) * kstep; const char* b2 = last ? nB : cB + (size_t)(t + 2) * kstep;
;             const char* a3 = a2 + kstep; const char* b3 = b2 + kstep;
;             PG8_LDB(B0, 0, 0); PG8_LDB(B1, 0, 1); PG8_SCHED; PG8_LDA(At, 0, 0); PG8_STAGE(PG8_SA(1, 1), a1 + hstepA, voffA);
;             PG8_WAIT_V(8); PG8_WAIT_L(0); PG8_BAR; PG8_MMA(0, 0, At, B0); PG8_MMA(0, 1, At, B1); PG8_BAR; PG8_SCHED;
;             PG8_LDA(At, 0, 1); PG8_STAGE(PG8_SB(0, 0), b2, voffB); PG8_STAGE(PG8_SB(0, 1), b2 + hstepB, voffB); PG8_STAGE(PG8_SA(0, 0), a2, voffA);
;             PG8_WAIT_V(8); PG8_WAIT_L(0); PG8_BAR; PG8_MMA(1, 0, At, B0); PG8_MMA(1, 1, At, B1); PG8_BAR; PG8_SCHED;
.LBB0_209:
	s_add_i32 s68, s0, 2
	s_add_u32 s1, s20, 0xfffc0080
	s_addc_u32 s52, s21, -1
	s_add_i32 s53, 0, 0x10000
	s_cmp_eq_u32 s72, s0
	s_cselect_b32 s85, s43, s52
	s_cselect_b32 s84, s59, s1
	s_cselect_b32 s1, s86, s89
	s_cselect_b32 s0, s87, s88
	s_add_i32 s52, 0, 0x14000
	v_add_u32_e32 v142, s53, v177
	v_add_u32_e32 v168, s52, v177
	ds_read_b128 v[130:133], v142
	ds_read_b128 v[134:137], v142 offset:1024
	ds_read_b128 v[138:141], v142 offset:2048
	ds_read_b128 v[142:145], v142 offset:3072
	ds_read_b128 v[156:159], v168
	ds_read_b128 v[160:163], v168 offset:1024
	ds_read_b128 v[164:167], v168 offset:2048
	ds_read_b128 v[180:183], v168 offset:3072
	v_lshl_add_u64 v[168:169], s[20:21], 0, v[154:155]
	s_add_i32 m0, s19, 0xc000
	ds_read_b128 v[196:199], v179
	ds_read_b128 v[200:203], v179 offset:1024
	ds_read_b128 v[204:207], v179 offset:2048
	ds_read_b128 v[208:211], v179 offset:3072
	ds_read_b128 v[212:215], v179 offset:4096
	ds_read_b128 v[216:219], v179 offset:5120
	ds_read_b128 v[232:235], v179 offset:6144
	ds_read_b128 v[248:251], v179 offset:7168
	global_load_lds_dwordx4 v[168:169], off
	v_lshl_add_u64 v[168:169], s[20:21], 0, v[152:153]
	s_add_i32 m0, s19, 0xe000
	s_nop 0
	global_load_lds_dwordx4 v[168:169], off
	s_waitcnt vmcnt(8)
	s_waitcnt lgkmcnt(0)
	s_setprio 1
	s_barrier
	v_mfma_f32_16x16x32_bf16 v[126:129], v[130:133], v[196:199], v[126:129]
	v_mfma_f32_16x16x32_bf16 v[122:125], v[138:141], v[196:199], v[122:125]
	v_mfma_f32_16x16x32_bf16 v[110:113], v[130:133], v[204:207], v[110:113]
	v_mfma_f32_16x16x32_bf16 v[106:109], v[138:141], v[204:207], v[106:109]
	v_mfma_f32_16x16x32_bf16 v[94:97], v[130:133], v[212:215], v[94:97]
	v_mfma_f32_16x16x32_bf16 v[90:93], v[138:141], v[212:215], v[90:93]
	v_mfma_f32_16x16x32_bf16 v[78:81], v[130:133], v[232:235], v[78:81]
	v_mfma_f32_16x16x32_bf16 v[74:77], v[138:141], v[232:235], v[74:77]
	v_mfma_f32_16x16x32_bf16 v[126:129], v[134:137], v[200:203], v[126:129]
	v_mfma_f32_16x16x32_bf16 v[122:125], v[142:145], v[200:203], v[122:125]
	v_mfma_f32_16x16x32_bf16 v[110:113], v[134:137], v[208:211], v[110:113]
	v_mfma_f32_16x16x32_bf16 v[106:109], v[142:145], v[208:211], v[106:109]
	v_mfma_f32_16x16x32_bf16 v[94:97], v[134:137], v[216:219], v[94:97]
	v_mfma_f32_16x16x32_bf16 v[90:93], v[142:145], v[216:219], v[90:93]
	v_mfma_f32_16x16x32_bf16 v[78:81], v[134:137], v[248:251], v[78:81]
	v_mfma_f32_16x16x32_bf16 v[74:77], v[142:145], v[248:251], v[74:77]
	v_mfma_f32_16x16x32_bf16 v[118:121], v[156:159], v[196:199], v[118:121]
	v_mfma_f32_16x16x32_bf16 v[114:117], v[164:167], v[196:199], v[114:117]
	v_mfma_f32_16x16x32_bf16 v[102:105], v[156:159], v[204:207], v[102:105]
	v_mfma_f32_16x16x32_bf16 v[98:101], v[164:167], v[204:207], v[98:101]
	v_mfma_f32_16x16x32_bf16 v[86:89], v[156:159], v[212:215], v[86:89]
	v_mfma_f32_16x16x32_bf16 v[82:85], v[164:167], v[212:215], v[82:85]
	v_mfma_f32_16x16x32_bf16 v[70:73], v[156:159], v[232:235], v[70:73]
	v_mfma_f32_16x16x32_bf16 v[66:69], v[164:167], v[232:235], v[66:69]
	v_mfma_f32_16x16x32_bf16 v[118:121], v[160:163], v[200:203], v[118:121]
	v_mfma_f32_16x16x32_bf16 v[114:117], v[180:183], v[200:203], v[114:117]
	v_mfma_f32_16x16x32_bf16 v[102:105], v[160:163], v[208:211], v[102:105]
	v_mfma_f32_16x16x32_bf16 v[98:101], v[180:183], v[208:211], v[98:101]
	v_mfma_f32_16x16x32_bf16 v[86:89], v[160:163], v[216:219], v[86:89]
	v_mfma_f32_16x16x32_bf16 v[82:85], v[180:183], v[216:219], v[82:85]
	v_mfma_f32_16x16x32_bf16 v[70:73], v[160:163], v[248:251], v[70:73]
	v_mfma_f32_16x16x32_bf16 v[66:69], v[180:183], v[248:251], v[66:69]
	s_barrier
	s_setprio 0
	s_add_i32 s53, s53, s17
	v_lshl_add_u64 v[168:169], s[0:1], 0, v[0:1]
	s_mov_b32 m0, s53
	ds_read_b128 v[196:199], v179 offset:16384
	ds_read_b128 v[200:203], v179 offset:17408
	ds_read_b128 v[204:207], v179 offset:18432
	ds_read_b128 v[208:211], v179 offset:19456
	ds_read_b128 v[212:215], v179 offset:20480
	ds_read_b128 v[216:219], v179 offset:21504
	ds_read_b128 v[232:235], v179 offset:22528
	ds_read_b128 v[248:251], v179 offset:23552
	global_load_lds_dwordx4 v[168:169], off
	s_add_i32 m0, s53, 0x2000
	s_add_u32 s90, s0, 0x40000
	v_lshl_add_u64 v[174:175], s[0:1], 0, v[150:151]
	s_addc_u32 s91, s1, 0
	s_add_i32 s52, s52, s17
	global_load_lds_dwordx4 v[174:175], off
	v_lshl_add_u64 v[184:185], s[90:91], 0, v[0:1]
	s_mov_b32 m0, s52
	v_lshl_add_u64 v[220:221], s[84:85], 0, v[148:149]
	global_load_lds_dwordx4 v[184:185], off
	v_lshl_add_u64 v[184:185], s[90:91], 0, v[150:151]
	s_add_i32 m0, s52, 0x2000
	s_nop 0
	global_load_lds_dwordx4 v[184:185], off
	v_lshl_add_u64 v[184:185], s[84:85], 0, v[146:147]
	s_mov_b32 m0, s19
	s_nop 0
	global_load_lds_dwordx4 v[184:185], off
	s_mov_b32 m0, s44
	s_nop 0
	global_load_lds_dwordx4 v[220:221], off
	s_waitcnt vmcnt(8)
	s_waitcnt lgkmcnt(0)
	s_setprio 1
	s_barrier
; #define PG8_STAGE(bufoff, gbase, voff) do { _Pragma("unroll") for (int _i = 0; _i < 2; ++_i) \
;         __builtin_amdgcn_global_load_lds((const unsigned*)((const char*)(gbase) + (voff)[_i]), (LAS unsigned*)(lds + (bufoff) + ldsw + _i * 8192), 16, 0, 0); } while (0)
; #define PG8_LDA(dst, b, h) do { _Pragma("unroll") for (int m = 0; m < 4; ++m) _Pragma("unroll") for (int k = 0; k < 2; ++k) dst[m][k] = *(const LAS bf16x8*)(lds + PG8_SA(b, h) + aoff + m * 2048 + k * 1024); } while (0)
; #define PG8_LDB(dst, b, h) do { _Pragma("unroll") for (int n = 0; n < 2; ++n) _Pragma("unroll") for (int k = 0; k < 2; ++k) dst[n][k] = *(const LAS bf16x8*)(lds + PG8_SB(b, h) + boff + n * 2048 + k * 1024); } while (0)
; #define PG8_MMA(ai, bj, At, Bt) do { __builtin_amdgcn_s_setprio(1); _Pragma("unroll") for (int m = 0; m < 4; ++m) _Pragma("unroll") for (int n = 0; n < 2; ++n) _Pragma("unroll") for (int k = 0; k < 2; ++k) \
;         acc[ai][bj][m][n] = __builtin_amdgcn_mfma_f32_16x16x32_bf16(Bt[n][k], At[m][k], acc[ai][bj][m][n], 0, 0, 0); __builtin_amdgcn_s_setprio(0); } while (0)
; #define PG8_WAIT_V(n) asm volatile("s_waitcnt vmcnt(" #n ")" ::: "memory")
; #define PG8_WAIT_L(n) asm volatile("s_waitcnt lgkmcnt(" #n ")" ::: "memory")
; #define PG8_BAR __builtin_amdgcn_s_barrier()
; #define PG8_SCHED __builtin_amdgcn_sched_barrier(0)
; template <class Epi, class Sched>
; __device__ __forceinline__ void gemm_phase(LAS unsigned char* lds, const Gemm g, const Sched& S, const Epi& E) {
;     ...
;             PG8_WAIT_V(8); PG8_WAIT_L(0); PG8_BAR; PG8_MMA(1, 0, At, B0); PG8_MMA(1, 1, At, B1); PG8_BAR; PG8_SCHED;
;             PG8_LDB(B0, 1, 0); PG8_LDB(B1, 1, 1); PG8_SCHED; PG8_LDA(At, 1, 0); PG8_STAGE(PG8_SA(0, 1), a2 + hstepA, voffA);
;             PG8_WAIT_V(8); PG8_WAIT_L(0); PG8_BAR; PG8_MMA(0, 0, At, B0); PG8_MMA(0, 1, At, B1); PG8_BAR; PG8_SCHED;
	v_mfma_f32_16x16x32_bf16 v[62:65], v[130:133], v[196:199], v[62:65]
	v_mfma_f32_16x16x32_bf16 v[58:61], v[138:141], v[196:199], v[58:61]
	v_mfma_f32_16x16x32_bf16 v[46:49], v[130:133], v[204:207], v[46:49]
	v_mfma_f32_16x16x32_bf16 v[42:45], v[138:141], v[204:207], v[42:45]
	v_mfma_f32_16x16x32_bf16 v[30:33], v[130:133], v[212:215], v[30:33]
	v_mfma_f32_16x16x32_bf16 v[26:29], v[138:141], v[212:215], v[26:29]
	v_mfma_f32_16x16x32_bf16 v[14:17], v[130:133], v[232:235], v[14:17]
	v_mfma_f32_16x16x32_bf16 v[10:13], v[138:141], v[232:235], v[10:13]
	v_mfma_f32_16x16x32_bf16 v[62:65], v[134:137], v[200:203], v[62:65]
	v_mfma_f32_16x16x32_bf16 v[58:61], v[142:145], v[200:203], v[58:61]
	v_mfma_f32_16x16x32_bf16 v[46:49], v[134:137], v[208:211], v[46:49]
	v_mfma_f32_16x16x32_bf16 v[42:45], v[142:145], v[208:211], v[42:45]
	v_mfma_f32_16x16x32_bf16 v[30:33], v[134:137], v[216:219], v[30:33]
	v_mfma_f32_16x16x32_bf16 v[26:29], v[142:145], v[216:219], v[26:29]
	v_mfma_f32_16x16x32_bf16 v[14:17], v[134:137], v[248:251], v[14:17]
	v_mfma_f32_16x16x32_bf16 v[10:13], v[142:145], v[248:251], v[10:13]
	v_mfma_f32_16x16x32_bf16 v[54:57], v[156:159], v[196:199], v[54:57]
	v_mfma_f32_16x16x32_bf16 v[50:53], v[164:167], v[196:199], v[50:53]
	v_mfma_f32_16x16x32_bf16 v[38:41], v[156:159], v[204:207], v[38:41]
	v_mfma_f32_16x16x32_bf16 v[34:37], v[164:167], v[204:207], v[34:37]
	v_mfma_f32_16x16x32_bf16 v[22:25], v[156:159], v[212:215], v[22:25]
	v_mfma_f32_16x16x32_bf16 v[18:21], v[164:167], v[212:215], v[18:21]
	v_mfma_f32_16x16x32_bf16 v[6:9], v[156:159], v[232:235], v[6:9]
	v_mfma_f32_16x16x32_bf16 v[2:5], v[164:167], v[232:235], v[2:5]
	v_mfma_f32_16x16x32_bf16 v[54:57], v[160:163], v[200:203], v[54:57]
	v_mfma_f32_16x16x32_bf16 v[50:53], v[180:183], v[200:203], v[50:53]
	v_mfma_f32_16x16x32_bf16 v[38:41], v[160:163], v[208:211], v[38:41]
	v_mfma_f32_16x16x32_bf16 v[34:37], v[180:183], v[208:211], v[34:37]
	v_mfma_f32_16x16x32_bf16 v[22:25], v[160:163], v[216:219], v[22:25]
	v_mfma_f32_16x16x32_bf16 v[18:21], v[180:183], v[216:219], v[18:21]
	v_mfma_f32_16x16x32_bf16 v[6:9], v[160:163], v[248:251], v[6:9]
	v_mfma_f32_16x16x32_bf16 v[2:5], v[180:183], v[248:251], v[2:5]
	s_barrier
	s_setprio 0
	s_add_i32 s52, 0, 0x18000
	s_add_i32 s53, 0, 0x1c000
	v_add_u32_e32 v142, s52, v177
	v_add_u32_e32 v170, s53, v177
	ds_read_b128 v[130:133], v142
	ds_read_b128 v[134:137], v142 offset:1024
	ds_read_b128 v[138:141], v142 offset:2048
	ds_read_b128 v[142:145], v142 offset:3072
	ds_read_b128 v[156:159], v170
	ds_read_b128 v[160:163], v170 offset:1024
	ds_read_b128 v[164:167], v170 offset:2048
	ds_read_b128 v[180:183], v170 offset:3072
	s_add_u32 s84, s84, 0x40000
	s_addc_u32 s85, s85, 0
	s_mov_b32 m0, s46
	v_lshl_add_u64 v[236:237], s[84:85], 0, v[146:147]
	ds_read_b128 v[196:199], v179 offset:32768
	ds_read_b128 v[200:203], v179 offset:33792
	ds_read_b128 v[204:207], v179 offset:34816
	ds_read_b128 v[208:211], v179 offset:35840
	ds_read_b128 v[212:215], v179 offset:36864
	ds_read_b128 v[216:219], v179 offset:37888
	ds_read_b128 v[232:235], v179 offset:38912
	ds_read_b128 v[248:251], v179 offset:39936
	global_load_lds_dwordx4 v[236:237], off
	v_lshl_add_u64 v[236:237], s[84:85], 0, v[148:149]
	s_mov_b32 m0, s47
	s_nop 0
	global_load_lds_dwordx4 v[236:237], off
	s_waitcnt vmcnt(8)
	s_waitcnt lgkmcnt(0)
	s_setprio 1
	s_barrier
	v_mfma_f32_16x16x32_bf16 v[126:129], v[130:133], v[196:199], v[126:129]
	v_mfma_f32_16x16x32_bf16 v[122:125], v[138:141], v[196:199], v[122:125]
	v_mfma_f32_16x16x32_bf16 v[110:113], v[130:133], v[204:207], v[110:113]
	v_mfma_f32_16x16x32_bf16 v[106:109], v[138:141], v[204:207], v[106:109]
	v_mfma_f32_16x16x32_bf16 v[94:97], v[130:133], v[212:215], v[94:97]
	v_mfma_f32_16x16x32_bf16 v[90:93], v[138:141], v[212:215], v[90:93]
	v_mfma_f32_16x16x32_bf16 v[78:81], v[130:133], v[232:235], v[78:81]
	v_mfma_f32_16x16x32_bf16 v[74:77], v[138:141], v[232:235], v[74:77]
	v_mfma_f32_16x16x32_bf16 v[126:129], v[134:137], v[200:203], v[126:129]
	v_mfma_f32_16x16x32_bf16 v[122:125], v[142:145], v[200:203], v[122:125]
	v_mfma_f32_16x16x32_bf16 v[110:113], v[134:137], v[208:211], v[110:113]
	v_mfma_f32_16x16x32_bf16 v[106:109], v[142:145], v[208:211], v[106:109]
	v_mfma_f32_16x16x32_bf16 v[94:97], v[134:137], v[216:219], v[94:97]
	v_mfma_f32_16x16x32_bf16 v[90:93], v[142:145], v[216:219], v[90:93]
	v_mfma_f32_16x16x32_bf16 v[78:81], v[134:137], v[248:251], v[78:81]
	v_mfma_f32_16x16x32_bf16 v[74:77], v[142:145], v[248:251], v[74:77]
	v_mfma_f32_16x16x32_bf16 v[118:121], v[156:159], v[196:199], v[118:121]
	v_mfma_f32_16x16x32_bf16 v[114:117], v[164:167], v[196:199], v[114:117]
	v_mfma_f32_16x16x32_bf16 v[102:105], v[156:159], v[204:207], v[102:105]
	v_mfma_f32_16x16x32_bf16 v[98:101], v[164:167], v[204:207], v[98:101]
	v_mfma_f32_16x16x32_bf16 v[86:89], v[156:159], v[212:215], v[86:89]
	v_mfma_f32_16x16x32_bf16 v[82:85], v[164:167], v[212:215], v[82:85]
	v_mfma_f32_16x16x32_bf16 v[70:73], v[156:159], v[232:235], v[70:73]
	v_mfma_f32_16x16x32_bf16 v[66:69], v[164:167], v[232:235], v[66:69]
	v_mfma_f32_16x16x32_bf16 v[118:121], v[160:163], v[200:203], v[118:121]
	v_mfma_f32_16x16x32_bf16 v[114:117], v[180:183], v[200:203], v[114:117]
	v_mfma_f32_16x16x32_bf16 v[102:105], v[160:163], v[208:211], v[102:105]
	v_mfma_f32_16x16x32_bf16 v[98:101], v[180:183], v[208:211], v[98:101]
	v_mfma_f32_16x16x32_bf16 v[86:89], v[160:163], v[216:219], v[86:89]
	v_mfma_f32_16x16x32_bf16 v[82:85], v[180:183], v[216:219], v[82:85]
	v_mfma_f32_16x16x32_bf16 v[70:73], v[160:163], v[248:251], v[70:73]
	v_mfma_f32_16x16x32_bf16 v[66:69], v[180:183], v[248:251], v[66:69]
	s_barrier
; #define PG8_STAGE(bufoff, gbase, voff) do { _Pragma("unroll") for (int _i = 0; _i < 2; ++_i) \
;         __builtin_amdgcn_global_load_lds((const unsigned*)((const char*)(gbase) + (voff)[_i]), (LAS unsigned*)(lds + (bufoff) + ldsw + _i * 8192), 16, 0, 0); } while (0)
; #define PG8_LDA(dst, b, h) do { _Pragma("unroll") for (int m = 0; m < 4; ++m) _Pragma("unroll") for (int k = 0; k < 2; ++k) dst[m][k] = *(const LAS bf16x8*)(lds + PG8_SA(b, h) + aoff + m * 2048 + k * 1024); } while (0)
; #define PG8_MMA(ai, bj, At, Bt) do { __builtin_amdgcn_s_setprio(1); _Pragma("unroll") for (int m = 0; m < 4; ++m) _Pragma("unroll") for (int n = 0; n < 2; ++n) _Pragma("unroll") for (int k = 0; k < 2; ++k) \
;         acc[ai][bj][m][n] = __builtin_amdgcn_mfma_f32_16x16x32_bf16(Bt[n][k], At[m][k], acc[ai][bj][m][n], 0, 0, 0); __builtin_amdgcn_s_setprio(0); } while (0)
; #define PG8_WAIT_V(n) asm volatile("s_waitcnt vmcnt(" #n ")" ::: "memory")
; #define PG8_WAIT_L(n) asm volatile("s_waitcnt lgkmcnt(" #n ")" ::: "memory")
; #define PG8_BAR __builtin_amdgcn_s_barrier()
; #define PG8_SCHED __builtin_amdgcn_sched_barrier(0)
; template <class Epi, class Sched>
; __device__ __forceinline__ void gemm_phase(LAS unsigned char* lds, const Gemm g, const Sched& S, const Epi& E) {
;     ...
;         for (int t = 0; t < nt; t += 2) {
;             if constexpr (Epi::HOOKS) { if (cur.kind == 3 && (t == 4 || t == 12)) { int fr_ = fr, fq_ = fq; asm volatile("" : "+v"(fr_), "+v"(fq_)); E.hook(acc, cur, t == 4 ? 0 : 1, wr, wc, fr_, fq_); } }
;             const bool last = (t == nt - 2);
;             const char* a1 = cA + (size_t)(t + 1) * kstep;
;             const char* a2 = last ? nA : cA + (size_t)(t + 2) * kstep; const char* b2 = last ? nB : cB + (size_t)(t + 2) * kstep;
;             const char* a3 = a2 + kstep; const char* b3 = b2 + kstep;
;     ...
;             PG8_LDA(At, 1, 1); PG8_STAGE(PG8_SB(1, 0), b3, voffB); PG8_STAGE(PG8_SB(1, 1), b3 + hstepB, voffB); PG8_STAGE(PG8_SA(1, 0), a3, voffA);
;             PG8_WAIT_V(8); PG8_WAIT_L(0); PG8_BAR; PG8_MMA(1, 0, At, B0); PG8_MMA(1, 1, At, B1); PG8_BAR; PG8_SCHED;
	s_setprio 0
	s_add_i32 s52, s52, s17
	v_lshl_add_u64 v[168:169], v[168:169], 0, s[26:27]
	s_mov_b32 m0, s52
	ds_read_b128 v[196:199], v179 offset:49152
	ds_read_b128 v[200:203], v179 offset:50176
	ds_read_b128 v[204:207], v179 offset:51200
	ds_read_b128 v[208:211], v179 offset:52224
	ds_read_b128 v[212:215], v179 offset:53248
	ds_read_b128 v[216:219], v179 offset:54272
	ds_read_b128 v[232:235], v179 offset:55296
	ds_read_b128 v[248:251], v179 offset:56320
	global_load_lds_dwordx4 v[168:169], off
	s_add_i32 m0, s52, 0x2000
	s_add_u32 s0, s0, 0x40080
	v_lshl_add_u64 v[168:169], v[174:175], 0, s[26:27]
	s_addc_u32 s1, s1, 0
	s_add_i32 s52, s53, s17
	global_load_lds_dwordx4 v[168:169], off
	v_lshl_add_u64 v[168:169], s[0:1], 0, v[0:1]
	s_mov_b32 m0, s52
	s_nop 0
	global_load_lds_dwordx4 v[168:169], off
	v_lshl_add_u64 v[168:169], s[0:1], 0, v[150:151]
	s_add_i32 m0, s52, 0x2000
	s_nop 0
	global_load_lds_dwordx4 v[168:169], off
	v_lshl_add_u64 v[168:169], v[184:185], 0, s[26:27]
	s_mov_b32 m0, s69
	s_nop 0
	global_load_lds_dwordx4 v[168:169], off
	v_lshl_add_u64 v[168:169], v[220:221], 0, s[26:27]
	s_mov_b32 m0, s71
	s_nop 0
	global_load_lds_dwordx4 v[168:169], off
	s_waitcnt vmcnt(8)
	s_waitcnt lgkmcnt(0)
	s_setprio 1
	s_barrier
	v_mfma_f32_16x16x32_bf16 v[62:65], v[130:133], v[196:199], v[62:65]
	v_mfma_f32_16x16x32_bf16 v[58:61], v[138:141], v[196:199], v[58:61]
	v_mfma_f32_16x16x32_bf16 v[46:49], v[130:133], v[204:207], v[46:49]
	v_mfma_f32_16x16x32_bf16 v[42:45], v[138:141], v[204:207], v[42:45]
	v_mfma_f32_16x16x32_bf16 v[30:33], v[130:133], v[212:215], v[30:33]
	v_mfma_f32_16x16x32_bf16 v[26:29], v[138:141], v[212:215], v[26:29]
	v_mfma_f32_16x16x32_bf16 v[14:17], v[130:133], v[232:235], v[14:17]
	v_mfma_f32_16x16x32_bf16 v[10:13], v[138:141], v[232:235], v[10:13]
	v_mfma_f32_16x16x32_bf16 v[62:65], v[134:137], v[200:203], v[62:65]
	v_mfma_f32_16x16x32_bf16 v[58:61], v[142:145], v[200:203], v[58:61]
	v_mfma_f32_16x16x32_bf16 v[46:49], v[134:137], v[208:211], v[46:49]
	v_mfma_f32_16x16x32_bf16 v[42:45], v[142:145], v[208:211], v[42:45]
	v_mfma_f32_16x16x32_bf16 v[30:33], v[134:137], v[216:219], v[30:33]
	v_mfma_f32_16x16x32_bf16 v[26:29], v[142:145], v[216:219], v[26:29]
	v_mfma_f32_16x16x32_bf16 v[14:17], v[134:137], v[248:251], v[14:17]
	v_mfma_f32_16x16x32_bf16 v[10:13], v[142:145], v[248:251], v[10:13]
	v_mfma_f32_16x16x32_bf16 v[54:57], v[156:159], v[196:199], v[54:57]
	v_mfma_f32_16x16x32_bf16 v[50:53], v[164:167], v[196:199], v[50:53]
	v_mfma_f32_16x16x32_bf16 v[38:41], v[156:159], v[204:207], v[38:41]
	v_mfma_f32_16x16x32_bf16 v[34:37], v[164:167], v[204:207], v[34:37]
	v_mfma_f32_16x16x32_bf16 v[22:25], v[156:159], v[212:215], v[22:25]
	v_mfma_f32_16x16x32_bf16 v[18:21], v[164:167], v[212:215], v[18:21]
	v_mfma_f32_16x16x32_bf16 v[6:9], v[156:159], v[232:235], v[6:9]
	v_mfma_f32_16x16x32_bf16 v[2:5], v[164:167], v[232:235], v[2:5]
	v_mfma_f32_16x16x32_bf16 v[54:57], v[160:163], v[200:203], v[54:57]
	v_mfma_f32_16x16x32_bf16 v[50:53], v[180:183], v[200:203], v[50:53]
	v_mfma_f32_16x16x32_bf16 v[38:41], v[160:163], v[208:211], v[38:41]
	v_mfma_f32_16x16x32_bf16 v[34:37], v[180:183], v[208:211], v[34:37]
	v_mfma_f32_16x16x32_bf16 v[22:25], v[160:163], v[216:219], v[22:25]
	v_mfma_f32_16x16x32_bf16 v[18:21], v[180:183], v[216:219], v[18:21]
	v_mfma_f32_16x16x32_bf16 v[6:9], v[160:163], v[248:251], v[6:9]
	v_mfma_f32_16x16x32_bf16 v[2:5], v[180:183], v[248:251], v[2:5]
	s_barrier
	s_setprio 0
	s_add_u32 s88, s88, 0x100
	s_addc_u32 s89, s89, 0
	s_add_u32 s20, s20, 0x100
	s_addc_u32 s21, s21, 0
	s_cmp_ge_i32 s68, s48
	s_mov_b32 s0, s68
	s_cbranch_scc0 .LBB0_209

; #define PG8_STAGE(bufoff, gbase, voff) do { _Pragma("unroll") for (int _i = 0; _i < 2; ++_i) \
;         __builtin_amdgcn_global_load_lds((const unsigned*)((const char*)(gbase) + (voff)[_i]), (LAS unsigned*)(lds + (bufoff) + ldsw + _i * 8192), 16, 0, 0); } while (0)
; #define PG8_LDA(dst, b, h) do { _Pragma("unroll") for (int m = 0; m < 4; ++m) _Pragma("unroll") for (int k = 0; k < 2; ++k) dst[m][k] = *(const LAS bf16x8*)(lds + PG8_SA(b, h) + aoff + m * 2048 + k * 1024); } while (0)
; #define PG8_LDB(dst, b, h) do { _Pragma("unroll") for (int n = 0; n < 2; ++n) _Pragma("unroll") for (int k = 0; k < 2; ++k) dst[n][k] = *(const LAS bf16x8*)(lds + PG8_SB(b, h) + boff + n * 2048 + k * 1024); } while (0)
; #define PG8_MMA(ai, bj, At, Bt) do { __builtin_amdgcn_s_setprio(1); _Pragma("unroll") for (int m = 0; m < 4; ++m) _Pragma("unroll") for (int n = 0; n < 2; ++n) _Pragma("unroll") for (int k = 0; k < 2; ++k) \
;         acc[ai][bj][m][n] = __builtin_amdgcn_mfma_f32_16x16x32_bf16(Bt[n][k], At[m][k], acc[ai][bj][m][n], 0, 0, 0); __builtin_amdgcn_s_setprio(0); } while (0)
; #define PG8_WAIT_V(n) asm volatile("s_waitcnt vmcnt(" #n ")" ::: "memory")
; template <class Epi, class Sched>
; __device__ __forceinline__ void gemm_phase(LAS unsigned char* lds, const Gemm g, const Sched& S, const Epi& E) {
;     ...
;         for (int t = 0; t < nt; t += 2) {
;             if constexpr (Epi::HOOKS) { if (cur.kind == 3 && (t == 4 || t == 12)) { int fr_ = fr, fq_ = fq; asm volatile("" : "+v"(fr_), "+v"(fq_)); E.hook(acc, cur, t == 4 ? 0 : 1, wr, wc, fr_, fq_); } }
;             const bool last = (t == nt - 2);
;             const char* a1 = cA + (size_t)(t + 1) * kstep;
;             const char* a2 = last ? nA : cA + (size_t)(t + 2) * kstep; const char* b2 = last ? nB : cB + (size_t)(t + 2) * kstep;
;             const char* a3 = a2 + kstep; const char* b3 = b2 + kstep;
;             PG8_LDB(B0, 0, 0); PG8_LDB(B1, 0, 1); PG8_SCHED; PG8_LDA(At, 0, 0); PG8_STAGE(PG8_SA(1, 1), a1 + hstepA, voffA);
;             PG8_WAIT_V(8); PG8_WAIT_L(0); PG8_BAR; PG8_MMA(0, 0, At, B0); PG8_MMA(0, 1, At, B1); PG8_BAR; PG8_SCHED;
;             PG8_LDA(At, 0, 1); PG8_STAGE(PG8_SB(0, 0), b2, voffB); PG8_STAGE(PG8_SB(0, 1), b2 + hstepB, voffB); PG8_STAGE(PG8_SA(0, 0), a2, voffA);
;             PG8_WAIT_V(8); PG8_WAIT_L(0); PG8_BAR; PG8_MMA(1, 0, At, B0); PG8_MMA(1, 1, At, B1); PG8_BAR; PG8_SCHED;
.LBB0_238:
	s_add_i32 s68, s0, 2
	s_add_u32 s1, s20, 0xfffc0080
	s_addc_u32 s52, s21, -1
	s_add_i32 s53, 0, 0x10000
	s_cmp_eq_u32 s71, s0
	s_cselect_b32 s89, s48, s52
	s_cselect_b32 s88, s59, s1
	s_cselect_b32 s1, s63, s90
	s_cselect_b32 s0, s85, s87
	s_add_i32 s52, 0, 0x14000
	v_add_u32_e32 v152, s53, v164
	v_add_u32_e32 v160, s52, v164
	ds_read_b128 v[130:133], v152
	ds_read_b128 v[134:137], v152 offset:1024
	ds_read_b128 v[138:141], v152 offset:2048
	ds_read_b128 v[152:155], v152 offset:3072
	ds_read_b128 v[156:159], v160
	ds_read_b128 v[166:169], v160 offset:1024
	ds_read_b128 v[170:173], v160 offset:2048
	ds_read_b128 v[174:177], v160 offset:3072
	v_lshl_add_u64 v[160:161], s[20:21], 0, v[150:151]
	s_add_i32 m0, s15, 0xc000
	ds_read_b128 v[178:181], v165
	ds_read_b128 v[182:185], v165 offset:1024
	ds_read_b128 v[196:199], v165 offset:2048
	ds_read_b128 v[200:203], v165 offset:3072
	ds_read_b128 v[204:207], v165 offset:4096
	ds_read_b128 v[208:211], v165 offset:5120
	ds_read_b128 v[212:215], v165 offset:6144
	ds_read_b128 v[216:219], v165 offset:7168
	global_load_lds_dwordx4 v[160:161], off
	v_lshl_add_u64 v[160:161], s[20:21], 0, v[148:149]
	s_add_i32 m0, s15, 0xe000
	s_nop 0
	global_load_lds_dwordx4 v[160:161], off
	s_waitcnt vmcnt(8)
	s_waitcnt lgkmcnt(0)
	s_setprio 1
	s_barrier
	v_mfma_f32_16x16x32_bf16 v[126:129], v[130:133], v[178:181], v[126:129]
	v_mfma_f32_16x16x32_bf16 v[122:125], v[138:141], v[178:181], v[122:125]
	v_mfma_f32_16x16x32_bf16 v[110:113], v[130:133], v[196:199], v[110:113]
	v_mfma_f32_16x16x32_bf16 v[106:109], v[138:141], v[196:199], v[106:109]
	v_mfma_f32_16x16x32_bf16 v[94:97], v[130:133], v[204:207], v[94:97]
	v_mfma_f32_16x16x32_bf16 v[90:93], v[138:141], v[204:207], v[90:93]
	v_mfma_f32_16x16x32_bf16 v[78:81], v[130:133], v[212:215], v[78:81]
	v_mfma_f32_16x16x32_bf16 v[74:77], v[138:141], v[212:215], v[74:77]
	v_mfma_f32_16x16x32_bf16 v[126:129], v[134:137], v[182:185], v[126:129]
	v_mfma_f32_16x16x32_bf16 v[122:125], v[152:155], v[182:185], v[122:125]
	v_mfma_f32_16x16x32_bf16 v[110:113], v[134:137], v[200:203], v[110:113]
	v_mfma_f32_16x16x32_bf16 v[106:109], v[152:155], v[200:203], v[106:109]
	v_mfma_f32_16x16x32_bf16 v[94:97], v[134:137], v[208:211], v[94:97]
	v_mfma_f32_16x16x32_bf16 v[90:93], v[152:155], v[208:211], v[90:93]
	v_mfma_f32_16x16x32_bf16 v[78:81], v[134:137], v[216:219], v[78:81]
	v_mfma_f32_16x16x32_bf16 v[74:77], v[152:155], v[216:219], v[74:77]
	v_mfma_f32_16x16x32_bf16 v[118:121], v[156:159], v[178:181], v[118:121]
	v_mfma_f32_16x16x32_bf16 v[114:117], v[170:173], v[178:181], v[114:117]
	v_mfma_f32_16x16x32_bf16 v[102:105], v[156:159], v[196:199], v[102:105]
	v_mfma_f32_16x16x32_bf16 v[98:101], v[170:173], v[196:199], v[98:101]
	v_mfma_f32_16x16x32_bf16 v[86:89], v[156:159], v[204:207], v[86:89]
	v_mfma_f32_16x16x32_bf16 v[82:85], v[170:173], v[204:207], v[82:85]
	v_mfma_f32_16x16x32_bf16 v[70:73], v[156:159], v[212:215], v[70:73]
	v_mfma_f32_16x16x32_bf16 v[66:69], v[170:173], v[212:215], v[66:69]
	v_mfma_f32_16x16x32_bf16 v[118:121], v[166:169], v[182:185], v[118:121]
	v_mfma_f32_16x16x32_bf16 v[114:117], v[174:177], v[182:185], v[114:117]
	v_mfma_f32_16x16x32_bf16 v[102:105], v[166:169], v[200:203], v[102:105]
	v_mfma_f32_16x16x32_bf16 v[98:101], v[174:177], v[200:203], v[98:101]
	v_mfma_f32_16x16x32_bf16 v[86:89], v[166:169], v[208:211], v[86:89]
	v_mfma_f32_16x16x32_bf16 v[82:85], v[174:177], v[208:211], v[82:85]
	v_mfma_f32_16x16x32_bf16 v[70:73], v[166:169], v[216:219], v[70:73]
	v_mfma_f32_16x16x32_bf16 v[66:69], v[174:177], v[216:219], v[66:69]
	s_barrier
	s_setprio 0
	s_add_i32 s53, s53, s14
	v_lshl_add_u64 v[160:161], s[0:1], 0, v[0:1]
	s_mov_b32 m0, s53
	ds_read_b128 v[178:181], v165 offset:16384
	ds_read_b128 v[182:185], v165 offset:17408
	ds_read_b128 v[196:199], v165 offset:18432
	ds_read_b128 v[200:203], v165 offset:19456
	ds_read_b128 v[204:207], v165 offset:20480
	ds_read_b128 v[208:211], v165 offset:21504
	ds_read_b128 v[212:215], v165 offset:22528
	ds_read_b128 v[216:219], v165 offset:23552
	global_load_lds_dwordx4 v[160:161], off
	s_add_i32 m0, s53, 0x2000
	s_add_u32 s92, s0, 0x40000
	v_lshl_add_u64 v[220:221], s[0:1], 0, v[146:147]
	s_addc_u32 s93, s1, 0
	s_add_i32 s52, s52, s14
	global_load_lds_dwordx4 v[220:221], off
	v_lshl_add_u64 v[232:233], s[92:93], 0, v[0:1]
	s_mov_b32 m0, s52
	v_lshl_add_u64 v[234:235], s[88:89], 0, v[144:145]
	global_load_lds_dwordx4 v[232:233], off
	v_lshl_add_u64 v[232:233], s[92:93], 0, v[146:147]
	s_add_i32 m0, s52, 0x2000
	s_nop 0
	global_load_lds_dwordx4 v[232:233], off
	v_lshl_add_u64 v[232:233], s[88:89], 0, v[142:143]
	s_mov_b32 m0, s15
	s_nop 0
	global_load_lds_dwordx4 v[232:233], off
	s_mov_b32 m0, s16
	s_nop 0
	global_load_lds_dwordx4 v[234:235], off
	s_waitcnt vmcnt(8)
	s_waitcnt lgkmcnt(0)
	s_setprio 1
	s_barrier
; #define PG8_STAGE(bufoff, gbase, voff) do { _Pragma("unroll") for (int _i = 0; _i < 2; ++_i) \
;         __builtin_amdgcn_global_load_lds((const unsigned*)((const char*)(gbase) + (voff)[_i]), (LAS unsigned*)(lds + (bufoff) + ldsw + _i * 8192), 16, 0, 0); } while (0)
; #define PG8_LDA(dst, b, h) do { _Pragma("unroll") for (int m = 0; m < 4; ++m) _Pragma("unroll") for (int k = 0; k < 2; ++k) dst[m][k] = *(const LAS bf16x8*)(lds + PG8_SA(b, h) + aoff + m * 2048 + k * 1024); } while (0)
; #define PG8_LDB(dst, b, h) do { _Pragma("unroll") for (int n = 0; n < 2; ++n) _Pragma("unroll") for (int k = 0; k < 2; ++k) dst[n][k] = *(const LAS bf16x8*)(lds + PG8_SB(b, h) + boff + n * 2048 + k * 1024); } while (0)
; #define PG8_MMA(ai, bj, At, Bt) do { __builtin_amdgcn_s_setprio(1); _Pragma("unroll") for (int m = 0; m < 4; ++m) _Pragma("unroll") for (int n = 0; n < 2; ++n) _Pragma("unroll") for (int k = 0; k < 2; ++k) \
;         acc[ai][bj][m][n] = __builtin_amdgcn_mfma_f32_16x16x32_bf16(Bt[n][k], At[m][k], acc[ai][bj][m][n], 0, 0, 0); __builtin_amdgcn_s_setprio(0); } while (0)
; #define PG8_WAIT_V(n) asm volatile("s_waitcnt vmcnt(" #n ")" ::: "memory")
; #define PG8_WAIT_L(n) asm volatile("s_waitcnt lgkmcnt(" #n ")" ::: "memory")
; #define PG8_BAR __builtin_amdgcn_s_barrier()
; #define PG8_SCHED __builtin_amdgcn_sched_barrier(0)
; template <class Epi, class Sched>
; __device__ __forceinline__ void gemm_phase(LAS unsigned char* lds, const Gemm g, const Sched& S, const Epi& E) {
;     ...
;             PG8_WAIT_V(8); PG8_WAIT_L(0); PG8_BAR; PG8_MMA(1, 0, At, B0); PG8_MMA(1, 1, At, B1); PG8_BAR; PG8_SCHED;
;             PG8_LDB(B0, 1, 0); PG8_LDB(B1, 1, 1); PG8_SCHED; PG8_LDA(At, 1, 0); PG8_STAGE(PG8_SA(0, 1), a2 + hstepA, voffA);
;             PG8_WAIT_V(8); PG8_WAIT_L(0); PG8_BAR; PG8_MMA(0, 0, At, B0); PG8_MMA(0, 1, At, B1); PG8_BAR; PG8_SCHED;
	v_mfma_f32_16x16x32_bf16 v[62:65], v[130:133], v[178:181], v[62:65]
	v_mfma_f32_16x16x32_bf16 v[58:61], v[138:141], v[178:181], v[58:61]
	v_mfma_f32_16x16x32_bf16 v[46:49], v[130:133], v[196:199], v[46:49]
	v_mfma_f32_16x16x32_bf16 v[42:45], v[138:141], v[196:199], v[42:45]
	v_mfma_f32_16x16x32_bf16 v[30:33], v[130:133], v[204:207], v[30:33]
	v_mfma_f32_16x16x32_bf16 v[26:29], v[138:141], v[204:207], v[26:29]
	v_mfma_f32_16x16x32_bf16 v[14:17], v[130:133], v[212:215], v[14:17]
	v_mfma_f32_16x16x32_bf16 v[10:13], v[138:141], v[212:215], v[10:13]
	v_mfma_f32_16x16x32_bf16 v[62:65], v[134:137], v[182:185], v[62:65]
	v_mfma_f32_16x16x32_bf16 v[58:61], v[152:155], v[182:185], v[58:61]
	v_mfma_f32_16x16x32_bf16 v[46:49], v[134:137], v[200:203], v[46:49]
	v_mfma_f32_16x16x32_bf16 v[42:45], v[152:155], v[200:203], v[42:45]
	v_mfma_f32_16x16x32_bf16 v[30:33], v[134:137], v[208:211], v[30:33]
	v_mfma_f32_16x16x32_bf16 v[26:29], v[152:155], v[208:211], v[26:29]
	v_mfma_f32_16x16x32_bf16 v[14:17], v[134:137], v[216:219], v[14:17]
	v_mfma_f32_16x16x32_bf16 v[10:13], v[152:155], v[216:219], v[10:13]
	v_mfma_f32_16x16x32_bf16 v[54:57], v[156:159], v[178:181], v[54:57]
	v_mfma_f32_16x16x32_bf16 v[50:53], v[170:173], v[178:181], v[50:53]
	v_mfma_f32_16x16x32_bf16 v[38:41], v[156:159], v[196:199], v[38:41]
	v_mfma_f32_16x16x32_bf16 v[34:37], v[170:173], v[196:199], v[34:37]
	v_mfma_f32_16x16x32_bf16 v[22:25], v[156:159], v[204:207], v[22:25]
	v_mfma_f32_16x16x32_bf16 v[18:21], v[170:173], v[204:207], v[18:21]
	v_mfma_f32_16x16x32_bf16 v[6:9], v[156:159], v[212:215], v[6:9]
	v_mfma_f32_16x16x32_bf16 v[2:5], v[170:173], v[212:215], v[2:5]
	v_mfma_f32_16x16x32_bf16 v[54:57], v[166:169], v[182:185], v[54:57]
	v_mfma_f32_16x16x32_bf16 v[50:53], v[174:177], v[182:185], v[50:53]
	v_mfma_f32_16x16x32_bf16 v[38:41], v[166:169], v[200:203], v[38:41]
	v_mfma_f32_16x16x32_bf16 v[34:37], v[174:177], v[200:203], v[34:37]
	v_mfma_f32_16x16x32_bf16 v[22:25], v[166:169], v[208:211], v[22:25]
	v_mfma_f32_16x16x32_bf16 v[18:21], v[174:177], v[208:211], v[18:21]
	v_mfma_f32_16x16x32_bf16 v[6:9], v[166:169], v[216:219], v[6:9]
	v_mfma_f32_16x16x32_bf16 v[2:5], v[174:177], v[216:219], v[2:5]
	s_barrier
	s_setprio 0
	s_add_i32 s52, 0, 0x18000
	s_add_i32 s53, 0, 0x1c000
	v_add_u32_e32 v152, s52, v164
	v_add_u32_e32 v174, s53, v164
	ds_read_b128 v[130:133], v152
	ds_read_b128 v[134:137], v152 offset:1024
	ds_read_b128 v[138:141], v152 offset:2048
	ds_read_b128 v[152:155], v152 offset:3072
	ds_read_b128 v[156:159], v174
	ds_read_b128 v[166:169], v174 offset:1024
	ds_read_b128 v[170:173], v174 offset:2048
	ds_read_b128 v[174:177], v174 offset:3072
	s_add_u32 s88, s88, 0x40000
	s_addc_u32 s89, s89, 0
	s_mov_b32 m0, s17
	v_lshl_add_u64 v[236:237], s[88:89], 0, v[142:143]
	ds_read_b128 v[178:181], v165 offset:32768
	ds_read_b128 v[182:185], v165 offset:33792
	ds_read_b128 v[196:199], v165 offset:34816
	ds_read_b128 v[200:203], v165 offset:35840
	ds_read_b128 v[204:207], v165 offset:36864
	ds_read_b128 v[208:211], v165 offset:37888
	ds_read_b128 v[212:215], v165 offset:38912
	ds_read_b128 v[216:219], v165 offset:39936
	global_load_lds_dwordx4 v[236:237], off
	v_lshl_add_u64 v[236:237], s[88:89], 0, v[144:145]
	s_mov_b32 m0, s19
	s_nop 0
	global_load_lds_dwordx4 v[236:237], off
	s_waitcnt vmcnt(8)
	s_waitcnt lgkmcnt(0)
	s_setprio 1
	s_barrier
	v_mfma_f32_16x16x32_bf16 v[126:129], v[130:133], v[178:181], v[126:129]
	v_mfma_f32_16x16x32_bf16 v[122:125], v[138:141], v[178:181], v[122:125]
	v_mfma_f32_16x16x32_bf16 v[110:113], v[130:133], v[196:199], v[110:113]
	v_mfma_f32_16x16x32_bf16 v[106:109], v[138:141], v[196:199], v[106:109]
	v_mfma_f32_16x16x32_bf16 v[94:97], v[130:133], v[204:207], v[94:97]
	v_mfma_f32_16x16x32_bf16 v[90:93], v[138:141], v[204:207], v[90:93]
	v_mfma_f32_16x16x32_bf16 v[78:81], v[130:133], v[212:215], v[78:81]
	v_mfma_f32_16x16x32_bf16 v[74:77], v[138:141], v[212:215], v[74:77]
	v_mfma_f32_16x16x32_bf16 v[126:129], v[134:137], v[182:185], v[126:129]
	v_mfma_f32_16x16x32_bf16 v[122:125], v[152:155], v[182:185], v[122:125]
	v_mfma_f32_16x16x32_bf16 v[110:113], v[134:137], v[200:203], v[110:113]
	v_mfma_f32_16x16x32_bf16 v[106:109], v[152:155], v[200:203], v[106:109]
	v_mfma_f32_16x16x32_bf16 v[94:97], v[134:137], v[208:211], v[94:97]
	v_mfma_f32_16x16x32_bf16 v[90:93], v[152:155], v[208:211], v[90:93]
	v_mfma_f32_16x16x32_bf16 v[78:81], v[134:137], v[216:219], v[78:81]
	v_mfma_f32_16x16x32_bf16 v[74:77], v[152:155], v[216:219], v[74:77]
	v_mfma_f32_16x16x32_bf16 v[118:121], v[156:159], v[178:181], v[118:121]
	v_mfma_f32_16x16x32_bf16 v[114:117], v[170:173], v[178:181], v[114:117]
	v_mfma_f32_16x16x32_bf16 v[102:105], v[156:159], v[196:199], v[102:105]
	v_mfma_f32_16x16x32_bf16 v[98:101], v[170:173], v[196:199], v[98:101]
	v_mfma_f32_16x16x32_bf16 v[86:89], v[156:159], v[204:207], v[86:89]
	v_mfma_f32_16x16x32_bf16 v[82:85], v[170:173], v[204:207], v[82:85]
	v_mfma_f32_16x16x32_bf16 v[70:73], v[156:159], v[212:215], v[70:73]
	v_mfma_f32_16x16x32_bf16 v[66:69], v[170:173], v[212:215], v[66:69]
	v_mfma_f32_16x16x32_bf16 v[118:121], v[166:169], v[182:185], v[118:121]
	v_mfma_f32_16x16x32_bf16 v[114:117], v[174:177], v[182:185], v[114:117]
	v_mfma_f32_16x16x32_bf16 v[102:105], v[166:169], v[200:203], v[102:105]
	v_mfma_f32_16x16x32_bf16 v[98:101], v[174:177], v[200:203], v[98:101]
	v_mfma_f32_16x16x32_bf16 v[86:89], v[166:169], v[208:211], v[86:89]
	v_mfma_f32_16x16x32_bf16 v[82:85], v[174:177], v[208:211], v[82:85]
	v_mfma_f32_16x16x32_bf16 v[70:73], v[166:169], v[216:219], v[70:73]
	v_mfma_f32_16x16x32_bf16 v[66:69], v[174:177], v[216:219], v[66:69]
	s_barrier
; #define PG8_STAGE(bufoff, gbase, voff) do { _Pragma("unroll") for (int _i = 0; _i < 2; ++_i) \
;         __builtin_amdgcn_global_load_lds((const unsigned*)((const char*)(gbase) + (voff)[_i]), (LAS unsigned*)(lds + (bufoff) + ldsw + _i * 8192), 16, 0, 0); } while (0)
; #define PG8_LDA(dst, b, h) do { _Pragma("unroll") for (int m = 0; m < 4; ++m) _Pragma("unroll") for (int k = 0; k < 2; ++k) dst[m][k] = *(const LAS bf16x8*)(lds + PG8_SA(b, h) + aoff + m * 2048 + k * 1024); } while (0)
; #define PG8_MMA(ai, bj, At, Bt) do { __builtin_amdgcn_s_setprio(1); _Pragma("unroll") for (int m = 0; m < 4; ++m) _Pragma("unroll") for (int n = 0; n < 2; ++n) _Pragma("unroll") for (int k = 0; k < 2; ++k) \
;         acc[ai][bj][m][n] = __builtin_amdgcn_mfma_f32_16x16x32_bf16(Bt[n][k], At[m][k], acc[ai][bj][m][n], 0, 0, 0); __builtin_amdgcn_s_setprio(0); } while (0)
; #define PG8_WAIT_V(n) asm volatile("s_waitcnt vmcnt(" #n ")" ::: "memory")
; #define PG8_WAIT_L(n) asm volatile("s_waitcnt lgkmcnt(" #n ")" ::: "memory")
; #define PG8_BAR __builtin_amdgcn_s_barrier()
; #define PG8_SCHED __builtin_amdgcn_sched_barrier(0)
; template <class Epi, class Sched>
; __device__ __forceinline__ void gemm_phase(LAS unsigned char* lds, const Gemm g, const Sched& S, const Epi& E) {
;     ...
;         for (int t = 0; t < nt; t += 2) {
;             if constexpr (Epi::HOOKS) { if (cur.kind == 3 && (t == 4 || t == 12)) { int fr_ = fr, fq_ = fq; asm volatile("" : "+v"(fr_), "+v"(fq_)); E.hook(acc, cur, t == 4 ? 0 : 1, wr, wc, fr_, fq_); } }
;             const bool last = (t == nt - 2);
;             const char* a1 = cA + (size_t)(t + 1) * kstep;
;             const char* a2 = last ? nA : cA + (size_t)(t + 2) * kstep; const char* b2 = last ? nB : cB + (size_t)(t + 2) * kstep;
;             const char* a3 = a2 + kstep; const char* b3 = b2 + kstep;
;     ...
;             PG8_LDA(At, 1, 1); PG8_STAGE(PG8_SB(1, 0), b3, voffB); PG8_STAGE(PG8_SB(1, 1), b3 + hstepB, voffB); PG8_STAGE(PG8_SA(1, 0), a3, voffA);
;             PG8_WAIT_V(8); PG8_WAIT_L(0); PG8_BAR; PG8_MMA(1, 0, At, B0); PG8_MMA(1, 1, At, B1); PG8_BAR; PG8_SCHED;
	s_setprio 0
	s_add_i32 s52, s52, s14
	v_lshl_add_u64 v[160:161], v[160:161], 0, s[26:27]
	s_mov_b32 m0, s52
	ds_read_b128 v[178:181], v165 offset:49152
	ds_read_b128 v[182:185], v165 offset:50176
	ds_read_b128 v[196:199], v165 offset:51200
	ds_read_b128 v[200:203], v165 offset:52224
	ds_read_b128 v[204:207], v165 offset:53248
	ds_read_b128 v[208:211], v165 offset:54272
	ds_read_b128 v[212:215], v165 offset:55296
	ds_read_b128 v[216:219], v165 offset:56320
	global_load_lds_dwordx4 v[160:161], off
	s_add_i32 m0, s52, 0x2000
	s_add_u32 s0, s0, 0x40080
	v_lshl_add_u64 v[160:161], v[220:221], 0, s[26:27]
	s_addc_u32 s1, s1, 0
	s_add_i32 s52, s53, s14
	global_load_lds_dwordx4 v[160:161], off
	v_lshl_add_u64 v[160:161], s[0:1], 0, v[0:1]
	s_mov_b32 m0, s52
	s_nop 0
	global_load_lds_dwordx4 v[160:161], off
	v_lshl_add_u64 v[160:161], s[0:1], 0, v[146:147]
	s_add_i32 m0, s52, 0x2000
	s_nop 0
	global_load_lds_dwordx4 v[160:161], off
	v_lshl_add_u64 v[160:161], v[232:233], 0, s[26:27]
	s_mov_b32 m0, s67
	s_nop 0
	global_load_lds_dwordx4 v[160:161], off
	v_lshl_add_u64 v[160:161], v[234:235], 0, s[26:27]
	s_mov_b32 m0, s69
	s_nop 0
	global_load_lds_dwordx4 v[160:161], off
	s_waitcnt vmcnt(8)
	s_waitcnt lgkmcnt(0)
	s_setprio 1
	s_barrier
	v_mfma_f32_16x16x32_bf16 v[62:65], v[130:133], v[178:181], v[62:65]
	v_mfma_f32_16x16x32_bf16 v[58:61], v[138:141], v[178:181], v[58:61]
	v_mfma_f32_16x16x32_bf16 v[46:49], v[130:133], v[196:199], v[46:49]
	v_mfma_f32_16x16x32_bf16 v[42:45], v[138:141], v[196:199], v[42:45]
	v_mfma_f32_16x16x32_bf16 v[30:33], v[130:133], v[204:207], v[30:33]
	v_mfma_f32_16x16x32_bf16 v[26:29], v[138:141], v[204:207], v[26:29]
	v_mfma_f32_16x16x32_bf16 v[14:17], v[130:133], v[212:215], v[14:17]
	v_mfma_f32_16x16x32_bf16 v[10:13], v[138:141], v[212:215], v[10:13]
	v_mfma_f32_16x16x32_bf16 v[62:65], v[134:137], v[182:185], v[62:65]
	v_mfma_f32_16x16x32_bf16 v[58:61], v[152:155], v[182:185], v[58:61]
	v_mfma_f32_16x16x32_bf16 v[46:49], v[134:137], v[200:203], v[46:49]
	v_mfma_f32_16x16x32_bf16 v[42:45], v[152:155], v[200:203], v[42:45]
	v_mfma_f32_16x16x32_bf16 v[30:33], v[134:137], v[208:211], v[30:33]
	v_mfma_f32_16x16x32_bf16 v[26:29], v[152:155], v[208:211], v[26:29]
	v_mfma_f32_16x16x32_bf16 v[14:17], v[134:137], v[216:219], v[14:17]
	v_mfma_f32_16x16x32_bf16 v[10:13], v[152:155], v[216:219], v[10:13]
	v_mfma_f32_16x16x32_bf16 v[54:57], v[156:159], v[178:181], v[54:57]
	v_mfma_f32_16x16x32_bf16 v[50:53], v[170:173], v[178:181], v[50:53]
	v_mfma_f32_16x16x32_bf16 v[38:41], v[156:159], v[196:199], v[38:41]
	v_mfma_f32_16x16x32_bf16 v[34:37], v[170:173], v[196:199], v[34:37]
	v_mfma_f32_16x16x32_bf16 v[22:25], v[156:159], v[204:207], v[22:25]
	v_mfma_f32_16x16x32_bf16 v[18:21], v[170:173], v[204:207], v[18:21]
	v_mfma_f32_16x16x32_bf16 v[6:9], v[156:159], v[212:215], v[6:9]
	v_mfma_f32_16x16x32_bf16 v[2:5], v[170:173], v[212:215], v[2:5]
	v_mfma_f32_16x16x32_bf16 v[54:57], v[166:169], v[182:185], v[54:57]
	v_mfma_f32_16x16x32_bf16 v[50:53], v[174:177], v[182:185], v[50:53]
	v_mfma_f32_16x16x32_bf16 v[38:41], v[166:169], v[200:203], v[38:41]
	v_mfma_f32_16x16x32_bf16 v[34:37], v[174:177], v[200:203], v[34:37]
	v_mfma_f32_16x16x32_bf16 v[22:25], v[166:169], v[208:211], v[22:25]
	v_mfma_f32_16x16x32_bf16 v[18:21], v[174:177], v[208:211], v[18:21]
	v_mfma_f32_16x16x32_bf16 v[6:9], v[166:169], v[216:219], v[6:9]
	v_mfma_f32_16x16x32_bf16 v[2:5], v[174:177], v[216:219], v[2:5]
	s_barrier
	s_setprio 0
	s_add_u32 s87, s87, 0x100
	s_addc_u32 s90, s90, 0
	s_add_u32 s20, s20, 0x100
	s_addc_u32 s21, s21, 0
	s_cmp_ge_i32 s68, s46
	s_mov_b32 s0, s68
	s_cbranch_scc0 .LBB0_238

; #define PG8_STAGE(bufoff, gbase, voff) do { _Pragma("unroll") for (int _i = 0; _i < 2; ++_i) \
;         __builtin_amdgcn_global_load_lds((const unsigned*)((const char*)(gbase) + (voff)[_i]), (LAS unsigned*)(lds + (bufoff) + ldsw + _i * 8192), 16, 0, 0); } while (0)
; #define PG8_LDA(dst, b, h) do { _Pragma("unroll") for (int m = 0; m < 4; ++m) _Pragma("unroll") for (int k = 0; k < 2; ++k) dst[m][k] = *(const LAS bf16x8*)(lds + PG8_SA(b, h) + aoff + m * 2048 + k * 1024); } while (0)
; #define PG8_LDB(dst, b, h) do { _Pragma("unroll") for (int n = 0; n < 2; ++n) _Pragma("unroll") for (int k = 0; k < 2; ++k) dst[n][k] = *(const LAS bf16x8*)(lds + PG8_SB(b, h) + boff + n * 2048 + k * 1024); } while (0)
; #define PG8_MMA(ai, bj, At, Bt) do { __builtin_amdgcn_s_setprio(1); _Pragma("unroll") for (int m = 0; m < 4; ++m) _Pragma("unroll") for (int n = 0; n < 2; ++n) _Pragma("unroll") for (int k = 0; k < 2; ++k) \
;         acc[ai][bj][m][n] = __builtin_amdgcn_mfma_f32_16x16x32_bf16(Bt[n][k], At[m][k], acc[ai][bj][m][n], 0, 0, 0); __builtin_amdgcn_s_setprio(0); } while (0)
; #define PG8_WAIT_V(n) asm volatile("s_waitcnt vmcnt(" #n ")" ::: "memory")
; template <class Epi, class Sched>
; __device__ __forceinline__ void gemm_phase(LAS unsigned char* lds, const Gemm g, const Sched& S, const Epi& E) {
;     ...
;         for (int t = 0; t < nt; t += 2) {
;             if constexpr (Epi::HOOKS) { if (cur.kind == 3 && (t == 4 || t == 12)) { int fr_ = fr, fq_ = fq; asm volatile("" : "+v"(fr_), "+v"(fq_)); E.hook(acc, cur, t == 4 ? 0 : 1, wr, wc, fr_, fq_); } }
;             const bool last = (t == nt - 2);
;             const char* a1 = cA + (size_t)(t + 1) * kstep;
;             const char* a2 = last ? nA : cA + (size_t)(t + 2) * kstep; const char* b2 = last ? nB : cB + (size_t)(t + 2) * kstep;
;             const char* a3 = a2 + kstep; const char* b3 = b2 + kstep;
;             PG8_LDB(B0, 0, 0); PG8_LDB(B1, 0, 1); PG8_SCHED; PG8_LDA(At, 0, 0); PG8_STAGE(PG8_SA(1, 1), a1 + hstepA, voffA);
;             PG8_WAIT_V(8); PG8_WAIT_L(0); PG8_BAR; PG8_MMA(0, 0, At, B0); PG8_MMA(0, 1, At, B1); PG8_BAR; PG8_SCHED;
;             PG8_LDA(At, 0, 1); PG8_STAGE(PG8_SB(0, 0), b2, voffB); PG8_STAGE(PG8_SB(0, 1), b2 + hstepB, voffB); PG8_STAGE(PG8_SA(0, 0), a2, voffA);
;             PG8_WAIT_V(8); PG8_WAIT_L(0); PG8_BAR; PG8_MMA(1, 0, At, B0); PG8_MMA(1, 1, At, B1); PG8_BAR; PG8_SCHED;
.LBB0_291:
	s_add_i32 s68, s19, 2
	s_add_u32 s0, s30, s40
	s_addc_u32 s1, s31, s41
	s_add_u32 s0, s0, 0x100
	s_addc_u32 s1, s1, 0
	s_add_u32 s52, s69, s40
	s_addc_u32 s53, s72, s41
	s_add_i32 s76, 0, 0x10000
	s_cmp_eq_u32 s71, s19
	s_cselect_b32 s21, s16, s1
	s_cselect_b32 s20, s17, s0
	s_cselect_b32 s1, s87, s53
	s_cselect_b32 s0, s86, s52
	s_add_i32 s19, 0, 0x14000
	v_add_u32_e32 v142, s76, v195
	v_add_u32_e32 v172, s19, v195
	ds_read_b128 v[130:133], v142
	ds_read_b128 v[134:137], v142 offset:1024
	ds_read_b128 v[138:141], v142 offset:2048
	ds_read_b128 v[142:145], v142 offset:3072
	ds_read_b128 v[146:149], v172
	ds_read_b128 v[164:167], v172 offset:1024
	ds_read_b128 v[168:171], v172 offset:2048
	ds_read_b128 v[172:175], v172 offset:3072
	v_lshl_add_u64 v[182:183], v[162:163], 0, s[40:41]
	s_add_i32 m0, s25, 0xc000
	ds_read_b128 v[176:179], v199
	ds_read_b128 v[200:203], v199 offset:1024
	ds_read_b128 v[204:207], v199 offset:2048
	ds_read_b128 v[208:211], v199 offset:3072
	ds_read_b128 v[212:215], v199 offset:4096
	ds_read_b128 v[216:219], v199 offset:5120
	ds_read_b128 v[232:235], v199 offset:6144
	ds_read_b128 v[248:251], v199 offset:7168
	global_load_lds_dwordx4 v[182:183], off
	v_lshl_add_u64 v[182:183], v[160:161], 0, s[40:41]
	s_add_i32 m0, s25, 0xe000
	s_nop 0
	global_load_lds_dwordx4 v[182:183], off
	s_waitcnt vmcnt(8)
	s_waitcnt lgkmcnt(0)
	s_setprio 1
	s_barrier
	v_mfma_f32_16x16x32_bf16 v[126:129], v[130:133], v[176:179], v[126:129]
	v_mfma_f32_16x16x32_bf16 v[122:125], v[138:141], v[176:179], v[122:125]
	v_mfma_f32_16x16x32_bf16 v[118:121], v[130:133], v[204:207], v[118:121]
	v_mfma_f32_16x16x32_bf16 v[114:117], v[138:141], v[204:207], v[114:117]
	v_mfma_f32_16x16x32_bf16 v[110:113], v[130:133], v[212:215], v[110:113]
	v_mfma_f32_16x16x32_bf16 v[106:109], v[138:141], v[212:215], v[106:109]
	v_mfma_f32_16x16x32_bf16 v[102:105], v[130:133], v[232:235], v[102:105]
	v_mfma_f32_16x16x32_bf16 v[98:101], v[138:141], v[232:235], v[98:101]
	v_mfma_f32_16x16x32_bf16 v[126:129], v[134:137], v[200:203], v[126:129]
	v_mfma_f32_16x16x32_bf16 v[122:125], v[142:145], v[200:203], v[122:125]
	v_mfma_f32_16x16x32_bf16 v[118:121], v[134:137], v[208:211], v[118:121]
	v_mfma_f32_16x16x32_bf16 v[114:117], v[142:145], v[208:211], v[114:117]
	v_mfma_f32_16x16x32_bf16 v[110:113], v[134:137], v[216:219], v[110:113]
	v_mfma_f32_16x16x32_bf16 v[106:109], v[142:145], v[216:219], v[106:109]
	v_mfma_f32_16x16x32_bf16 v[102:105], v[134:137], v[248:251], v[102:105]
	v_mfma_f32_16x16x32_bf16 v[98:101], v[142:145], v[248:251], v[98:101]
	v_mfma_f32_16x16x32_bf16 v[62:65], v[146:149], v[176:179], v[62:65]
	v_mfma_f32_16x16x32_bf16 v[58:61], v[168:171], v[176:179], v[58:61]
	v_mfma_f32_16x16x32_bf16 v[54:57], v[146:149], v[204:207], v[54:57]
	v_mfma_f32_16x16x32_bf16 v[50:53], v[168:171], v[204:207], v[50:53]
	v_mfma_f32_16x16x32_bf16 v[46:49], v[146:149], v[212:215], v[46:49]
	v_mfma_f32_16x16x32_bf16 v[42:45], v[168:171], v[212:215], v[42:45]
	v_mfma_f32_16x16x32_bf16 v[38:41], v[146:149], v[232:235], v[38:41]
	v_mfma_f32_16x16x32_bf16 v[34:37], v[168:171], v[232:235], v[34:37]
	v_mfma_f32_16x16x32_bf16 v[62:65], v[164:167], v[200:203], v[62:65]
	v_mfma_f32_16x16x32_bf16 v[58:61], v[172:175], v[200:203], v[58:61]
	v_mfma_f32_16x16x32_bf16 v[54:57], v[164:167], v[208:211], v[54:57]
	v_mfma_f32_16x16x32_bf16 v[50:53], v[172:175], v[208:211], v[50:53]
	v_mfma_f32_16x16x32_bf16 v[46:49], v[164:167], v[216:219], v[46:49]
	v_mfma_f32_16x16x32_bf16 v[42:45], v[172:175], v[216:219], v[42:45]
	v_mfma_f32_16x16x32_bf16 v[38:41], v[164:167], v[248:251], v[38:41]
	v_mfma_f32_16x16x32_bf16 v[34:37], v[172:175], v[248:251], v[34:37]
	s_barrier
	s_setprio 0
	s_add_i32 s52, s76, s92
	v_lshl_add_u64 v[182:183], s[0:1], 0, v[0:1]
	s_mov_b32 m0, s52
	ds_read_b128 v[176:179], v199 offset:16384
	ds_read_b128 v[200:203], v199 offset:17408
	ds_read_b128 v[204:207], v199 offset:18432
	ds_read_b128 v[208:211], v199 offset:19456
	ds_read_b128 v[212:215], v199 offset:20480
	ds_read_b128 v[216:219], v199 offset:21504
	ds_read_b128 v[232:235], v199 offset:22528
	ds_read_b128 v[248:251], v199 offset:23552
	global_load_lds_dwordx4 v[182:183], off
	s_add_i32 m0, s52, 0x2000
	s_add_u32 vcc_lo, s0, 0x40000
	v_lshl_add_u64 v[196:197], s[0:1], 0, v[154:155]
	s_addc_u32 vcc_hi, s1, 0
	s_add_i32 s19, s19, s92
	global_load_lds_dwordx4 v[196:197], off
	v_lshl_add_u64 v[220:221], vcc, 0, v[0:1]
	s_mov_b32 m0, s19
	v_lshl_add_u64 v[236:237], s[20:21], 0, v[152:153]
	global_load_lds_dwordx4 v[220:221], off
	v_lshl_add_u64 v[220:221], vcc, 0, v[154:155]
	s_add_i32 m0, s19, 0x2000
	s_nop 0
	global_load_lds_dwordx4 v[220:221], off
	v_lshl_add_u64 v[220:221], s[20:21], 0, v[150:151]
	s_mov_b32 m0, s25
	s_nop 0
	global_load_lds_dwordx4 v[220:221], off
	s_mov_b32 m0, s93
	s_nop 0
	global_load_lds_dwordx4 v[236:237], off
	s_waitcnt vmcnt(8)
	s_waitcnt lgkmcnt(0)
	s_setprio 1
	s_barrier
; #define PG8_STAGE(bufoff, gbase, voff) do { _Pragma("unroll") for (int _i = 0; _i < 2; ++_i) \
;         __builtin_amdgcn_global_load_lds((const unsigned*)((const char*)(gbase) + (voff)[_i]), (LAS unsigned*)(lds + (bufoff) + ldsw + _i * 8192), 16, 0, 0); } while (0)
; #define PG8_LDA(dst, b, h) do { _Pragma("unroll") for (int m = 0; m < 4; ++m) _Pragma("unroll") for (int k = 0; k < 2; ++k) dst[m][k] = *(const LAS bf16x8*)(lds + PG8_SA(b, h) + aoff + m * 2048 + k * 1024); } while (0)
; #define PG8_LDB(dst, b, h) do { _Pragma("unroll") for (int n = 0; n < 2; ++n) _Pragma("unroll") for (int k = 0; k < 2; ++k) dst[n][k] = *(const LAS bf16x8*)(lds + PG8_SB(b, h) + boff + n * 2048 + k * 1024); } while (0)
; #define PG8_MMA(ai, bj, At, Bt) do { __builtin_amdgcn_s_setprio(1); _Pragma("unroll") for (int m = 0; m < 4; ++m) _Pragma("unroll") for (int n = 0; n < 2; ++n) _Pragma("unroll") for (int k = 0; k < 2; ++k) \
;         acc[ai][bj][m][n] = __builtin_amdgcn_mfma_f32_16x16x32_bf16(Bt[n][k], At[m][k], acc[ai][bj][m][n], 0, 0, 0); __builtin_amdgcn_s_setprio(0); } while (0)
; #define PG8_WAIT_V(n) asm volatile("s_waitcnt vmcnt(" #n ")" ::: "memory")
; #define PG8_WAIT_L(n) asm volatile("s_waitcnt lgkmcnt(" #n ")" ::: "memory")
; #define PG8_BAR __builtin_amdgcn_s_barrier()
; #define PG8_SCHED __builtin_amdgcn_sched_barrier(0)
; template <class Epi, class Sched>
; __device__ __forceinline__ void gemm_phase(LAS unsigned char* lds, const Gemm g, const Sched& S, const Epi& E) {
;     ...
;             PG8_WAIT_V(8); PG8_WAIT_L(0); PG8_BAR; PG8_MMA(1, 0, At, B0); PG8_MMA(1, 1, At, B1); PG8_BAR; PG8_SCHED;
;             PG8_LDB(B0, 1, 0); PG8_LDB(B1, 1, 1); PG8_SCHED; PG8_LDA(At, 1, 0); PG8_STAGE(PG8_SA(0, 1), a2 + hstepA, voffA);
;             PG8_WAIT_V(8); PG8_WAIT_L(0); PG8_BAR; PG8_MMA(0, 0, At, B0); PG8_MMA(0, 1, At, B1); PG8_BAR; PG8_SCHED;
	v_mfma_f32_16x16x32_bf16 v[94:97], v[130:133], v[176:179], v[94:97]
	v_mfma_f32_16x16x32_bf16 v[90:93], v[138:141], v[176:179], v[90:93]
	v_mfma_f32_16x16x32_bf16 v[86:89], v[130:133], v[204:207], v[86:89]
	v_mfma_f32_16x16x32_bf16 v[82:85], v[138:141], v[204:207], v[82:85]
	v_mfma_f32_16x16x32_bf16 v[78:81], v[130:133], v[212:215], v[78:81]
	v_mfma_f32_16x16x32_bf16 v[74:77], v[138:141], v[212:215], v[74:77]
	v_mfma_f32_16x16x32_bf16 v[70:73], v[130:133], v[232:235], v[70:73]
	v_mfma_f32_16x16x32_bf16 v[66:69], v[138:141], v[232:235], v[66:69]
	v_mfma_f32_16x16x32_bf16 v[94:97], v[134:137], v[200:203], v[94:97]
	v_mfma_f32_16x16x32_bf16 v[90:93], v[142:145], v[200:203], v[90:93]
	v_mfma_f32_16x16x32_bf16 v[86:89], v[134:137], v[208:211], v[86:89]
	v_mfma_f32_16x16x32_bf16 v[82:85], v[142:145], v[208:211], v[82:85]
	v_mfma_f32_16x16x32_bf16 v[78:81], v[134:137], v[216:219], v[78:81]
	v_mfma_f32_16x16x32_bf16 v[74:77], v[142:145], v[216:219], v[74:77]
	v_mfma_f32_16x16x32_bf16 v[70:73], v[134:137], v[248:251], v[70:73]
	v_mfma_f32_16x16x32_bf16 v[66:69], v[142:145], v[248:251], v[66:69]
	v_mfma_f32_16x16x32_bf16 v[30:33], v[146:149], v[176:179], v[30:33]
	v_mfma_f32_16x16x32_bf16 v[26:29], v[168:171], v[176:179], v[26:29]
	v_mfma_f32_16x16x32_bf16 v[22:25], v[146:149], v[204:207], v[22:25]
	v_mfma_f32_16x16x32_bf16 v[18:21], v[168:171], v[204:207], v[18:21]
	v_mfma_f32_16x16x32_bf16 v[14:17], v[146:149], v[212:215], v[14:17]
	v_mfma_f32_16x16x32_bf16 v[10:13], v[168:171], v[212:215], v[10:13]
	v_mfma_f32_16x16x32_bf16 v[6:9], v[146:149], v[232:235], v[6:9]
	v_mfma_f32_16x16x32_bf16 v[2:5], v[168:171], v[232:235], v[2:5]
	v_mfma_f32_16x16x32_bf16 v[30:33], v[164:167], v[200:203], v[30:33]
	v_mfma_f32_16x16x32_bf16 v[26:29], v[172:175], v[200:203], v[26:29]
	v_mfma_f32_16x16x32_bf16 v[22:25], v[164:167], v[208:211], v[22:25]
	v_mfma_f32_16x16x32_bf16 v[18:21], v[172:175], v[208:211], v[18:21]
	v_mfma_f32_16x16x32_bf16 v[14:17], v[164:167], v[216:219], v[14:17]
	v_mfma_f32_16x16x32_bf16 v[10:13], v[172:175], v[216:219], v[10:13]
	v_mfma_f32_16x16x32_bf16 v[6:9], v[164:167], v[248:251], v[6:9]
	v_mfma_f32_16x16x32_bf16 v[2:5], v[172:175], v[248:251], v[2:5]
	s_barrier
	s_setprio 0
	s_add_i32 s19, 0, 0x18000
	s_add_i32 s52, 0, 0x1c000
	v_add_u32_e32 v142, s19, v195
	v_add_u32_e32 v172, s52, v195
	ds_read_b128 v[130:133], v142
	ds_read_b128 v[134:137], v142 offset:1024
	ds_read_b128 v[138:141], v142 offset:2048
	ds_read_b128 v[142:145], v142 offset:3072
	ds_read_b128 v[146:149], v172
	ds_read_b128 v[164:167], v172 offset:1024
	ds_read_b128 v[168:171], v172 offset:2048
	ds_read_b128 v[172:175], v172 offset:3072
	s_add_u32 s20, s20, 0x40000
	s_addc_u32 s21, s21, 0
	s_mov_b32 m0, s94
	v_lshl_add_u64 v[246:247], s[20:21], 0, v[150:151]
	ds_read_b128 v[176:179], v199 offset:32768
	ds_read_b128 v[200:203], v199 offset:33792
	ds_read_b128 v[204:207], v199 offset:34816
	ds_read_b128 v[208:211], v199 offset:35840
	ds_read_b128 v[212:215], v199 offset:36864
	ds_read_b128 v[216:219], v199 offset:37888
	ds_read_b128 v[232:235], v199 offset:38912
	ds_read_b128 v[248:251], v199 offset:39936
	global_load_lds_dwordx4 v[246:247], off
	v_lshl_add_u64 v[246:247], s[20:21], 0, v[152:153]
	s_mov_b32 m0, s95
	s_nop 0
	global_load_lds_dwordx4 v[246:247], off
	s_waitcnt vmcnt(8)
	s_waitcnt lgkmcnt(0)
	s_setprio 1
	s_barrier
	v_mfma_f32_16x16x32_bf16 v[126:129], v[130:133], v[176:179], v[126:129]
	v_mfma_f32_16x16x32_bf16 v[122:125], v[138:141], v[176:179], v[122:125]
	v_mfma_f32_16x16x32_bf16 v[118:121], v[130:133], v[204:207], v[118:121]
	v_mfma_f32_16x16x32_bf16 v[114:117], v[138:141], v[204:207], v[114:117]
	v_mfma_f32_16x16x32_bf16 v[110:113], v[130:133], v[212:215], v[110:113]
	v_mfma_f32_16x16x32_bf16 v[106:109], v[138:141], v[212:215], v[106:109]
	v_mfma_f32_16x16x32_bf16 v[102:105], v[130:133], v[232:235], v[102:105]
	v_mfma_f32_16x16x32_bf16 v[98:101], v[138:141], v[232:235], v[98:101]
	v_mfma_f32_16x16x32_bf16 v[126:129], v[134:137], v[200:203], v[126:129]
	v_mfma_f32_16x16x32_bf16 v[122:125], v[142:145], v[200:203], v[122:125]
	v_mfma_f32_16x16x32_bf16 v[118:121], v[134:137], v[208:211], v[118:121]
	v_mfma_f32_16x16x32_bf16 v[114:117], v[142:145], v[208:211], v[114:117]
	v_mfma_f32_16x16x32_bf16 v[110:113], v[134:137], v[216:219], v[110:113]
	v_mfma_f32_16x16x32_bf16 v[106:109], v[142:145], v[216:219], v[106:109]
	v_mfma_f32_16x16x32_bf16 v[102:105], v[134:137], v[248:251], v[102:105]
	v_mfma_f32_16x16x32_bf16 v[98:101], v[142:145], v[248:251], v[98:101]
	v_mfma_f32_16x16x32_bf16 v[62:65], v[146:149], v[176:179], v[62:65]
	v_mfma_f32_16x16x32_bf16 v[58:61], v[168:171], v[176:179], v[58:61]
	v_mfma_f32_16x16x32_bf16 v[54:57], v[146:149], v[204:207], v[54:57]
	v_mfma_f32_16x16x32_bf16 v[50:53], v[168:171], v[204:207], v[50:53]
	v_mfma_f32_16x16x32_bf16 v[46:49], v[146:149], v[212:215], v[46:49]
	v_mfma_f32_16x16x32_bf16 v[42:45], v[168:171], v[212:215], v[42:45]
	v_mfma_f32_16x16x32_bf16 v[38:41], v[146:149], v[232:235], v[38:41]
	v_mfma_f32_16x16x32_bf16 v[34:37], v[168:171], v[232:235], v[34:37]
	v_mfma_f32_16x16x32_bf16 v[62:65], v[164:167], v[200:203], v[62:65]
	v_mfma_f32_16x16x32_bf16 v[58:61], v[172:175], v[200:203], v[58:61]
	v_mfma_f32_16x16x32_bf16 v[54:57], v[164:167], v[208:211], v[54:57]
	v_mfma_f32_16x16x32_bf16 v[50:53], v[172:175], v[208:211], v[50:53]
	v_mfma_f32_16x16x32_bf16 v[46:49], v[164:167], v[216:219], v[46:49]
	v_mfma_f32_16x16x32_bf16 v[42:45], v[172:175], v[216:219], v[42:45]
	v_mfma_f32_16x16x32_bf16 v[38:41], v[164:167], v[248:251], v[38:41]
	v_mfma_f32_16x16x32_bf16 v[34:37], v[172:175], v[248:251], v[34:37]
	s_barrier
; #define PG8_STAGE(bufoff, gbase, voff) do { _Pragma("unroll") for (int _i = 0; _i < 2; ++_i) \
;         __builtin_amdgcn_global_load_lds((const unsigned*)((const char*)(gbase) + (voff)[_i]), (LAS unsigned*)(lds + (bufoff) + ldsw + _i * 8192), 16, 0, 0); } while (0)
; #define PG8_LDA(dst, b, h) do { _Pragma("unroll") for (int m = 0; m < 4; ++m) _Pragma("unroll") for (int k = 0; k < 2; ++k) dst[m][k] = *(const LAS bf16x8*)(lds + PG8_SA(b, h) + aoff + m * 2048 + k * 1024); } while (0)
; #define PG8_MMA(ai, bj, At, Bt) do { __builtin_amdgcn_s_setprio(1); _Pragma("unroll") for (int m = 0; m < 4; ++m) _Pragma("unroll") for (int n = 0; n < 2; ++n) _Pragma("unroll") for (int k = 0; k < 2; ++k) \
;         acc[ai][bj][m][n] = __builtin_amdgcn_mfma_f32_16x16x32_bf16(Bt[n][k], At[m][k], acc[ai][bj][m][n], 0, 0, 0); __builtin_amdgcn_s_setprio(0); } while (0)
; #define PG8_WAIT_V(n) asm volatile("s_waitcnt vmcnt(" #n ")" ::: "memory")
; #define PG8_WAIT_L(n) asm volatile("s_waitcnt lgkmcnt(" #n ")" ::: "memory")
; #define PG8_BAR __builtin_amdgcn_s_barrier()
; #define PG8_SCHED __builtin_amdgcn_sched_barrier(0)
; template <class Epi, class Sched>
; __device__ __forceinline__ void gemm_phase(LAS unsigned char* lds, const Gemm g, const Sched& S, const Epi& E) {
;     ...
;             PG8_LDA(At, 1, 1); PG8_STAGE(PG8_SB(1, 0), b3, voffB); PG8_STAGE(PG8_SB(1, 1), b3 + hstepB, voffB); PG8_STAGE(PG8_SA(1, 0), a3, voffA);
;             PG8_WAIT_V(8); PG8_WAIT_L(0); PG8_BAR; PG8_MMA(1, 0, At, B0); PG8_MMA(1, 1, At, B1); PG8_BAR; PG8_SCHED;
;         }
	s_setprio 0
	s_add_i32 s19, s19, s92
	v_lshl_add_u64 v[182:183], v[182:183], 0, s[26:27]
	s_mov_b32 m0, s19
	ds_read_b128 v[176:179], v199 offset:49152
	ds_read_b128 v[200:203], v199 offset:50176
	ds_read_b128 v[204:207], v199 offset:51200
	ds_read_b128 v[208:211], v199 offset:52224
	ds_read_b128 v[212:215], v199 offset:53248
	ds_read_b128 v[216:219], v199 offset:54272
	ds_read_b128 v[232:235], v199 offset:55296
	ds_read_b128 v[248:251], v199 offset:56320
	global_load_lds_dwordx4 v[182:183], off
	s_add_i32 m0, s19, 0x2000
	s_add_u32 s0, s0, 0x40080
	v_lshl_add_u64 v[182:183], v[196:197], 0, s[26:27]
	s_addc_u32 s1, s1, 0
	s_add_i32 s19, s52, s92
	global_load_lds_dwordx4 v[182:183], off
	v_lshl_add_u64 v[182:183], s[0:1], 0, v[0:1]
	s_mov_b32 m0, s19
	s_nop 0
	global_load_lds_dwordx4 v[182:183], off
	v_lshl_add_u64 v[182:183], s[0:1], 0, v[154:155]
	s_add_i32 m0, s19, 0x2000
	s_nop 0
	global_load_lds_dwordx4 v[182:183], off
	v_lshl_add_u64 v[182:183], v[220:221], 0, s[26:27]
	s_mov_b32 m0, s97
	s_nop 0
	global_load_lds_dwordx4 v[182:183], off
	v_lshl_add_u64 v[182:183], v[236:237], 0, s[26:27]
	s_mov_b32 m0, s44
	s_nop 0
	global_load_lds_dwordx4 v[182:183], off
	s_waitcnt vmcnt(8)
	s_waitcnt lgkmcnt(0)
	s_setprio 1
	s_barrier
	v_mfma_f32_16x16x32_bf16 v[94:97], v[130:133], v[176:179], v[94:97]
	v_mfma_f32_16x16x32_bf16 v[90:93], v[138:141], v[176:179], v[90:93]
	v_mfma_f32_16x16x32_bf16 v[86:89], v[130:133], v[204:207], v[86:89]
	v_mfma_f32_16x16x32_bf16 v[82:85], v[138:141], v[204:207], v[82:85]
	v_mfma_f32_16x16x32_bf16 v[78:81], v[130:133], v[212:215], v[78:81]
	v_mfma_f32_16x16x32_bf16 v[74:77], v[138:141], v[212:215], v[74:77]
	v_mfma_f32_16x16x32_bf16 v[70:73], v[130:133], v[232:235], v[70:73]
	v_mfma_f32_16x16x32_bf16 v[66:69], v[138:141], v[232:235], v[66:69]
	v_mfma_f32_16x16x32_bf16 v[94:97], v[134:137], v[200:203], v[94:97]
	v_mfma_f32_16x16x32_bf16 v[90:93], v[142:145], v[200:203], v[90:93]
	v_mfma_f32_16x16x32_bf16 v[86:89], v[134:137], v[208:211], v[86:89]
	v_mfma_f32_16x16x32_bf16 v[82:85], v[142:145], v[208:211], v[82:85]
	v_mfma_f32_16x16x32_bf16 v[78:81], v[134:137], v[216:219], v[78:81]
	v_mfma_f32_16x16x32_bf16 v[74:77], v[142:145], v[216:219], v[74:77]
	v_mfma_f32_16x16x32_bf16 v[70:73], v[134:137], v[248:251], v[70:73]
	v_mfma_f32_16x16x32_bf16 v[66:69], v[142:145], v[248:251], v[66:69]
	v_mfma_f32_16x16x32_bf16 v[30:33], v[146:149], v[176:179], v[30:33]
	v_mfma_f32_16x16x32_bf16 v[26:29], v[168:171], v[176:179], v[26:29]
	v_mfma_f32_16x16x32_bf16 v[22:25], v[146:149], v[204:207], v[22:25]
	v_mfma_f32_16x16x32_bf16 v[18:21], v[168:171], v[204:207], v[18:21]
	v_mfma_f32_16x16x32_bf16 v[14:17], v[146:149], v[212:215], v[14:17]
	v_mfma_f32_16x16x32_bf16 v[10:13], v[168:171], v[212:215], v[10:13]
	v_mfma_f32_16x16x32_bf16 v[6:9], v[146:149], v[232:235], v[6:9]
	v_mfma_f32_16x16x32_bf16 v[2:5], v[168:171], v[232:235], v[2:5]
	v_mfma_f32_16x16x32_bf16 v[30:33], v[164:167], v[200:203], v[30:33]
	v_mfma_f32_16x16x32_bf16 v[26:29], v[172:175], v[200:203], v[26:29]
	v_mfma_f32_16x16x32_bf16 v[22:25], v[164:167], v[208:211], v[22:25]
	v_mfma_f32_16x16x32_bf16 v[18:21], v[172:175], v[208:211], v[18:21]
	v_mfma_f32_16x16x32_bf16 v[14:17], v[164:167], v[216:219], v[14:17]
	v_mfma_f32_16x16x32_bf16 v[10:13], v[172:175], v[216:219], v[10:13]
	v_mfma_f32_16x16x32_bf16 v[6:9], v[164:167], v[248:251], v[6:9]
	v_mfma_f32_16x16x32_bf16 v[2:5], v[172:175], v[248:251], v[2:5]
	s_barrier
	s_setprio 0
	s_add_u32 s40, s40, 0x100
	s_addc_u32 s41, s41, 0
	s_cmp_ge_i32 s68, s46
	s_cbranch_scc0 .LBB0_284

; #define PG8_STAGE(bufoff, gbase, voff) do { _Pragma("unroll") for (int _i = 0; _i < 2; ++_i) \
;         __builtin_amdgcn_global_load_lds((const unsigned*)((const char*)(gbase) + (voff)[_i]), (LAS unsigned*)(lds + (bufoff) + ldsw + _i * 8192), 16, 0, 0); } while (0)
; #define PG8_LDA(dst, b, h) do { _Pragma("unroll") for (int m = 0; m < 4; ++m) _Pragma("unroll") for (int k = 0; k < 2; ++k) dst[m][k] = *(const LAS bf16x8*)(lds + PG8_SA(b, h) + aoff + m * 2048 + k * 1024); } while (0)
; #define PG8_LDB(dst, b, h) do { _Pragma("unroll") for (int n = 0; n < 2; ++n) _Pragma("unroll") for (int k = 0; k < 2; ++k) dst[n][k] = *(const LAS bf16x8*)(lds + PG8_SB(b, h) + boff + n * 2048 + k * 1024); } while (0)
; #define PG8_MMA(ai, bj, At, Bt) do { __builtin_amdgcn_s_setprio(1); _Pragma("unroll") for (int m = 0; m < 4; ++m) _Pragma("unroll") for (int n = 0; n < 2; ++n) _Pragma("unroll") for (int k = 0; k < 2; ++k) \
;         acc[ai][bj][m][n] = __builtin_amdgcn_mfma_f32_16x16x32_bf16(Bt[n][k], At[m][k], acc[ai][bj][m][n], 0, 0, 0); __builtin_amdgcn_s_setprio(0); } while (0)
; #define PG8_WAIT_V(n) asm volatile("s_waitcnt vmcnt(" #n ")" ::: "memory")
; template <class Epi, class Sched>
; __device__ __forceinline__ void gemm_phase(LAS unsigned char* lds, const Gemm g, const Sched& S, const Epi& E) {
;     ...
;         for (int t = 0; t < nt; t += 2) {
;             if constexpr (Epi::HOOKS) { if (cur.kind == 3 && (t == 4 || t == 12)) { int fr_ = fr, fq_ = fq; asm volatile("" : "+v"(fr_), "+v"(fq_)); E.hook(acc, cur, t == 4 ? 0 : 1, wr, wc, fr_, fq_); } }
;             const bool last = (t == nt - 2);
;             const char* a1 = cA + (size_t)(t + 1) * kstep;
;             const char* a2 = last ? nA : cA + (size_t)(t + 2) * kstep; const char* b2 = last ? nB : cB + (size_t)(t + 2) * kstep;
;             const char* a3 = a2 + kstep; const char* b3 = b2 + kstep;
;             PG8_LDB(B0, 0, 0); PG8_LDB(B1, 0, 1); PG8_SCHED; PG8_LDA(At, 0, 0); PG8_STAGE(PG8_SA(1, 1), a1 + hstepA, voffA);
;             PG8_WAIT_V(8); PG8_WAIT_L(0); PG8_BAR; PG8_MMA(0, 0, At, B0); PG8_MMA(0, 1, At, B1); PG8_BAR; PG8_SCHED;
;             PG8_LDA(At, 0, 1); PG8_STAGE(PG8_SB(0, 0), b2, voffB); PG8_STAGE(PG8_SB(0, 1), b2 + hstepB, voffB); PG8_STAGE(PG8_SA(0, 0), a2, voffA);
;             PG8_WAIT_V(8); PG8_WAIT_L(0); PG8_BAR; PG8_MMA(1, 0, At, B0); PG8_MMA(1, 1, At, B1); PG8_BAR; PG8_SCHED;
.LBB0_375:
	s_add_i32 s63, s40, 2
	s_add_u32 s0, s20, 0x100
	s_addc_u32 s1, s21, 0
	s_add_i32 s72, 0, 0x10000
	s_cmp_eq_u32 s77, s40
	s_cselect_b32 s43, s91, s1
	s_cselect_b32 s42, s90, s0
	v_add_u32_e32 v0, s72, v178
	s_cselect_b32 s41, s93, s62
	s_cselect_b32 s40, s92, s68
	s_add_i32 s76, 0, 0x14000
	ds_read_b128 v[142:145], v0
	ds_read_b128 v[146:149], v0 offset:1024
	ds_read_b128 v[150:153], v0 offset:2048
	ds_read_b128 v[154:157], v0 offset:3072
	v_add_u32_e32 v0, s76, v178
	ds_read_b128 v[158:161], v0
	ds_read_b128 v[162:165], v0 offset:1024
	ds_read_b128 v[166:169], v0 offset:2048
	ds_read_b128 v[170:173], v0 offset:3072
	v_lshl_add_u64 v[174:175], s[20:21], 0, v[140:141]
	s_add_i32 m0, s17, 0xc000
	ds_read_b128 v[180:183], v179
	ds_read_b128 v[196:199], v179 offset:1024
	ds_read_b128 v[200:203], v179 offset:2048
	ds_read_b128 v[204:207], v179 offset:3072
	ds_read_b128 v[208:211], v179 offset:4096
	ds_read_b128 v[212:215], v179 offset:5120
	ds_read_b128 v[216:219], v179 offset:6144
	ds_read_b128 v[248:251], v179 offset:7168
	global_load_lds_dwordx4 v[174:175], off
	v_lshl_add_u64 v[174:175], s[20:21], 0, v[138:139]
	s_add_i32 m0, s17, 0xe000
	s_nop 0
	global_load_lds_dwordx4 v[174:175], off
	s_waitcnt vmcnt(8)
	s_waitcnt lgkmcnt(0)
	s_setprio 1
	s_barrier
	v_mfma_f32_16x16x32_bf16 v[126:129], v[142:145], v[180:183], v[126:129]
	v_mfma_f32_16x16x32_bf16 v[122:125], v[150:153], v[180:183], v[122:125]
	v_mfma_f32_16x16x32_bf16 v[118:121], v[142:145], v[200:203], v[118:121]
	v_mfma_f32_16x16x32_bf16 v[114:117], v[150:153], v[200:203], v[114:117]
	v_mfma_f32_16x16x32_bf16 v[110:113], v[142:145], v[208:211], v[110:113]
	v_mfma_f32_16x16x32_bf16 v[106:109], v[150:153], v[208:211], v[106:109]
	v_mfma_f32_16x16x32_bf16 v[102:105], v[142:145], v[216:219], v[102:105]
	v_mfma_f32_16x16x32_bf16 v[98:101], v[150:153], v[216:219], v[98:101]
	v_mfma_f32_16x16x32_bf16 v[126:129], v[146:149], v[196:199], v[126:129]
	v_mfma_f32_16x16x32_bf16 v[122:125], v[154:157], v[196:199], v[122:125]
	v_mfma_f32_16x16x32_bf16 v[118:121], v[146:149], v[204:207], v[118:121]
	v_mfma_f32_16x16x32_bf16 v[114:117], v[154:157], v[204:207], v[114:117]
	v_mfma_f32_16x16x32_bf16 v[110:113], v[146:149], v[212:215], v[110:113]
	v_mfma_f32_16x16x32_bf16 v[106:109], v[154:157], v[212:215], v[106:109]
	v_mfma_f32_16x16x32_bf16 v[102:105], v[146:149], v[248:251], v[102:105]
	v_mfma_f32_16x16x32_bf16 v[98:101], v[154:157], v[248:251], v[98:101]
	v_mfma_f32_16x16x32_bf16 v[62:65], v[158:161], v[180:183], v[62:65]
	v_mfma_f32_16x16x32_bf16 v[58:61], v[166:169], v[180:183], v[58:61]
	v_mfma_f32_16x16x32_bf16 v[54:57], v[158:161], v[200:203], v[54:57]
	v_mfma_f32_16x16x32_bf16 v[50:53], v[166:169], v[200:203], v[50:53]
	v_mfma_f32_16x16x32_bf16 v[46:49], v[158:161], v[208:211], v[46:49]
	v_mfma_f32_16x16x32_bf16 v[42:45], v[166:169], v[208:211], v[42:45]
	v_mfma_f32_16x16x32_bf16 v[38:41], v[158:161], v[216:219], v[38:41]
	v_mfma_f32_16x16x32_bf16 v[34:37], v[166:169], v[216:219], v[34:37]
	v_mfma_f32_16x16x32_bf16 v[62:65], v[162:165], v[196:199], v[62:65]
	v_mfma_f32_16x16x32_bf16 v[58:61], v[170:173], v[196:199], v[58:61]
	v_mfma_f32_16x16x32_bf16 v[54:57], v[162:165], v[204:207], v[54:57]
	v_mfma_f32_16x16x32_bf16 v[50:53], v[170:173], v[204:207], v[50:53]
	v_mfma_f32_16x16x32_bf16 v[46:49], v[162:165], v[212:215], v[46:49]
	v_mfma_f32_16x16x32_bf16 v[42:45], v[170:173], v[212:215], v[42:45]
	v_mfma_f32_16x16x32_bf16 v[38:41], v[162:165], v[248:251], v[38:41]
	v_mfma_f32_16x16x32_bf16 v[34:37], v[170:173], v[248:251], v[34:37]
	s_barrier
	s_setprio 0
	s_add_i32 s20, s72, s16
	v_lshl_add_u64 v[174:175], s[40:41], 0, v[132:133]
	s_mov_b32 m0, s20
	ds_read_b128 v[180:183], v179 offset:16384
	ds_read_b128 v[196:199], v179 offset:17408
	ds_read_b128 v[200:203], v179 offset:18432
	ds_read_b128 v[204:207], v179 offset:19456
	ds_read_b128 v[208:211], v179 offset:20480
	ds_read_b128 v[212:215], v179 offset:21504
	ds_read_b128 v[216:219], v179 offset:22528
	ds_read_b128 v[248:251], v179 offset:23552
	global_load_lds_dwordx4 v[174:175], off
	s_add_i32 m0, s20, 0x2000
	s_add_u32 s20, s40, 0x18000
	v_lshl_add_u64 v[184:185], s[40:41], 0, v[136:137]
	s_addc_u32 s21, s41, 0
	s_add_i32 s72, s76, s16
	global_load_lds_dwordx4 v[184:185], off
	v_lshl_add_u64 v[220:221], s[20:21], 0, v[132:133]
	s_mov_b32 m0, s72
	v_lshl_add_u64 v[232:233], s[42:43], 0, v[134:135]
	global_load_lds_dwordx4 v[220:221], off
	v_lshl_add_u64 v[220:221], s[20:21], 0, v[136:137]
	s_add_i32 m0, s72, 0x2000
	s_nop 0
	global_load_lds_dwordx4 v[220:221], off
	v_lshl_add_u64 v[220:221], s[42:43], 0, v[130:131]
	s_mov_b32 m0, s17
	s_nop 0
	global_load_lds_dwordx4 v[220:221], off
	s_mov_b32 m0, s44
	s_nop 0
	global_load_lds_dwordx4 v[232:233], off
	s_waitcnt vmcnt(8)
	s_waitcnt lgkmcnt(0)
	s_setprio 1
	s_barrier
; #define PG8_STAGE(bufoff, gbase, voff) do { _Pragma("unroll") for (int _i = 0; _i < 2; ++_i) \
;         __builtin_amdgcn_global_load_lds((const unsigned*)((const char*)(gbase) + (voff)[_i]), (LAS unsigned*)(lds + (bufoff) + ldsw + _i * 8192), 16, 0, 0); } while (0)
; #define PG8_LDA(dst, b, h) do { _Pragma("unroll") for (int m = 0; m < 4; ++m) _Pragma("unroll") for (int k = 0; k < 2; ++k) dst[m][k] = *(const LAS bf16x8*)(lds + PG8_SA(b, h) + aoff + m * 2048 + k * 1024); } while (0)
; #define PG8_LDB(dst, b, h) do { _Pragma("unroll") for (int n = 0; n < 2; ++n) _Pragma("unroll") for (int k = 0; k < 2; ++k) dst[n][k] = *(const LAS bf16x8*)(lds + PG8_SB(b, h) + boff + n * 2048 + k * 1024); } while (0)
; #define PG8_MMA(ai, bj, At, Bt) do { __builtin_amdgcn_s_setprio(1); _Pragma("unroll") for (int m = 0; m < 4; ++m) _Pragma("unroll") for (int n = 0; n < 2; ++n) _Pragma("unroll") for (int k = 0; k < 2; ++k) \
;         acc[ai][bj][m][n] = __builtin_amdgcn_mfma_f32_16x16x32_bf16(Bt[n][k], At[m][k], acc[ai][bj][m][n], 0, 0, 0); __builtin_amdgcn_s_setprio(0); } while (0)
; #define PG8_WAIT_V(n) asm volatile("s_waitcnt vmcnt(" #n ")" ::: "memory")
; #define PG8_WAIT_L(n) asm volatile("s_waitcnt lgkmcnt(" #n ")" ::: "memory")
; #define PG8_BAR __builtin_amdgcn_s_barrier()
; #define PG8_SCHED __builtin_amdgcn_sched_barrier(0)
; template <class Epi, class Sched>
; __device__ __forceinline__ void gemm_phase(LAS unsigned char* lds, const Gemm g, const Sched& S, const Epi& E) {
;     ...
;             PG8_WAIT_V(8); PG8_WAIT_L(0); PG8_BAR; PG8_MMA(1, 0, At, B0); PG8_MMA(1, 1, At, B1); PG8_BAR; PG8_SCHED;
;             PG8_LDB(B0, 1, 0); PG8_LDB(B1, 1, 1); PG8_SCHED; PG8_LDA(At, 1, 0); PG8_STAGE(PG8_SA(0, 1), a2 + hstepA, voffA);
;             PG8_WAIT_V(8); PG8_WAIT_L(0); PG8_BAR; PG8_MMA(0, 0, At, B0); PG8_MMA(0, 1, At, B1); PG8_BAR; PG8_SCHED;
	v_mfma_f32_16x16x32_bf16 v[94:97], v[142:145], v[180:183], v[94:97]
	v_mfma_f32_16x16x32_bf16 v[90:93], v[150:153], v[180:183], v[90:93]
	v_mfma_f32_16x16x32_bf16 v[86:89], v[142:145], v[200:203], v[86:89]
	v_mfma_f32_16x16x32_bf16 v[82:85], v[150:153], v[200:203], v[82:85]
	v_mfma_f32_16x16x32_bf16 v[78:81], v[142:145], v[208:211], v[78:81]
	v_mfma_f32_16x16x32_bf16 v[74:77], v[150:153], v[208:211], v[74:77]
	v_mfma_f32_16x16x32_bf16 v[70:73], v[142:145], v[216:219], v[70:73]
	v_mfma_f32_16x16x32_bf16 v[66:69], v[150:153], v[216:219], v[66:69]
	v_mfma_f32_16x16x32_bf16 v[94:97], v[146:149], v[196:199], v[94:97]
	v_mfma_f32_16x16x32_bf16 v[90:93], v[154:157], v[196:199], v[90:93]
	v_mfma_f32_16x16x32_bf16 v[86:89], v[146:149], v[204:207], v[86:89]
	v_mfma_f32_16x16x32_bf16 v[82:85], v[154:157], v[204:207], v[82:85]
	v_mfma_f32_16x16x32_bf16 v[78:81], v[146:149], v[212:215], v[78:81]
	v_mfma_f32_16x16x32_bf16 v[74:77], v[154:157], v[212:215], v[74:77]
	v_mfma_f32_16x16x32_bf16 v[70:73], v[146:149], v[248:251], v[70:73]
	v_mfma_f32_16x16x32_bf16 v[66:69], v[154:157], v[248:251], v[66:69]
	v_mfma_f32_16x16x32_bf16 v[30:33], v[158:161], v[180:183], v[30:33]
	v_mfma_f32_16x16x32_bf16 v[26:29], v[166:169], v[180:183], v[26:29]
	v_mfma_f32_16x16x32_bf16 v[22:25], v[158:161], v[200:203], v[22:25]
	v_mfma_f32_16x16x32_bf16 v[18:21], v[166:169], v[200:203], v[18:21]
	v_mfma_f32_16x16x32_bf16 v[14:17], v[158:161], v[208:211], v[14:17]
	v_mfma_f32_16x16x32_bf16 v[10:13], v[166:169], v[208:211], v[10:13]
	v_mfma_f32_16x16x32_bf16 v[6:9], v[158:161], v[216:219], v[6:9]
	v_mfma_f32_16x16x32_bf16 v[2:5], v[166:169], v[216:219], v[2:5]
	v_mfma_f32_16x16x32_bf16 v[30:33], v[162:165], v[196:199], v[30:33]
	v_mfma_f32_16x16x32_bf16 v[26:29], v[170:173], v[196:199], v[26:29]
	v_mfma_f32_16x16x32_bf16 v[22:25], v[162:165], v[204:207], v[22:25]
	v_mfma_f32_16x16x32_bf16 v[18:21], v[170:173], v[204:207], v[18:21]
	v_mfma_f32_16x16x32_bf16 v[14:17], v[162:165], v[212:215], v[14:17]
	v_mfma_f32_16x16x32_bf16 v[10:13], v[170:173], v[212:215], v[10:13]
	v_mfma_f32_16x16x32_bf16 v[6:9], v[162:165], v[248:251], v[6:9]
	v_mfma_f32_16x16x32_bf16 v[2:5], v[170:173], v[248:251], v[2:5]
	s_barrier
	s_setprio 0
	s_add_i32 s72, 0, 0x18000
	v_add_u32_e32 v0, s72, v178
	s_add_i32 s76, 0, 0x1c000
	ds_read_b128 v[142:145], v0
	ds_read_b128 v[146:149], v0 offset:1024
	ds_read_b128 v[150:153], v0 offset:2048
	ds_read_b128 v[154:157], v0 offset:3072
	v_add_u32_e32 v0, s76, v178
	ds_read_b128 v[158:161], v0
	ds_read_b128 v[162:165], v0 offset:1024
	ds_read_b128 v[166:169], v0 offset:2048
	ds_read_b128 v[170:173], v0 offset:3072
	s_add_u32 s20, s42, 0x50000
	s_addc_u32 s21, s43, 0
	s_mov_b32 m0, s45
	v_lshl_add_u64 v[234:235], s[20:21], 0, v[130:131]
	ds_read_b128 v[180:183], v179 offset:32768
	ds_read_b128 v[196:199], v179 offset:33792
	ds_read_b128 v[200:203], v179 offset:34816
	ds_read_b128 v[204:207], v179 offset:35840
	ds_read_b128 v[208:211], v179 offset:36864
	ds_read_b128 v[212:215], v179 offset:37888
	ds_read_b128 v[216:219], v179 offset:38912
	ds_read_b128 v[248:251], v179 offset:39936
	global_load_lds_dwordx4 v[234:235], off
	v_lshl_add_u64 v[234:235], s[20:21], 0, v[134:135]
	s_mov_b32 m0, s46
	s_nop 0
	global_load_lds_dwordx4 v[234:235], off
	s_waitcnt vmcnt(8)
	s_waitcnt lgkmcnt(0)
	s_setprio 1
	s_barrier
	v_mfma_f32_16x16x32_bf16 v[126:129], v[142:145], v[180:183], v[126:129]
	v_mfma_f32_16x16x32_bf16 v[122:125], v[150:153], v[180:183], v[122:125]
	v_mfma_f32_16x16x32_bf16 v[118:121], v[142:145], v[200:203], v[118:121]
	v_mfma_f32_16x16x32_bf16 v[114:117], v[150:153], v[200:203], v[114:117]
	v_mfma_f32_16x16x32_bf16 v[110:113], v[142:145], v[208:211], v[110:113]
	v_mfma_f32_16x16x32_bf16 v[106:109], v[150:153], v[208:211], v[106:109]
	v_mfma_f32_16x16x32_bf16 v[102:105], v[142:145], v[216:219], v[102:105]
	v_mfma_f32_16x16x32_bf16 v[98:101], v[150:153], v[216:219], v[98:101]
	v_mfma_f32_16x16x32_bf16 v[126:129], v[146:149], v[196:199], v[126:129]
	v_mfma_f32_16x16x32_bf16 v[122:125], v[154:157], v[196:199], v[122:125]
	v_mfma_f32_16x16x32_bf16 v[118:121], v[146:149], v[204:207], v[118:121]
	v_mfma_f32_16x16x32_bf16 v[114:117], v[154:157], v[204:207], v[114:117]
	v_mfma_f32_16x16x32_bf16 v[110:113], v[146:149], v[212:215], v[110:113]
	v_mfma_f32_16x16x32_bf16 v[106:109], v[154:157], v[212:215], v[106:109]
	v_mfma_f32_16x16x32_bf16 v[102:105], v[146:149], v[248:251], v[102:105]
	v_mfma_f32_16x16x32_bf16 v[98:101], v[154:157], v[248:251], v[98:101]
	v_mfma_f32_16x16x32_bf16 v[62:65], v[158:161], v[180:183], v[62:65]
	v_mfma_f32_16x16x32_bf16 v[58:61], v[166:169], v[180:183], v[58:61]
	v_mfma_f32_16x16x32_bf16 v[54:57], v[158:161], v[200:203], v[54:57]
	v_mfma_f32_16x16x32_bf16 v[50:53], v[166:169], v[200:203], v[50:53]
	v_mfma_f32_16x16x32_bf16 v[46:49], v[158:161], v[208:211], v[46:49]
	v_mfma_f32_16x16x32_bf16 v[42:45], v[166:169], v[208:211], v[42:45]
	v_mfma_f32_16x16x32_bf16 v[38:41], v[158:161], v[216:219], v[38:41]
	v_mfma_f32_16x16x32_bf16 v[34:37], v[166:169], v[216:219], v[34:37]
	v_mfma_f32_16x16x32_bf16 v[62:65], v[162:165], v[196:199], v[62:65]
	v_mfma_f32_16x16x32_bf16 v[58:61], v[170:173], v[196:199], v[58:61]
	v_mfma_f32_16x16x32_bf16 v[54:57], v[162:165], v[204:207], v[54:57]
	v_mfma_f32_16x16x32_bf16 v[50:53], v[170:173], v[204:207], v[50:53]
	v_mfma_f32_16x16x32_bf16 v[46:49], v[162:165], v[212:215], v[46:49]
	v_mfma_f32_16x16x32_bf16 v[42:45], v[170:173], v[212:215], v[42:45]
	v_mfma_f32_16x16x32_bf16 v[38:41], v[162:165], v[248:251], v[38:41]
	v_mfma_f32_16x16x32_bf16 v[34:37], v[170:173], v[248:251], v[34:37]
	s_barrier
; #define PG8_STAGE(bufoff, gbase, voff) do { _Pragma("unroll") for (int _i = 0; _i < 2; ++_i) \
;         __builtin_amdgcn_global_load_lds((const unsigned*)((const char*)(gbase) + (voff)[_i]), (LAS unsigned*)(lds + (bufoff) + ldsw + _i * 8192), 16, 0, 0); } while (0)
; #define PG8_LDA(dst, b, h) do { _Pragma("unroll") for (int m = 0; m < 4; ++m) _Pragma("unroll") for (int k = 0; k < 2; ++k) dst[m][k] = *(const LAS bf16x8*)(lds + PG8_SA(b, h) + aoff + m * 2048 + k * 1024); } while (0)
; #define PG8_MMA(ai, bj, At, Bt) do { __builtin_amdgcn_s_setprio(1); _Pragma("unroll") for (int m = 0; m < 4; ++m) _Pragma("unroll") for (int n = 0; n < 2; ++n) _Pragma("unroll") for (int k = 0; k < 2; ++k) \
;         acc[ai][bj][m][n] = __builtin_amdgcn_mfma_f32_16x16x32_bf16(Bt[n][k], At[m][k], acc[ai][bj][m][n], 0, 0, 0); __builtin_amdgcn_s_setprio(0); } while (0)
; #define PG8_WAIT_V(n) asm volatile("s_waitcnt vmcnt(" #n ")" ::: "memory")
; #define PG8_WAIT_L(n) asm volatile("s_waitcnt lgkmcnt(" #n ")" ::: "memory")
; #define PG8_BAR __builtin_amdgcn_s_barrier()
; #define PG8_SCHED __builtin_amdgcn_sched_barrier(0)
; template <class Epi, class Sched>
; __device__ __forceinline__ void gemm_phase(LAS unsigned char* lds, const Gemm g, const Sched& S, const Epi& E) {
;     ...
;             PG8_LDA(At, 1, 1); PG8_STAGE(PG8_SB(1, 0), b3, voffB); PG8_STAGE(PG8_SB(1, 1), b3 + hstepB, voffB); PG8_STAGE(PG8_SA(1, 0), a3, voffA);
;             PG8_WAIT_V(8); PG8_WAIT_L(0); PG8_BAR; PG8_MMA(1, 0, At, B0); PG8_MMA(1, 1, At, B1); PG8_BAR; PG8_SCHED;
;         }
	s_setprio 0
	s_add_i32 s20, s72, s16
	v_lshl_add_u64 v[174:175], v[174:175], 0, s[26:27]
	s_mov_b32 m0, s20
	ds_read_b128 v[180:183], v179 offset:49152
	ds_read_b128 v[196:199], v179 offset:50176
	ds_read_b128 v[200:203], v179 offset:51200
	ds_read_b128 v[204:207], v179 offset:52224
	ds_read_b128 v[208:211], v179 offset:53248
	ds_read_b128 v[212:215], v179 offset:54272
	ds_read_b128 v[216:219], v179 offset:55296
	ds_read_b128 v[248:251], v179 offset:56320
	global_load_lds_dwordx4 v[174:175], off
	s_add_i32 m0, s20, 0x2000
	s_add_u32 s20, s40, 0x18080
	v_lshl_add_u64 v[174:175], v[184:185], 0, s[26:27]
	s_addc_u32 s21, s41, 0
	s_add_i32 s40, s76, s16
	global_load_lds_dwordx4 v[174:175], off
	v_lshl_add_u64 v[174:175], s[20:21], 0, v[132:133]
	s_mov_b32 m0, s40
	s_nop 0
	global_load_lds_dwordx4 v[174:175], off
	v_lshl_add_u64 v[174:175], s[20:21], 0, v[136:137]
	s_add_i32 m0, s40, 0x2000
	s_nop 0
	global_load_lds_dwordx4 v[174:175], off
	v_lshl_add_u64 v[174:175], v[220:221], 0, s[26:27]
	s_mov_b32 m0, s71
	s_nop 0
	global_load_lds_dwordx4 v[174:175], off
	v_lshl_add_u64 v[174:175], v[232:233], 0, s[26:27]
	s_mov_b32 m0, s74
	s_nop 0
	global_load_lds_dwordx4 v[174:175], off
	s_waitcnt vmcnt(8)
	s_waitcnt lgkmcnt(0)
	s_setprio 1
	s_barrier
	v_mfma_f32_16x16x32_bf16 v[94:97], v[142:145], v[180:183], v[94:97]
	v_mfma_f32_16x16x32_bf16 v[90:93], v[150:153], v[180:183], v[90:93]
	v_mfma_f32_16x16x32_bf16 v[86:89], v[142:145], v[200:203], v[86:89]
	v_mfma_f32_16x16x32_bf16 v[82:85], v[150:153], v[200:203], v[82:85]
	v_mfma_f32_16x16x32_bf16 v[78:81], v[142:145], v[208:211], v[78:81]
	v_mfma_f32_16x16x32_bf16 v[74:77], v[150:153], v[208:211], v[74:77]
	v_mfma_f32_16x16x32_bf16 v[70:73], v[142:145], v[216:219], v[70:73]
	v_mfma_f32_16x16x32_bf16 v[66:69], v[150:153], v[216:219], v[66:69]
	v_mfma_f32_16x16x32_bf16 v[94:97], v[146:149], v[196:199], v[94:97]
	v_mfma_f32_16x16x32_bf16 v[90:93], v[154:157], v[196:199], v[90:93]
	v_mfma_f32_16x16x32_bf16 v[86:89], v[146:149], v[204:207], v[86:89]
	v_mfma_f32_16x16x32_bf16 v[82:85], v[154:157], v[204:207], v[82:85]
	v_mfma_f32_16x16x32_bf16 v[78:81], v[146:149], v[212:215], v[78:81]
	v_mfma_f32_16x16x32_bf16 v[74:77], v[154:157], v[212:215], v[74:77]
	v_mfma_f32_16x16x32_bf16 v[70:73], v[146:149], v[248:251], v[70:73]
	v_mfma_f32_16x16x32_bf16 v[66:69], v[154:157], v[248:251], v[66:69]
	v_mfma_f32_16x16x32_bf16 v[30:33], v[158:161], v[180:183], v[30:33]
	v_mfma_f32_16x16x32_bf16 v[26:29], v[166:169], v[180:183], v[26:29]
	v_mfma_f32_16x16x32_bf16 v[22:25], v[158:161], v[200:203], v[22:25]
	v_mfma_f32_16x16x32_bf16 v[18:21], v[166:169], v[200:203], v[18:21]
	v_mfma_f32_16x16x32_bf16 v[14:17], v[158:161], v[208:211], v[14:17]
	v_mfma_f32_16x16x32_bf16 v[10:13], v[166:169], v[208:211], v[10:13]
	v_mfma_f32_16x16x32_bf16 v[6:9], v[158:161], v[216:219], v[6:9]
	v_mfma_f32_16x16x32_bf16 v[2:5], v[166:169], v[216:219], v[2:5]
	v_mfma_f32_16x16x32_bf16 v[30:33], v[162:165], v[196:199], v[30:33]
	v_mfma_f32_16x16x32_bf16 v[26:29], v[170:173], v[196:199], v[26:29]
	v_mfma_f32_16x16x32_bf16 v[22:25], v[162:165], v[204:207], v[22:25]
	v_mfma_f32_16x16x32_bf16 v[18:21], v[170:173], v[204:207], v[18:21]
	v_mfma_f32_16x16x32_bf16 v[14:17], v[162:165], v[212:215], v[14:17]
	v_mfma_f32_16x16x32_bf16 v[10:13], v[170:173], v[212:215], v[10:13]
	v_mfma_f32_16x16x32_bf16 v[6:9], v[162:165], v[248:251], v[6:9]
	v_mfma_f32_16x16x32_bf16 v[2:5], v[170:173], v[248:251], v[2:5]
	s_barrier
	s_setprio 0
	s_add_u32 s68, s68, 0x100
	s_addc_u32 s62, s62, 0
	s_cmp_ge_i32 s63, s48
	s_mov_b64 s[20:21], s[0:1]
	s_mov_b32 s40, s63
	s_cbranch_scc0 .LBB0_375

; #define PG8_STAGE(bufoff, gbase, voff) do { _Pragma("unroll") for (int _i = 0; _i < 2; ++_i) \
;         __builtin_amdgcn_global_load_lds((const unsigned*)((const char*)(gbase) + (voff)[_i]), (LAS unsigned*)(lds + (bufoff) + ldsw + _i * 8192), 16, 0, 0); } while (0)
; #define PG8_LDA(dst, b, h) do { _Pragma("unroll") for (int m = 0; m < 4; ++m) _Pragma("unroll") for (int k = 0; k < 2; ++k) dst[m][k] = *(const LAS bf16x8*)(lds + PG8_SA(b, h) + aoff + m * 2048 + k * 1024); } while (0)
; #define PG8_LDB(dst, b, h) do { _Pragma("unroll") for (int n = 0; n < 2; ++n) _Pragma("unroll") for (int k = 0; k < 2; ++k) dst[n][k] = *(const LAS bf16x8*)(lds + PG8_SB(b, h) + boff + n * 2048 + k * 1024); } while (0)
; #define PG8_MMA(ai, bj, At, Bt) do { __builtin_amdgcn_s_setprio(1); _Pragma("unroll") for (int m = 0; m < 4; ++m) _Pragma("unroll") for (int n = 0; n < 2; ++n) _Pragma("unroll") for (int k = 0; k < 2; ++k) \
;         acc[ai][bj][m][n] = __builtin_amdgcn_mfma_f32_16x16x32_bf16(Bt[n][k], At[m][k], acc[ai][bj][m][n], 0, 0, 0); __builtin_amdgcn_s_setprio(0); } while (0)
; #define PG8_WAIT_V(n) asm volatile("s_waitcnt vmcnt(" #n ")" ::: "memory")
; template <class Epi, class Sched>
; __device__ __forceinline__ void gemm_phase(LAS unsigned char* lds, const Gemm g, const Sched& S, const Epi& E) {
;     ...
;         for (int t = 0; t < nt; t += 2) {
;             if constexpr (Epi::HOOKS) { if (cur.kind == 3 && (t == 4 || t == 12)) { int fr_ = fr, fq_ = fq; asm volatile("" : "+v"(fr_), "+v"(fq_)); E.hook(acc, cur, t == 4 ? 0 : 1, wr, wc, fr_, fq_); } }
;             const bool last = (t == nt - 2);
;             const char* a1 = cA + (size_t)(t + 1) * kstep;
;             const char* a2 = last ? nA : cA + (size_t)(t + 2) * kstep; const char* b2 = last ? nB : cB + (size_t)(t + 2) * kstep;
;             const char* a3 = a2 + kstep; const char* b3 = b2 + kstep;
;             PG8_LDB(B0, 0, 0); PG8_LDB(B1, 0, 1); PG8_SCHED; PG8_LDA(At, 0, 0); PG8_STAGE(PG8_SA(1, 1), a1 + hstepA, voffA);
;             PG8_WAIT_V(8); PG8_WAIT_L(0); PG8_BAR; PG8_MMA(0, 0, At, B0); PG8_MMA(0, 1, At, B1); PG8_BAR; PG8_SCHED;
;             PG8_LDA(At, 0, 1); PG8_STAGE(PG8_SB(0, 0), b2, voffB); PG8_STAGE(PG8_SB(0, 1), b2 + hstepB, voffB); PG8_STAGE(PG8_SA(0, 0), a2, voffA);
;             PG8_WAIT_V(8); PG8_WAIT_L(0); PG8_BAR; PG8_MMA(1, 0, At, B0); PG8_MMA(1, 1, At, B1); PG8_BAR; PG8_SCHED;
.LBB0_499:
	s_add_i32 s76, s94, 2
	s_add_u32 s40, s92, 0x100
	s_addc_u32 s41, s93, 0
	s_add_i32 s52, 0, 0x10000
	s_cmp_eq_u32 s71, s94
	s_cselect_b32 vcc_hi, s21, s41
	s_cselect_b32 vcc_lo, s20, s40
	v_add_u32_e32 v0, s52, v169
	s_cselect_b32 s95, s91, s63
	s_cselect_b32 s94, s68, s62
	s_add_i32 s53, 0, 0x14000
	ds_read_b128 v[130:133], v0
	ds_read_b128 v[134:137], v0 offset:1024
	ds_read_b128 v[150:153], v0 offset:2048
	ds_read_b128 v[154:157], v0 offset:3072
	v_add_u32_e32 v0, s53, v169
	ds_read_b128 v[158:161], v0
	ds_read_b128 v[174:177], v0 offset:1024
	ds_read_b128 v[178:181], v0 offset:2048
	ds_read_b128 v[182:185], v0 offset:3072
	v_lshl_add_u64 v[164:165], s[92:93], 0, v[148:149]
	s_add_i32 m0, s19, 0xc000
	ds_read_b128 v[196:199], v173
	ds_read_b128 v[200:203], v173 offset:1024
	ds_read_b128 v[204:207], v173 offset:2048
	ds_read_b128 v[208:211], v173 offset:3072
	ds_read_b128 v[212:215], v173 offset:4096
	ds_read_b128 v[216:219], v173 offset:5120
	ds_read_b128 v[248:251], v173 offset:6144
	ds_read_b128 v[232:235], v173 offset:7168
	global_load_lds_dwordx4 v[164:165], off
	v_lshl_add_u64 v[164:165], s[92:93], 0, v[146:147]
	s_add_i32 m0, s19, 0xe000
	s_nop 0
	global_load_lds_dwordx4 v[164:165], off
	s_waitcnt vmcnt(8)
	s_waitcnt lgkmcnt(0)
	s_setprio 1
	s_barrier
	v_mfma_f32_16x16x32_bf16 v[126:129], v[130:133], v[196:199], v[126:129]
	v_mfma_f32_16x16x32_bf16 v[122:125], v[150:153], v[196:199], v[122:125]
	v_mfma_f32_16x16x32_bf16 v[110:113], v[130:133], v[204:207], v[110:113]
	v_mfma_f32_16x16x32_bf16 v[106:109], v[150:153], v[204:207], v[106:109]
	v_mfma_f32_16x16x32_bf16 v[94:97], v[130:133], v[212:215], v[94:97]
	v_mfma_f32_16x16x32_bf16 v[90:93], v[150:153], v[212:215], v[90:93]
	v_mfma_f32_16x16x32_bf16 v[78:81], v[130:133], v[248:251], v[78:81]
	v_mfma_f32_16x16x32_bf16 v[74:77], v[150:153], v[248:251], v[74:77]
	v_mfma_f32_16x16x32_bf16 v[126:129], v[134:137], v[200:203], v[126:129]
	v_mfma_f32_16x16x32_bf16 v[122:125], v[154:157], v[200:203], v[122:125]
	v_mfma_f32_16x16x32_bf16 v[110:113], v[134:137], v[208:211], v[110:113]
	v_mfma_f32_16x16x32_bf16 v[106:109], v[154:157], v[208:211], v[106:109]
	v_mfma_f32_16x16x32_bf16 v[94:97], v[134:137], v[216:219], v[94:97]
	v_mfma_f32_16x16x32_bf16 v[90:93], v[154:157], v[216:219], v[90:93]
	v_mfma_f32_16x16x32_bf16 v[78:81], v[134:137], v[232:235], v[78:81]
	v_mfma_f32_16x16x32_bf16 v[74:77], v[154:157], v[232:235], v[74:77]
	v_mfma_f32_16x16x32_bf16 v[118:121], v[158:161], v[196:199], v[118:121]
	v_mfma_f32_16x16x32_bf16 v[114:117], v[178:181], v[196:199], v[114:117]
	v_mfma_f32_16x16x32_bf16 v[102:105], v[158:161], v[204:207], v[102:105]
	v_mfma_f32_16x16x32_bf16 v[98:101], v[178:181], v[204:207], v[98:101]
	v_mfma_f32_16x16x32_bf16 v[86:89], v[158:161], v[212:215], v[86:89]
	v_mfma_f32_16x16x32_bf16 v[82:85], v[178:181], v[212:215], v[82:85]
	v_mfma_f32_16x16x32_bf16 v[70:73], v[158:161], v[248:251], v[70:73]
	v_mfma_f32_16x16x32_bf16 v[66:69], v[178:181], v[248:251], v[66:69]
	v_mfma_f32_16x16x32_bf16 v[118:121], v[174:177], v[200:203], v[118:121]
	v_mfma_f32_16x16x32_bf16 v[114:117], v[182:185], v[200:203], v[114:117]
	v_mfma_f32_16x16x32_bf16 v[102:105], v[174:177], v[208:211], v[102:105]
	v_mfma_f32_16x16x32_bf16 v[98:101], v[182:185], v[208:211], v[98:101]
	v_mfma_f32_16x16x32_bf16 v[86:89], v[174:177], v[216:219], v[86:89]
	v_mfma_f32_16x16x32_bf16 v[82:85], v[182:185], v[216:219], v[82:85]
	v_mfma_f32_16x16x32_bf16 v[70:73], v[174:177], v[232:235], v[70:73]
	v_mfma_f32_16x16x32_bf16 v[66:69], v[182:185], v[232:235], v[66:69]
	s_barrier
	s_setprio 0
	s_add_i32 s52, s52, s17
	v_lshl_add_u64 v[164:165], s[94:95], 0, v[140:141]
	s_mov_b32 m0, s52
	ds_read_b128 v[196:199], v173 offset:16384
	ds_read_b128 v[200:203], v173 offset:17408
	ds_read_b128 v[204:207], v173 offset:18432
	ds_read_b128 v[208:211], v173 offset:19456
	ds_read_b128 v[212:215], v173 offset:20480
	ds_read_b128 v[216:219], v173 offset:21504
	ds_read_b128 v[232:235], v173 offset:22528
	ds_read_b128 v[248:251], v173 offset:23552
	global_load_lds_dwordx4 v[164:165], off
	s_add_i32 m0, s52, 0x2000
	s_add_u32 s92, s94, 0x10000
	v_lshl_add_u64 v[170:171], s[94:95], 0, v[144:145]
	s_addc_u32 s93, s95, 0
	s_add_i32 s52, s53, s17
	global_load_lds_dwordx4 v[170:171], off
	v_lshl_add_u64 v[220:221], s[92:93], 0, v[140:141]
	s_mov_b32 m0, s52
	v_lshl_add_u64 v[246:247], vcc, 0, v[142:143]
	global_load_lds_dwordx4 v[220:221], off
	v_lshl_add_u64 v[220:221], s[92:93], 0, v[144:145]
	s_add_i32 m0, s52, 0x2000
	s_nop 0
	global_load_lds_dwordx4 v[220:221], off
	v_lshl_add_u64 v[220:221], vcc, 0, v[138:139]
	s_mov_b32 m0, s19
	s_nop 0
	global_load_lds_dwordx4 v[220:221], off
	s_mov_b32 m0, s44
	s_nop 0
	global_load_lds_dwordx4 v[246:247], off
	s_waitcnt vmcnt(8)
	s_waitcnt lgkmcnt(0)
	s_setprio 1
	s_barrier
; #define PG8_STAGE(bufoff, gbase, voff) do { _Pragma("unroll") for (int _i = 0; _i < 2; ++_i) \
;         __builtin_amdgcn_global_load_lds((const unsigned*)((const char*)(gbase) + (voff)[_i]), (LAS unsigned*)(lds + (bufoff) + ldsw + _i * 8192), 16, 0, 0); } while (0)
; #define PG8_LDA(dst, b, h) do { _Pragma("unroll") for (int m = 0; m < 4; ++m) _Pragma("unroll") for (int k = 0; k < 2; ++k) dst[m][k] = *(const LAS bf16x8*)(lds + PG8_SA(b, h) + aoff + m * 2048 + k * 1024); } while (0)
; #define PG8_LDB(dst, b, h) do { _Pragma("unroll") for (int n = 0; n < 2; ++n) _Pragma("unroll") for (int k = 0; k < 2; ++k) dst[n][k] = *(const LAS bf16x8*)(lds + PG8_SB(b, h) + boff + n * 2048 + k * 1024); } while (0)
; #define PG8_MMA(ai, bj, At, Bt) do { __builtin_amdgcn_s_setprio(1); _Pragma("unroll") for (int m = 0; m < 4; ++m) _Pragma("unroll") for (int n = 0; n < 2; ++n) _Pragma("unroll") for (int k = 0; k < 2; ++k) \
;         acc[ai][bj][m][n] = __builtin_amdgcn_mfma_f32_16x16x32_bf16(Bt[n][k], At[m][k], acc[ai][bj][m][n], 0, 0, 0); __builtin_amdgcn_s_setprio(0); } while (0)
; #define PG8_WAIT_V(n) asm volatile("s_waitcnt vmcnt(" #n ")" ::: "memory")
; #define PG8_WAIT_L(n) asm volatile("s_waitcnt lgkmcnt(" #n ")" ::: "memory")
; #define PG8_BAR __builtin_amdgcn_s_barrier()
; #define PG8_SCHED __builtin_amdgcn_sched_barrier(0)
; template <class Epi, class Sched>
; __device__ __forceinline__ void gemm_phase(LAS unsigned char* lds, const Gemm g, const Sched& S, const Epi& E) {
;     ...
;             PG8_WAIT_V(8); PG8_WAIT_L(0); PG8_BAR; PG8_MMA(1, 0, At, B0); PG8_MMA(1, 1, At, B1); PG8_BAR; PG8_SCHED;
;             PG8_LDB(B0, 1, 0); PG8_LDB(B1, 1, 1); PG8_SCHED; PG8_LDA(At, 1, 0); PG8_STAGE(PG8_SA(0, 1), a2 + hstepA, voffA);
;             PG8_WAIT_V(8); PG8_WAIT_L(0); PG8_BAR; PG8_MMA(0, 0, At, B0); PG8_MMA(0, 1, At, B1); PG8_BAR; PG8_SCHED;
	v_mfma_f32_16x16x32_bf16 v[62:65], v[130:133], v[196:199], v[62:65]
	v_mfma_f32_16x16x32_bf16 v[58:61], v[150:153], v[196:199], v[58:61]
	v_mfma_f32_16x16x32_bf16 v[46:49], v[130:133], v[204:207], v[46:49]
	v_mfma_f32_16x16x32_bf16 v[42:45], v[150:153], v[204:207], v[42:45]
	v_mfma_f32_16x16x32_bf16 v[30:33], v[130:133], v[212:215], v[30:33]
	v_mfma_f32_16x16x32_bf16 v[26:29], v[150:153], v[212:215], v[26:29]
	v_mfma_f32_16x16x32_bf16 v[14:17], v[130:133], v[232:235], v[14:17]
	v_mfma_f32_16x16x32_bf16 v[10:13], v[150:153], v[232:235], v[10:13]
	v_mfma_f32_16x16x32_bf16 v[62:65], v[134:137], v[200:203], v[62:65]
	v_mfma_f32_16x16x32_bf16 v[58:61], v[154:157], v[200:203], v[58:61]
	v_mfma_f32_16x16x32_bf16 v[46:49], v[134:137], v[208:211], v[46:49]
	v_mfma_f32_16x16x32_bf16 v[42:45], v[154:157], v[208:211], v[42:45]
	v_mfma_f32_16x16x32_bf16 v[30:33], v[134:137], v[216:219], v[30:33]
	v_mfma_f32_16x16x32_bf16 v[26:29], v[154:157], v[216:219], v[26:29]
	v_mfma_f32_16x16x32_bf16 v[14:17], v[134:137], v[248:251], v[14:17]
	v_mfma_f32_16x16x32_bf16 v[10:13], v[154:157], v[248:251], v[10:13]
	v_mfma_f32_16x16x32_bf16 v[54:57], v[158:161], v[196:199], v[54:57]
	v_mfma_f32_16x16x32_bf16 v[50:53], v[178:181], v[196:199], v[50:53]
	v_mfma_f32_16x16x32_bf16 v[38:41], v[158:161], v[204:207], v[38:41]
	v_mfma_f32_16x16x32_bf16 v[34:37], v[178:181], v[204:207], v[34:37]
	v_mfma_f32_16x16x32_bf16 v[22:25], v[158:161], v[212:215], v[22:25]
	v_mfma_f32_16x16x32_bf16 v[18:21], v[178:181], v[212:215], v[18:21]
	v_mfma_f32_16x16x32_bf16 v[6:9], v[158:161], v[232:235], v[6:9]
	v_mfma_f32_16x16x32_bf16 v[2:5], v[178:181], v[232:235], v[2:5]
	v_mfma_f32_16x16x32_bf16 v[54:57], v[174:177], v[200:203], v[54:57]
	v_mfma_f32_16x16x32_bf16 v[50:53], v[182:185], v[200:203], v[50:53]
	v_mfma_f32_16x16x32_bf16 v[38:41], v[174:177], v[208:211], v[38:41]
	v_mfma_f32_16x16x32_bf16 v[34:37], v[182:185], v[208:211], v[34:37]
	v_mfma_f32_16x16x32_bf16 v[22:25], v[174:177], v[216:219], v[22:25]
	v_mfma_f32_16x16x32_bf16 v[18:21], v[182:185], v[216:219], v[18:21]
	v_mfma_f32_16x16x32_bf16 v[6:9], v[174:177], v[248:251], v[6:9]
	v_mfma_f32_16x16x32_bf16 v[2:5], v[182:185], v[248:251], v[2:5]
	s_barrier
	s_setprio 0
	s_add_i32 s52, 0, 0x18000
	v_add_u32_e32 v0, s52, v169
	s_add_i32 s53, 0, 0x1c000
	ds_read_b128 v[130:133], v0
	ds_read_b128 v[134:137], v0 offset:1024
	ds_read_b128 v[150:153], v0 offset:2048
	ds_read_b128 v[154:157], v0 offset:3072
	v_add_u32_e32 v0, s53, v169
	ds_read_b128 v[158:161], v0
	ds_read_b128 v[174:177], v0 offset:1024
	ds_read_b128 v[178:181], v0 offset:2048
	ds_read_b128 v[182:185], v0 offset:3072
	s_add_u32 s92, vcc_lo, 0x50000
	s_addc_u32 s93, vcc_hi, 0
	s_mov_b32 m0, s45
	v_lshl_add_u64 v[236:237], s[92:93], 0, v[138:139]
	ds_read_b128 v[196:199], v173 offset:32768
	ds_read_b128 v[200:203], v173 offset:33792
	ds_read_b128 v[204:207], v173 offset:34816
	ds_read_b128 v[208:211], v173 offset:35840
	ds_read_b128 v[212:215], v173 offset:36864
	ds_read_b128 v[216:219], v173 offset:37888
	ds_read_b128 v[232:235], v173 offset:38912
	ds_read_b128 v[248:251], v173 offset:39936
	global_load_lds_dwordx4 v[236:237], off
	v_lshl_add_u64 v[236:237], s[92:93], 0, v[142:143]
	s_mov_b32 m0, s46
	s_nop 0
	global_load_lds_dwordx4 v[236:237], off
	s_waitcnt vmcnt(8)
	s_waitcnt lgkmcnt(0)
	s_setprio 1
	s_barrier
	v_mfma_f32_16x16x32_bf16 v[126:129], v[130:133], v[196:199], v[126:129]
	v_mfma_f32_16x16x32_bf16 v[122:125], v[150:153], v[196:199], v[122:125]
	v_mfma_f32_16x16x32_bf16 v[110:113], v[130:133], v[204:207], v[110:113]
	v_mfma_f32_16x16x32_bf16 v[106:109], v[150:153], v[204:207], v[106:109]
	v_mfma_f32_16x16x32_bf16 v[94:97], v[130:133], v[212:215], v[94:97]
	v_mfma_f32_16x16x32_bf16 v[90:93], v[150:153], v[212:215], v[90:93]
	v_mfma_f32_16x16x32_bf16 v[78:81], v[130:133], v[232:235], v[78:81]
	v_mfma_f32_16x16x32_bf16 v[74:77], v[150:153], v[232:235], v[74:77]
	v_mfma_f32_16x16x32_bf16 v[126:129], v[134:137], v[200:203], v[126:129]
	v_mfma_f32_16x16x32_bf16 v[122:125], v[154:157], v[200:203], v[122:125]
	v_mfma_f32_16x16x32_bf16 v[110:113], v[134:137], v[208:211], v[110:113]
	v_mfma_f32_16x16x32_bf16 v[106:109], v[154:157], v[208:211], v[106:109]
	v_mfma_f32_16x16x32_bf16 v[94:97], v[134:137], v[216:219], v[94:97]
	v_mfma_f32_16x16x32_bf16 v[90:93], v[154:157], v[216:219], v[90:93]
	v_mfma_f32_16x16x32_bf16 v[78:81], v[134:137], v[248:251], v[78:81]
	v_mfma_f32_16x16x32_bf16 v[74:77], v[154:157], v[248:251], v[74:77]
	v_mfma_f32_16x16x32_bf16 v[118:121], v[158:161], v[196:199], v[118:121]
	v_mfma_f32_16x16x32_bf16 v[114:117], v[178:181], v[196:199], v[114:117]
	v_mfma_f32_16x16x32_bf16 v[102:105], v[158:161], v[204:207], v[102:105]
	v_mfma_f32_16x16x32_bf16 v[98:101], v[178:181], v[204:207], v[98:101]
	v_mfma_f32_16x16x32_bf16 v[86:89], v[158:161], v[212:215], v[86:89]
	v_mfma_f32_16x16x32_bf16 v[82:85], v[178:181], v[212:215], v[82:85]
	v_mfma_f32_16x16x32_bf16 v[70:73], v[158:161], v[232:235], v[70:73]
	v_mfma_f32_16x16x32_bf16 v[66:69], v[178:181], v[232:235], v[66:69]
	v_mfma_f32_16x16x32_bf16 v[118:121], v[174:177], v[200:203], v[118:121]
	v_mfma_f32_16x16x32_bf16 v[114:117], v[182:185], v[200:203], v[114:117]
	v_mfma_f32_16x16x32_bf16 v[102:105], v[174:177], v[208:211], v[102:105]
	v_mfma_f32_16x16x32_bf16 v[98:101], v[182:185], v[208:211], v[98:101]
	v_mfma_f32_16x16x32_bf16 v[86:89], v[174:177], v[216:219], v[86:89]
	v_mfma_f32_16x16x32_bf16 v[82:85], v[182:185], v[216:219], v[82:85]
	v_mfma_f32_16x16x32_bf16 v[70:73], v[174:177], v[248:251], v[70:73]
	v_mfma_f32_16x16x32_bf16 v[66:69], v[182:185], v[248:251], v[66:69]
	s_barrier
; #define PG8_STAGE(bufoff, gbase, voff) do { _Pragma("unroll") for (int _i = 0; _i < 2; ++_i) \
;         __builtin_amdgcn_global_load_lds((const unsigned*)((const char*)(gbase) + (voff)[_i]), (LAS unsigned*)(lds + (bufoff) + ldsw + _i * 8192), 16, 0, 0); } while (0)
; #define PG8_LDA(dst, b, h) do { _Pragma("unroll") for (int m = 0; m < 4; ++m) _Pragma("unroll") for (int k = 0; k < 2; ++k) dst[m][k] = *(const LAS bf16x8*)(lds + PG8_SA(b, h) + aoff + m * 2048 + k * 1024); } while (0)
; #define PG8_MMA(ai, bj, At, Bt) do { __builtin_amdgcn_s_setprio(1); _Pragma("unroll") for (int m = 0; m < 4; ++m) _Pragma("unroll") for (int n = 0; n < 2; ++n) _Pragma("unroll") for (int k = 0; k < 2; ++k) \
;         acc[ai][bj][m][n] = __builtin_amdgcn_mfma_f32_16x16x32_bf16(Bt[n][k], At[m][k], acc[ai][bj][m][n], 0, 0, 0); __builtin_amdgcn_s_setprio(0); } while (0)
; #define PG8_WAIT_V(n) asm volatile("s_waitcnt vmcnt(" #n ")" ::: "memory")
; #define PG8_WAIT_L(n) asm volatile("s_waitcnt lgkmcnt(" #n ")" ::: "memory")
; #define PG8_BAR __builtin_amdgcn_s_barrier()
; #define PG8_SCHED __builtin_amdgcn_sched_barrier(0)
; template <class Epi, class Sched>
; __device__ __forceinline__ void gemm_phase(LAS unsigned char* lds, const Gemm g, const Sched& S, const Epi& E) {
;     ...
;             PG8_LDA(At, 1, 1); PG8_STAGE(PG8_SB(1, 0), b3, voffB); PG8_STAGE(PG8_SB(1, 1), b3 + hstepB, voffB); PG8_STAGE(PG8_SA(1, 0), a3, voffA);
;             PG8_WAIT_V(8); PG8_WAIT_L(0); PG8_BAR; PG8_MMA(1, 0, At, B0); PG8_MMA(1, 1, At, B1); PG8_BAR; PG8_SCHED;
;         }
	s_setprio 0
	s_add_i32 s52, s52, s17
	v_lshl_add_u64 v[164:165], v[164:165], 0, s[26:27]
	s_mov_b32 m0, s52
	ds_read_b128 v[196:199], v173 offset:49152
	ds_read_b128 v[200:203], v173 offset:50176
	ds_read_b128 v[204:207], v173 offset:51200
	ds_read_b128 v[208:211], v173 offset:52224
	ds_read_b128 v[212:215], v173 offset:53248
	ds_read_b128 v[216:219], v173 offset:54272
	ds_read_b128 v[232:235], v173 offset:55296
	ds_read_b128 v[248:251], v173 offset:56320
	global_load_lds_dwordx4 v[164:165], off
	s_add_i32 m0, s52, 0x2000
	s_add_u32 s92, s94, 0x10080
	v_lshl_add_u64 v[164:165], v[170:171], 0, s[26:27]
	s_addc_u32 s93, s95, 0
	s_add_i32 s52, s53, s17
	global_load_lds_dwordx4 v[164:165], off
	v_lshl_add_u64 v[164:165], s[92:93], 0, v[140:141]
	s_mov_b32 m0, s52
	s_nop 0
	global_load_lds_dwordx4 v[164:165], off
	v_lshl_add_u64 v[164:165], s[92:93], 0, v[144:145]
	s_add_i32 m0, s52, 0x2000
	s_nop 0
	global_load_lds_dwordx4 v[164:165], off
	v_lshl_add_u64 v[164:165], v[220:221], 0, s[26:27]
	s_mov_b32 m0, s67
	s_nop 0
	global_load_lds_dwordx4 v[164:165], off
	v_lshl_add_u64 v[164:165], v[246:247], 0, s[26:27]
	s_mov_b32 m0, s69
	s_nop 0
	global_load_lds_dwordx4 v[164:165], off
	s_waitcnt vmcnt(8)
	s_waitcnt lgkmcnt(0)
	s_setprio 1
	s_barrier
	v_mfma_f32_16x16x32_bf16 v[62:65], v[130:133], v[196:199], v[62:65]
	v_mfma_f32_16x16x32_bf16 v[58:61], v[150:153], v[196:199], v[58:61]
	v_mfma_f32_16x16x32_bf16 v[46:49], v[130:133], v[204:207], v[46:49]
	v_mfma_f32_16x16x32_bf16 v[42:45], v[150:153], v[204:207], v[42:45]
	v_mfma_f32_16x16x32_bf16 v[30:33], v[130:133], v[212:215], v[30:33]
	v_mfma_f32_16x16x32_bf16 v[26:29], v[150:153], v[212:215], v[26:29]
	v_mfma_f32_16x16x32_bf16 v[14:17], v[130:133], v[232:235], v[14:17]
	v_mfma_f32_16x16x32_bf16 v[10:13], v[150:153], v[232:235], v[10:13]
	v_mfma_f32_16x16x32_bf16 v[62:65], v[134:137], v[200:203], v[62:65]
	v_mfma_f32_16x16x32_bf16 v[58:61], v[154:157], v[200:203], v[58:61]
	v_mfma_f32_16x16x32_bf16 v[46:49], v[134:137], v[208:211], v[46:49]
	v_mfma_f32_16x16x32_bf16 v[42:45], v[154:157], v[208:211], v[42:45]
	v_mfma_f32_16x16x32_bf16 v[30:33], v[134:137], v[216:219], v[30:33]
	v_mfma_f32_16x16x32_bf16 v[26:29], v[154:157], v[216:219], v[26:29]
	v_mfma_f32_16x16x32_bf16 v[14:17], v[134:137], v[248:251], v[14:17]
	v_mfma_f32_16x16x32_bf16 v[10:13], v[154:157], v[248:251], v[10:13]
	v_mfma_f32_16x16x32_bf16 v[54:57], v[158:161], v[196:199], v[54:57]
	v_mfma_f32_16x16x32_bf16 v[50:53], v[178:181], v[196:199], v[50:53]
	v_mfma_f32_16x16x32_bf16 v[38:41], v[158:161], v[204:207], v[38:41]
	v_mfma_f32_16x16x32_bf16 v[34:37], v[178:181], v[204:207], v[34:37]
	v_mfma_f32_16x16x32_bf16 v[22:25], v[158:161], v[212:215], v[22:25]
	v_mfma_f32_16x16x32_bf16 v[18:21], v[178:181], v[212:215], v[18:21]
	v_mfma_f32_16x16x32_bf16 v[6:9], v[158:161], v[232:235], v[6:9]
	v_mfma_f32_16x16x32_bf16 v[2:5], v[178:181], v[232:235], v[2:5]
	v_mfma_f32_16x16x32_bf16 v[54:57], v[174:177], v[200:203], v[54:57]
	v_mfma_f32_16x16x32_bf16 v[50:53], v[182:185], v[200:203], v[50:53]
	v_mfma_f32_16x16x32_bf16 v[38:41], v[174:177], v[208:211], v[38:41]
	v_mfma_f32_16x16x32_bf16 v[34:37], v[182:185], v[208:211], v[34:37]
	v_mfma_f32_16x16x32_bf16 v[22:25], v[174:177], v[216:219], v[22:25]
	v_mfma_f32_16x16x32_bf16 v[18:21], v[182:185], v[216:219], v[18:21]
	v_mfma_f32_16x16x32_bf16 v[6:9], v[174:177], v[248:251], v[6:9]
	v_mfma_f32_16x16x32_bf16 v[2:5], v[182:185], v[248:251], v[2:5]
	s_barrier
	s_setprio 0
	s_add_u32 s62, s62, 0x100
	s_addc_u32 s63, s63, 0
	s_cmp_ge_i32 s76, s47
	s_mov_b64 s[92:93], s[40:41]
	s_mov_b32 s94, s76
	s_cbranch_scc0 .LBB0_499

; #define PG8_STAGE(bufoff, gbase, voff) do { _Pragma("unroll") for (int _i = 0; _i < 2; ++_i) \
;         __builtin_amdgcn_global_load_lds((const unsigned*)((const char*)(gbase) + (voff)[_i]), (LAS unsigned*)(lds + (bufoff) + ldsw + _i * 8192), 16, 0, 0); } while (0)
; #define PG8_LDA(dst, b, h) do { _Pragma("unroll") for (int m = 0; m < 4; ++m) _Pragma("unroll") for (int k = 0; k < 2; ++k) dst[m][k] = *(const LAS bf16x8*)(lds + PG8_SA(b, h) + aoff + m * 2048 + k * 1024); } while (0)
; #define PG8_LDB(dst, b, h) do { _Pragma("unroll") for (int n = 0; n < 2; ++n) _Pragma("unroll") for (int k = 0; k < 2; ++k) dst[n][k] = *(const LAS bf16x8*)(lds + PG8_SB(b, h) + boff + n * 2048 + k * 1024); } while (0)
; #define PG8_MMA(ai, bj, At, Bt) do { __builtin_amdgcn_s_setprio(1); _Pragma("unroll") for (int m = 0; m < 4; ++m) _Pragma("unroll") for (int n = 0; n < 2; ++n) _Pragma("unroll") for (int k = 0; k < 2; ++k) \
;         acc[ai][bj][m][n] = __builtin_amdgcn_mfma_f32_16x16x32_bf16(Bt[n][k], At[m][k], acc[ai][bj][m][n], 0, 0, 0); __builtin_amdgcn_s_setprio(0); } while (0)
; #define PG8_WAIT_V(n) asm volatile("s_waitcnt vmcnt(" #n ")" ::: "memory")
; template <class Epi, class Sched>
; __device__ __forceinline__ void gemm_phase(LAS unsigned char* lds, const Gemm g, const Sched& S, const Epi& E) {
;     ...
;         for (int t = 0; t < nt; t += 2) {
;             if constexpr (Epi::HOOKS) { if (cur.kind == 3 && (t == 4 || t == 12)) { int fr_ = fr, fq_ = fq; asm volatile("" : "+v"(fr_), "+v"(fq_)); E.hook(acc, cur, t == 4 ? 0 : 1, wr, wc, fr_, fq_); } }
;             const bool last = (t == nt - 2);
;             const char* a1 = cA + (size_t)(t + 1) * kstep;
;             const char* a2 = last ? nA : cA + (size_t)(t + 2) * kstep; const char* b2 = last ? nB : cB + (size_t)(t + 2) * kstep;
;             const char* a3 = a2 + kstep; const char* b3 = b2 + kstep;
;             PG8_LDB(B0, 0, 0); PG8_LDB(B1, 0, 1); PG8_SCHED; PG8_LDA(At, 0, 0); PG8_STAGE(PG8_SA(1, 1), a1 + hstepA, voffA);
;             PG8_WAIT_V(8); PG8_WAIT_L(0); PG8_BAR; PG8_MMA(0, 0, At, B0); PG8_MMA(0, 1, At, B1); PG8_BAR; PG8_SCHED;
;             PG8_LDA(At, 0, 1); PG8_STAGE(PG8_SB(0, 0), b2, voffB); PG8_STAGE(PG8_SB(0, 1), b2 + hstepB, voffB); PG8_STAGE(PG8_SA(0, 0), a2, voffA);
;             PG8_WAIT_V(8); PG8_WAIT_L(0); PG8_BAR; PG8_MMA(1, 0, At, B0); PG8_MMA(1, 1, At, B1); PG8_BAR; PG8_SCHED;
.LBB0_526:
	s_add_i32 s62, s0, 2
	s_add_u32 s1, s20, 0xffff0080
	s_addc_u32 s38, s21, -1
	s_add_i32 s39, 0, 0x10000
	s_cmp_eq_u32 s71, s0
	s_cselect_b32 s43, s61, s38
	s_cselect_b32 s42, s96, s1
	v_add_u32_e32 v0, s39, v201
	s_cselect_b32 s1, s91, vcc_lo
	s_cselect_b32 s0, s90, s97
	s_add_i32 s52, 0, 0x14000
	ds_read_b128 v[130:133], v0
	ds_read_b128 v[134:137], v0 offset:1024
	ds_read_b128 v[138:141], v0 offset:2048
	ds_read_b128 v[142:145], v0 offset:3072
	v_add_u32_e32 v0, s52, v201
	ds_read_b128 v[146:149], v0
	ds_read_b128 v[150:153], v0 offset:1024
	ds_read_b128 v[154:157], v0 offset:2048
	ds_read_b128 v[158:161], v0 offset:3072
	v_lshl_add_u64 v[220:221], s[20:21], 0, v[176:177]
	s_add_i32 m0, s19, 0xc000
	ds_read_b128 v[162:165], v202
	ds_read_b128 v[178:181], v202 offset:1024
	ds_read_b128 v[182:185], v202 offset:2048
	ds_read_b128 v[196:199], v202 offset:3072
	ds_read_b128 v[204:207], v202 offset:4096
	ds_read_b128 v[208:211], v202 offset:5120
	ds_read_b128 v[212:215], v202 offset:6144
	ds_read_b128 v[216:219], v202 offset:7168
	global_load_lds_dwordx4 v[220:221], off
	v_lshl_add_u64 v[220:221], s[20:21], 0, v[174:175]
	s_add_i32 m0, s19, 0xe000
	s_nop 0
	global_load_lds_dwordx4 v[220:221], off
	s_waitcnt vmcnt(8)
	s_waitcnt lgkmcnt(0)
	s_setprio 1
	s_barrier
	v_mfma_f32_16x16x32_bf16 v[126:129], v[130:133], v[162:165], v[126:129]
	v_mfma_f32_16x16x32_bf16 v[122:125], v[138:141], v[162:165], v[122:125]
	v_mfma_f32_16x16x32_bf16 v[110:113], v[130:133], v[182:185], v[110:113]
	v_mfma_f32_16x16x32_bf16 v[106:109], v[138:141], v[182:185], v[106:109]
	v_mfma_f32_16x16x32_bf16 v[94:97], v[130:133], v[204:207], v[94:97]
	v_mfma_f32_16x16x32_bf16 v[90:93], v[138:141], v[204:207], v[90:93]
	v_mfma_f32_16x16x32_bf16 v[78:81], v[130:133], v[212:215], v[78:81]
	v_mfma_f32_16x16x32_bf16 v[74:77], v[138:141], v[212:215], v[74:77]
	v_mfma_f32_16x16x32_bf16 v[126:129], v[134:137], v[178:181], v[126:129]
	v_mfma_f32_16x16x32_bf16 v[122:125], v[142:145], v[178:181], v[122:125]
	v_mfma_f32_16x16x32_bf16 v[110:113], v[134:137], v[196:199], v[110:113]
	v_mfma_f32_16x16x32_bf16 v[106:109], v[142:145], v[196:199], v[106:109]
	v_mfma_f32_16x16x32_bf16 v[94:97], v[134:137], v[208:211], v[94:97]
	v_mfma_f32_16x16x32_bf16 v[90:93], v[142:145], v[208:211], v[90:93]
	v_mfma_f32_16x16x32_bf16 v[78:81], v[134:137], v[216:219], v[78:81]
	v_mfma_f32_16x16x32_bf16 v[74:77], v[142:145], v[216:219], v[74:77]
	v_mfma_f32_16x16x32_bf16 v[118:121], v[146:149], v[162:165], v[118:121]
	v_mfma_f32_16x16x32_bf16 v[114:117], v[154:157], v[162:165], v[114:117]
	v_mfma_f32_16x16x32_bf16 v[102:105], v[146:149], v[182:185], v[102:105]
	v_mfma_f32_16x16x32_bf16 v[98:101], v[154:157], v[182:185], v[98:101]
	v_mfma_f32_16x16x32_bf16 v[86:89], v[146:149], v[204:207], v[86:89]
	v_mfma_f32_16x16x32_bf16 v[82:85], v[154:157], v[204:207], v[82:85]
	v_mfma_f32_16x16x32_bf16 v[70:73], v[146:149], v[212:215], v[70:73]
	v_mfma_f32_16x16x32_bf16 v[66:69], v[154:157], v[212:215], v[66:69]
	v_mfma_f32_16x16x32_bf16 v[118:121], v[150:153], v[178:181], v[118:121]
	v_mfma_f32_16x16x32_bf16 v[114:117], v[158:161], v[178:181], v[114:117]
	v_mfma_f32_16x16x32_bf16 v[102:105], v[150:153], v[196:199], v[102:105]
	v_mfma_f32_16x16x32_bf16 v[98:101], v[158:161], v[196:199], v[98:101]
	v_mfma_f32_16x16x32_bf16 v[86:89], v[150:153], v[208:211], v[86:89]
	v_mfma_f32_16x16x32_bf16 v[82:85], v[158:161], v[208:211], v[82:85]
	v_mfma_f32_16x16x32_bf16 v[70:73], v[150:153], v[216:219], v[70:73]
	v_mfma_f32_16x16x32_bf16 v[66:69], v[158:161], v[216:219], v[66:69]
	s_barrier
	s_setprio 0
	s_add_i32 s38, s39, s17
	v_lshl_add_u64 v[220:221], s[0:1], 0, v[168:169]
	s_mov_b32 m0, s38
	ds_read_b128 v[162:165], v202 offset:16384
	ds_read_b128 v[178:181], v202 offset:17408
	ds_read_b128 v[182:185], v202 offset:18432
	ds_read_b128 v[196:199], v202 offset:19456
	ds_read_b128 v[204:207], v202 offset:20480
	ds_read_b128 v[208:211], v202 offset:21504
	ds_read_b128 v[212:215], v202 offset:22528
	ds_read_b128 v[216:219], v202 offset:23552
	global_load_lds_dwordx4 v[220:221], off
	s_add_i32 m0, s38, 0x2000
	s_add_u32 s38, s0, 0x50000
	v_lshl_add_u64 v[232:233], s[0:1], 0, v[172:173]
	s_addc_u32 s39, s1, 0
	s_add_i32 s52, s52, s17
	global_load_lds_dwordx4 v[232:233], off
	v_lshl_add_u64 v[234:235], s[38:39], 0, v[168:169]
	s_mov_b32 m0, s52
	v_lshl_add_u64 v[236:237], s[42:43], 0, v[170:171]
	global_load_lds_dwordx4 v[234:235], off
	v_lshl_add_u64 v[234:235], s[38:39], 0, v[172:173]
	s_add_i32 m0, s52, 0x2000
	s_nop 0
	global_load_lds_dwordx4 v[234:235], off
	v_lshl_add_u64 v[234:235], s[42:43], 0, v[166:167]
	s_mov_b32 m0, s19
	s_nop 0
	global_load_lds_dwordx4 v[234:235], off
	s_mov_b32 m0, s44
	s_nop 0
	global_load_lds_dwordx4 v[236:237], off
	s_waitcnt vmcnt(8)
	s_waitcnt lgkmcnt(0)
	s_setprio 1
	s_barrier
; #define PG8_STAGE(bufoff, gbase, voff) do { _Pragma("unroll") for (int _i = 0; _i < 2; ++_i) \
;         __builtin_amdgcn_global_load_lds((const unsigned*)((const char*)(gbase) + (voff)[_i]), (LAS unsigned*)(lds + (bufoff) + ldsw + _i * 8192), 16, 0, 0); } while (0)
; #define PG8_LDA(dst, b, h) do { _Pragma("unroll") for (int m = 0; m < 4; ++m) _Pragma("unroll") for (int k = 0; k < 2; ++k) dst[m][k] = *(const LAS bf16x8*)(lds + PG8_SA(b, h) + aoff + m * 2048 + k * 1024); } while (0)
; #define PG8_LDB(dst, b, h) do { _Pragma("unroll") for (int n = 0; n < 2; ++n) _Pragma("unroll") for (int k = 0; k < 2; ++k) dst[n][k] = *(const LAS bf16x8*)(lds + PG8_SB(b, h) + boff + n * 2048 + k * 1024); } while (0)
; #define PG8_MMA(ai, bj, At, Bt) do { __builtin_amdgcn_s_setprio(1); _Pragma("unroll") for (int m = 0; m < 4; ++m) _Pragma("unroll") for (int n = 0; n < 2; ++n) _Pragma("unroll") for (int k = 0; k < 2; ++k) \
;         acc[ai][bj][m][n] = __builtin_amdgcn_mfma_f32_16x16x32_bf16(Bt[n][k], At[m][k], acc[ai][bj][m][n], 0, 0, 0); __builtin_amdgcn_s_setprio(0); } while (0)
; #define PG8_WAIT_V(n) asm volatile("s_waitcnt vmcnt(" #n ")" ::: "memory")
; #define PG8_WAIT_L(n) asm volatile("s_waitcnt lgkmcnt(" #n ")" ::: "memory")
; #define PG8_BAR __builtin_amdgcn_s_barrier()
; #define PG8_SCHED __builtin_amdgcn_sched_barrier(0)
; template <class Epi, class Sched>
; __device__ __forceinline__ void gemm_phase(LAS unsigned char* lds, const Gemm g, const Sched& S, const Epi& E) {
;     ...
;             PG8_WAIT_V(8); PG8_WAIT_L(0); PG8_BAR; PG8_MMA(1, 0, At, B0); PG8_MMA(1, 1, At, B1); PG8_BAR; PG8_SCHED;
;             PG8_LDB(B0, 1, 0); PG8_LDB(B1, 1, 1); PG8_SCHED; PG8_LDA(At, 1, 0); PG8_STAGE(PG8_SA(0, 1), a2 + hstepA, voffA);
;             PG8_WAIT_V(8); PG8_WAIT_L(0); PG8_BAR; PG8_MMA(0, 0, At, B0); PG8_MMA(0, 1, At, B1); PG8_BAR; PG8_SCHED;
	v_mfma_f32_16x16x32_bf16 v[62:65], v[130:133], v[162:165], v[62:65]
	v_mfma_f32_16x16x32_bf16 v[58:61], v[138:141], v[162:165], v[58:61]
	v_mfma_f32_16x16x32_bf16 v[46:49], v[130:133], v[182:185], v[46:49]
	v_mfma_f32_16x16x32_bf16 v[42:45], v[138:141], v[182:185], v[42:45]
	v_mfma_f32_16x16x32_bf16 v[30:33], v[130:133], v[204:207], v[30:33]
	v_mfma_f32_16x16x32_bf16 v[26:29], v[138:141], v[204:207], v[26:29]
	v_mfma_f32_16x16x32_bf16 v[14:17], v[130:133], v[212:215], v[14:17]
	v_mfma_f32_16x16x32_bf16 v[10:13], v[138:141], v[212:215], v[10:13]
	v_mfma_f32_16x16x32_bf16 v[62:65], v[134:137], v[178:181], v[62:65]
	v_mfma_f32_16x16x32_bf16 v[58:61], v[142:145], v[178:181], v[58:61]
	v_mfma_f32_16x16x32_bf16 v[46:49], v[134:137], v[196:199], v[46:49]
	v_mfma_f32_16x16x32_bf16 v[42:45], v[142:145], v[196:199], v[42:45]
	v_mfma_f32_16x16x32_bf16 v[30:33], v[134:137], v[208:211], v[30:33]
	v_mfma_f32_16x16x32_bf16 v[26:29], v[142:145], v[208:211], v[26:29]
	v_mfma_f32_16x16x32_bf16 v[14:17], v[134:137], v[216:219], v[14:17]
	v_mfma_f32_16x16x32_bf16 v[10:13], v[142:145], v[216:219], v[10:13]
	v_mfma_f32_16x16x32_bf16 v[54:57], v[146:149], v[162:165], v[54:57]
	v_mfma_f32_16x16x32_bf16 v[50:53], v[154:157], v[162:165], v[50:53]
	v_mfma_f32_16x16x32_bf16 v[38:41], v[146:149], v[182:185], v[38:41]
	v_mfma_f32_16x16x32_bf16 v[34:37], v[154:157], v[182:185], v[34:37]
	v_mfma_f32_16x16x32_bf16 v[22:25], v[146:149], v[204:207], v[22:25]
	v_mfma_f32_16x16x32_bf16 v[18:21], v[154:157], v[204:207], v[18:21]
	v_mfma_f32_16x16x32_bf16 v[6:9], v[146:149], v[212:215], v[6:9]
	v_mfma_f32_16x16x32_bf16 v[2:5], v[154:157], v[212:215], v[2:5]
	v_mfma_f32_16x16x32_bf16 v[54:57], v[150:153], v[178:181], v[54:57]
	v_mfma_f32_16x16x32_bf16 v[50:53], v[158:161], v[178:181], v[50:53]
	v_mfma_f32_16x16x32_bf16 v[38:41], v[150:153], v[196:199], v[38:41]
	v_mfma_f32_16x16x32_bf16 v[34:37], v[158:161], v[196:199], v[34:37]
	v_mfma_f32_16x16x32_bf16 v[22:25], v[150:153], v[208:211], v[22:25]
	v_mfma_f32_16x16x32_bf16 v[18:21], v[158:161], v[208:211], v[18:21]
	v_mfma_f32_16x16x32_bf16 v[6:9], v[150:153], v[216:219], v[6:9]
	v_mfma_f32_16x16x32_bf16 v[2:5], v[158:161], v[216:219], v[2:5]
	s_barrier
	s_setprio 0
	s_add_i32 s52, 0, 0x18000
	v_add_u32_e32 v0, s52, v201
	s_add_i32 s53, 0, 0x1c000
	ds_read_b128 v[130:133], v0
	ds_read_b128 v[134:137], v0 offset:1024
	ds_read_b128 v[138:141], v0 offset:2048
	ds_read_b128 v[142:145], v0 offset:3072
	v_add_u32_e32 v0, s53, v201
	ds_read_b128 v[146:149], v0
	ds_read_b128 v[150:153], v0 offset:1024
	ds_read_b128 v[154:157], v0 offset:2048
	ds_read_b128 v[158:161], v0 offset:3072
	s_add_u32 s38, s42, 0x10000
	s_addc_u32 s39, s43, 0
	s_mov_b32 m0, s45
	v_lshl_add_u64 v[246:247], s[38:39], 0, v[166:167]
	ds_read_b128 v[162:165], v202 offset:32768
	ds_read_b128 v[178:181], v202 offset:33792
	ds_read_b128 v[182:185], v202 offset:34816
	ds_read_b128 v[196:199], v202 offset:35840
	ds_read_b128 v[204:207], v202 offset:36864
	ds_read_b128 v[208:211], v202 offset:37888
	ds_read_b128 v[212:215], v202 offset:38912
	ds_read_b128 v[216:219], v202 offset:39936
	global_load_lds_dwordx4 v[246:247], off
	v_lshl_add_u64 v[246:247], s[38:39], 0, v[170:171]
	s_mov_b32 m0, s46
	s_nop 0
	global_load_lds_dwordx4 v[246:247], off
	s_waitcnt vmcnt(8)
	s_waitcnt lgkmcnt(0)
	s_setprio 1
	s_barrier
	v_mfma_f32_16x16x32_bf16 v[126:129], v[130:133], v[162:165], v[126:129]
	v_mfma_f32_16x16x32_bf16 v[122:125], v[138:141], v[162:165], v[122:125]
	v_mfma_f32_16x16x32_bf16 v[110:113], v[130:133], v[182:185], v[110:113]
	v_mfma_f32_16x16x32_bf16 v[106:109], v[138:141], v[182:185], v[106:109]
	v_mfma_f32_16x16x32_bf16 v[94:97], v[130:133], v[204:207], v[94:97]
	v_mfma_f32_16x16x32_bf16 v[90:93], v[138:141], v[204:207], v[90:93]
	v_mfma_f32_16x16x32_bf16 v[78:81], v[130:133], v[212:215], v[78:81]
	v_mfma_f32_16x16x32_bf16 v[74:77], v[138:141], v[212:215], v[74:77]
	v_mfma_f32_16x16x32_bf16 v[126:129], v[134:137], v[178:181], v[126:129]
	v_mfma_f32_16x16x32_bf16 v[122:125], v[142:145], v[178:181], v[122:125]
	v_mfma_f32_16x16x32_bf16 v[110:113], v[134:137], v[196:199], v[110:113]
	v_mfma_f32_16x16x32_bf16 v[106:109], v[142:145], v[196:199], v[106:109]
	v_mfma_f32_16x16x32_bf16 v[94:97], v[134:137], v[208:211], v[94:97]
	v_mfma_f32_16x16x32_bf16 v[90:93], v[142:145], v[208:211], v[90:93]
	v_mfma_f32_16x16x32_bf16 v[78:81], v[134:137], v[216:219], v[78:81]
	v_mfma_f32_16x16x32_bf16 v[74:77], v[142:145], v[216:219], v[74:77]
	v_mfma_f32_16x16x32_bf16 v[118:121], v[146:149], v[162:165], v[118:121]
	v_mfma_f32_16x16x32_bf16 v[114:117], v[154:157], v[162:165], v[114:117]
	v_mfma_f32_16x16x32_bf16 v[102:105], v[146:149], v[182:185], v[102:105]
	v_mfma_f32_16x16x32_bf16 v[98:101], v[154:157], v[182:185], v[98:101]
	v_mfma_f32_16x16x32_bf16 v[86:89], v[146:149], v[204:207], v[86:89]
	v_mfma_f32_16x16x32_bf16 v[82:85], v[154:157], v[204:207], v[82:85]
	v_mfma_f32_16x16x32_bf16 v[70:73], v[146:149], v[212:215], v[70:73]
	v_mfma_f32_16x16x32_bf16 v[66:69], v[154:157], v[212:215], v[66:69]
	v_mfma_f32_16x16x32_bf16 v[118:121], v[150:153], v[178:181], v[118:121]
	v_mfma_f32_16x16x32_bf16 v[114:117], v[158:161], v[178:181], v[114:117]
	v_mfma_f32_16x16x32_bf16 v[102:105], v[150:153], v[196:199], v[102:105]
	v_mfma_f32_16x16x32_bf16 v[98:101], v[158:161], v[196:199], v[98:101]
	v_mfma_f32_16x16x32_bf16 v[86:89], v[150:153], v[208:211], v[86:89]
	v_mfma_f32_16x16x32_bf16 v[82:85], v[158:161], v[208:211], v[82:85]
	v_mfma_f32_16x16x32_bf16 v[70:73], v[150:153], v[216:219], v[70:73]
	v_mfma_f32_16x16x32_bf16 v[66:69], v[158:161], v[216:219], v[66:69]
	s_barrier
; #define PG8_STAGE(bufoff, gbase, voff) do { _Pragma("unroll") for (int _i = 0; _i < 2; ++_i) \
;         __builtin_amdgcn_global_load_lds((const unsigned*)((const char*)(gbase) + (voff)[_i]), (LAS unsigned*)(lds + (bufoff) + ldsw + _i * 8192), 16, 0, 0); } while (0)
; #define PG8_LDA(dst, b, h) do { _Pragma("unroll") for (int m = 0; m < 4; ++m) _Pragma("unroll") for (int k = 0; k < 2; ++k) dst[m][k] = *(const LAS bf16x8*)(lds + PG8_SA(b, h) + aoff + m * 2048 + k * 1024); } while (0)
; #define PG8_MMA(ai, bj, At, Bt) do { __builtin_amdgcn_s_setprio(1); _Pragma("unroll") for (int m = 0; m < 4; ++m) _Pragma("unroll") for (int n = 0; n < 2; ++n) _Pragma("unroll") for (int k = 0; k < 2; ++k) \
;         acc[ai][bj][m][n] = __builtin_amdgcn_mfma_f32_16x16x32_bf16(Bt[n][k], At[m][k], acc[ai][bj][m][n], 0, 0, 0); __builtin_amdgcn_s_setprio(0); } while (0)
; #define PG8_WAIT_V(n) asm volatile("s_waitcnt vmcnt(" #n ")" ::: "memory")
; #define PG8_WAIT_L(n) asm volatile("s_waitcnt lgkmcnt(" #n ")" ::: "memory")
; #define PG8_BAR __builtin_amdgcn_s_barrier()
; #define PG8_SCHED __builtin_amdgcn_sched_barrier(0)
; template <class Epi, class Sched>
; __device__ __forceinline__ void gemm_phase(LAS unsigned char* lds, const Gemm g, const Sched& S, const Epi& E) {
;     ...
;             PG8_LDA(At, 1, 1); PG8_STAGE(PG8_SB(1, 0), b3, voffB); PG8_STAGE(PG8_SB(1, 1), b3 + hstepB, voffB); PG8_STAGE(PG8_SA(1, 0), a3, voffA);
;             PG8_WAIT_V(8); PG8_WAIT_L(0); PG8_BAR; PG8_MMA(1, 0, At, B0); PG8_MMA(1, 1, At, B1); PG8_BAR; PG8_SCHED;
;         }
	s_setprio 0
	s_add_i32 s38, s52, s17
	v_lshl_add_u64 v[220:221], v[220:221], 0, s[26:27]
	s_mov_b32 m0, s38
	ds_read_b128 v[162:165], v202 offset:49152
	ds_read_b128 v[178:181], v202 offset:50176
	ds_read_b128 v[182:185], v202 offset:51200
	ds_read_b128 v[196:199], v202 offset:52224
	ds_read_b128 v[204:207], v202 offset:53248
	ds_read_b128 v[208:211], v202 offset:54272
	ds_read_b128 v[212:215], v202 offset:55296
	ds_read_b128 v[216:219], v202 offset:56320
	global_load_lds_dwordx4 v[220:221], off
	s_add_i32 m0, s38, 0x2000
	s_add_u32 s0, s0, 0x50080
	v_lshl_add_u64 v[220:221], v[232:233], 0, s[26:27]
	s_addc_u32 s1, s1, 0
	s_add_i32 s38, s53, s17
	global_load_lds_dwordx4 v[220:221], off
	v_lshl_add_u64 v[220:221], s[0:1], 0, v[168:169]
	s_mov_b32 m0, s38
	s_nop 0
	global_load_lds_dwordx4 v[220:221], off
	v_lshl_add_u64 v[220:221], s[0:1], 0, v[172:173]
	s_add_i32 m0, s38, 0x2000
	s_nop 0
	global_load_lds_dwordx4 v[220:221], off
	v_lshl_add_u64 v[220:221], v[234:235], 0, s[26:27]
	s_mov_b32 m0, s67
	s_nop 0
	global_load_lds_dwordx4 v[220:221], off
	v_lshl_add_u64 v[220:221], v[236:237], 0, s[26:27]
	s_mov_b32 m0, s69
	s_nop 0
	global_load_lds_dwordx4 v[220:221], off
	s_waitcnt vmcnt(8)
	s_waitcnt lgkmcnt(0)
	s_setprio 1
	s_barrier
	v_mfma_f32_16x16x32_bf16 v[62:65], v[130:133], v[162:165], v[62:65]
	v_mfma_f32_16x16x32_bf16 v[58:61], v[138:141], v[162:165], v[58:61]
	v_mfma_f32_16x16x32_bf16 v[46:49], v[130:133], v[182:185], v[46:49]
	v_mfma_f32_16x16x32_bf16 v[42:45], v[138:141], v[182:185], v[42:45]
	v_mfma_f32_16x16x32_bf16 v[30:33], v[130:133], v[204:207], v[30:33]
	v_mfma_f32_16x16x32_bf16 v[26:29], v[138:141], v[204:207], v[26:29]
	v_mfma_f32_16x16x32_bf16 v[14:17], v[130:133], v[212:215], v[14:17]
	v_mfma_f32_16x16x32_bf16 v[10:13], v[138:141], v[212:215], v[10:13]
	v_mfma_f32_16x16x32_bf16 v[62:65], v[134:137], v[178:181], v[62:65]
	v_mfma_f32_16x16x32_bf16 v[58:61], v[142:145], v[178:181], v[58:61]
	v_mfma_f32_16x16x32_bf16 v[46:49], v[134:137], v[196:199], v[46:49]
	v_mfma_f32_16x16x32_bf16 v[42:45], v[142:145], v[196:199], v[42:45]
	v_mfma_f32_16x16x32_bf16 v[30:33], v[134:137], v[208:211], v[30:33]
	v_mfma_f32_16x16x32_bf16 v[26:29], v[142:145], v[208:211], v[26:29]
	v_mfma_f32_16x16x32_bf16 v[14:17], v[134:137], v[216:219], v[14:17]
	v_mfma_f32_16x16x32_bf16 v[10:13], v[142:145], v[216:219], v[10:13]
	v_mfma_f32_16x16x32_bf16 v[54:57], v[146:149], v[162:165], v[54:57]
	v_mfma_f32_16x16x32_bf16 v[50:53], v[154:157], v[162:165], v[50:53]
	v_mfma_f32_16x16x32_bf16 v[38:41], v[146:149], v[182:185], v[38:41]
	v_mfma_f32_16x16x32_bf16 v[34:37], v[154:157], v[182:185], v[34:37]
	v_mfma_f32_16x16x32_bf16 v[22:25], v[146:149], v[204:207], v[22:25]
	v_mfma_f32_16x16x32_bf16 v[18:21], v[154:157], v[204:207], v[18:21]
	v_mfma_f32_16x16x32_bf16 v[6:9], v[146:149], v[212:215], v[6:9]
	v_mfma_f32_16x16x32_bf16 v[2:5], v[154:157], v[212:215], v[2:5]
	v_mfma_f32_16x16x32_bf16 v[54:57], v[150:153], v[178:181], v[54:57]
	v_mfma_f32_16x16x32_bf16 v[50:53], v[158:161], v[178:181], v[50:53]
	v_mfma_f32_16x16x32_bf16 v[38:41], v[150:153], v[196:199], v[38:41]
	v_mfma_f32_16x16x32_bf16 v[34:37], v[158:161], v[196:199], v[34:37]
	v_mfma_f32_16x16x32_bf16 v[22:25], v[150:153], v[208:211], v[22:25]
	v_mfma_f32_16x16x32_bf16 v[18:21], v[158:161], v[208:211], v[18:21]
	v_mfma_f32_16x16x32_bf16 v[6:9], v[150:153], v[216:219], v[6:9]
	v_mfma_f32_16x16x32_bf16 v[2:5], v[158:161], v[216:219], v[2:5]
	s_barrier
	s_setprio 0
	s_add_u32 s97, s97, 0x100
	s_addc_u32 vcc_lo, vcc_lo, 0
	s_add_u32 s20, s20, 0x100
	s_addc_u32 s21, s21, 0
	s_cmp_ge_i32 s62, s47
	s_mov_b32 s0, s62
	s_cbranch_scc0 .LBB0_526

; #define PG8_STAGE(bufoff, gbase, voff) do { _Pragma("unroll") for (int _i = 0; _i < 2; ++_i) \
;         __builtin_amdgcn_global_load_lds((const unsigned*)((const char*)(gbase) + (voff)[_i]), (LAS unsigned*)(lds + (bufoff) + ldsw + _i * 8192), 16, 0, 0); } while (0)
; #define PG8_LDA(dst, b, h) do { _Pragma("unroll") for (int m = 0; m < 4; ++m) _Pragma("unroll") for (int k = 0; k < 2; ++k) dst[m][k] = *(const LAS bf16x8*)(lds + PG8_SA(b, h) + aoff + m * 2048 + k * 1024); } while (0)
; #define PG8_LDB(dst, b, h) do { _Pragma("unroll") for (int n = 0; n < 2; ++n) _Pragma("unroll") for (int k = 0; k < 2; ++k) dst[n][k] = *(const LAS bf16x8*)(lds + PG8_SB(b, h) + boff + n * 2048 + k * 1024); } while (0)
; #define PG8_MMA(ai, bj, At, Bt) do { __builtin_amdgcn_s_setprio(1); _Pragma("unroll") for (int m = 0; m < 4; ++m) _Pragma("unroll") for (int n = 0; n < 2; ++n) _Pragma("unroll") for (int k = 0; k < 2; ++k) \
;         acc[ai][bj][m][n] = __builtin_amdgcn_mfma_f32_16x16x32_bf16(Bt[n][k], At[m][k], acc[ai][bj][m][n], 0, 0, 0); __builtin_amdgcn_s_setprio(0); } while (0)
; #define PG8_WAIT_V(n) asm volatile("s_waitcnt vmcnt(" #n ")" ::: "memory")
; template <class Epi, class Sched>
; __device__ __forceinline__ void gemm_phase(LAS unsigned char* lds, const Gemm g, const Sched& S, const Epi& E) {
;     ...
;         for (int t = 0; t < nt; t += 2) {
;             if constexpr (Epi::HOOKS) { if (cur.kind == 3 && (t == 4 || t == 12)) { int fr_ = fr, fq_ = fq; asm volatile("" : "+v"(fr_), "+v"(fq_)); E.hook(acc, cur, t == 4 ? 0 : 1, wr, wc, fr_, fq_); } }
;             const bool last = (t == nt - 2);
;             const char* a1 = cA + (size_t)(t + 1) * kstep;
;             const char* a2 = last ? nA : cA + (size_t)(t + 2) * kstep; const char* b2 = last ? nB : cB + (size_t)(t + 2) * kstep;
;             const char* a3 = a2 + kstep; const char* b3 = b2 + kstep;
;             PG8_LDB(B0, 0, 0); PG8_LDB(B1, 0, 1); PG8_SCHED; PG8_LDA(At, 0, 0); PG8_STAGE(PG8_SA(1, 1), a1 + hstepA, voffA);
;             PG8_WAIT_V(8); PG8_WAIT_L(0); PG8_BAR; PG8_MMA(0, 0, At, B0); PG8_MMA(0, 1, At, B1); PG8_BAR; PG8_SCHED;
;             PG8_LDA(At, 0, 1); PG8_STAGE(PG8_SB(0, 0), b2, voffB); PG8_STAGE(PG8_SB(0, 1), b2 + hstepB, voffB); PG8_STAGE(PG8_SA(0, 0), a2, voffA);
;             PG8_WAIT_V(8); PG8_WAIT_L(0); PG8_BAR; PG8_MMA(1, 0, At, B0); PG8_MMA(1, 1, At, B1); PG8_BAR; PG8_SCHED;
.LBB0_551:
	s_add_i32 s62, s0, 2
	s_add_u32 s1, s20, 0xffff0080
	s_addc_u32 s42, s21, -1
	s_add_i32 s43, 0, 0x10000
	s_cmp_eq_u32 s71, s0
	s_cselect_b32 vcc_hi, s19, s42
	s_cselect_b32 vcc_lo, s25, s1
	s_cselect_b32 s1, s41, s72
	s_cselect_b32 s0, s67, s69
	s_add_i32 s52, 0, 0x14000
	v_add_u32_e32 v38, s43, v251
	v_add_u32_e32 v70, s52, v251
	ds_read_b128 v[26:29], v38
	ds_read_b128 v[30:33], v38 offset:1024
	ds_read_b128 v[34:37], v38 offset:2048
	ds_read_b128 v[38:41], v38 offset:3072
	ds_read_b128 v[50:53], v70
	ds_read_b128 v[54:57], v70 offset:1024
	ds_read_b128 v[58:61], v70 offset:2048
	ds_read_b128 v[70:73], v70 offset:3072
	v_lshl_add_u64 v[214:215], s[20:21], 0, v[204:205]
	s_add_i32 m0, s46, 0xc000
	ds_read_b128 v[90:93], v252
	ds_read_b128 v[110:113], v252 offset:1024
	ds_read_b128 v[126:129], v252 offset:2048
	ds_read_b128 v[142:145], v252 offset:3072
	ds_read_b128 v[162:165], v252 offset:4096
	ds_read_b128 v[182:185], v252 offset:5120
	ds_read_b128 v[206:209], v252 offset:6144
	ds_read_b128 v[210:213], v252 offset:7168
	global_load_lds_dwordx4 v[214:215], off
	v_lshl_add_u64 v[214:215], s[20:21], 0, v[202:203]
	s_add_i32 m0, s46, 0xe000
	s_nop 0
	global_load_lds_dwordx4 v[214:215], off
	s_waitcnt vmcnt(8)
	s_waitcnt lgkmcnt(0)
	s_setprio 1
	s_barrier
	v_mfma_f32_16x16x32_bf16 v[178:181], v[26:29], v[90:93], v[178:181]
	v_mfma_f32_16x16x32_bf16 v[170:173], v[34:37], v[90:93], v[170:173]
	v_mfma_f32_16x16x32_bf16 v[158:161], v[26:29], v[126:129], v[158:161]
	v_mfma_f32_16x16x32_bf16 v[150:153], v[34:37], v[126:129], v[150:153]
	v_mfma_f32_16x16x32_bf16 v[138:141], v[26:29], v[162:165], v[138:141]
	v_mfma_f32_16x16x32_bf16 v[130:133], v[34:37], v[162:165], v[130:133]
	v_mfma_f32_16x16x32_bf16 v[118:121], v[26:29], v[206:209], v[118:121]
	v_mfma_f32_16x16x32_bf16 v[106:109], v[34:37], v[206:209], v[106:109]
	v_mfma_f32_16x16x32_bf16 v[178:181], v[30:33], v[110:113], v[178:181]
	v_mfma_f32_16x16x32_bf16 v[170:173], v[38:41], v[110:113], v[170:173]
	v_mfma_f32_16x16x32_bf16 v[158:161], v[30:33], v[142:145], v[158:161]
	v_mfma_f32_16x16x32_bf16 v[150:153], v[38:41], v[142:145], v[150:153]
	v_mfma_f32_16x16x32_bf16 v[138:141], v[30:33], v[182:185], v[138:141]
	v_mfma_f32_16x16x32_bf16 v[130:133], v[38:41], v[182:185], v[130:133]
	v_mfma_f32_16x16x32_bf16 v[118:121], v[30:33], v[210:213], v[118:121]
	v_mfma_f32_16x16x32_bf16 v[106:109], v[38:41], v[210:213], v[106:109]
	v_mfma_f32_16x16x32_bf16 v[174:177], v[50:53], v[90:93], v[174:177]
	v_mfma_f32_16x16x32_bf16 v[90:93], v[58:61], v[90:93], v[166:169]
	v_mfma_f32_16x16x32_bf16 v[134:137], v[50:53], v[162:165], v[134:137]
	v_mfma_f32_16x16x32_bf16 v[122:125], v[58:61], v[162:165], v[122:125]
	v_mfma_f32_16x16x32_bf16 v[114:117], v[50:53], v[206:209], v[114:117]
	v_mfma_f32_16x16x32_bf16 v[102:105], v[58:61], v[206:209], v[102:105]
	v_mfma_f32_16x16x32_bf16 v[174:177], v[54:57], v[110:113], v[174:177]
	v_mfma_f32_16x16x32_bf16 v[90:93], v[70:73], v[110:113], v[90:93]
	v_mfma_f32_16x16x32_bf16 v[110:113], v[50:53], v[126:129], v[154:157]
	v_mfma_f32_16x16x32_bf16 v[126:129], v[58:61], v[126:129], v[146:149]
	v_mfma_f32_16x16x32_bf16 v[134:137], v[54:57], v[182:185], v[134:137]
	v_mfma_f32_16x16x32_bf16 v[122:125], v[70:73], v[182:185], v[122:125]
	v_mfma_f32_16x16x32_bf16 v[114:117], v[54:57], v[210:213], v[114:117]
	v_mfma_f32_16x16x32_bf16 v[102:105], v[70:73], v[210:213], v[102:105]
	v_mfma_f32_16x16x32_bf16 v[110:113], v[54:57], v[142:145], v[110:113]
	v_mfma_f32_16x16x32_bf16 v[126:129], v[70:73], v[142:145], v[126:129]
	s_barrier
	s_setprio 0
	s_add_i32 s42, s43, s45
	v_lshl_add_u64 v[232:233], s[0:1], 0, v[0:1]
	s_mov_b32 m0, s42
	ds_read_b128 v[142:145], v252 offset:16384
	ds_read_b128 v[146:149], v252 offset:17408
	ds_read_b128 v[154:157], v252 offset:18432
	ds_read_b128 v[162:165], v252 offset:19456
	ds_read_b128 v[166:169], v252 offset:20480
	ds_read_b128 v[182:185], v252 offset:21504
	ds_read_b128 v[206:209], v252 offset:22528
	ds_read_b128 v[210:213], v252 offset:23552
	global_load_lds_dwordx4 v[232:233], off
	s_add_i32 m0, s42, 0x2000
	s_add_u32 s42, s0, 0x10000
	v_lshl_add_u64 v[234:235], s[0:1], 0, v[200:201]
	s_addc_u32 s43, s1, 0
	s_add_i32 s52, s52, s45
	global_load_lds_dwordx4 v[234:235], off
	v_lshl_add_u64 v[214:215], s[42:43], 0, v[0:1]
	s_mov_b32 m0, s52
	v_lshl_add_u64 v[236:237], vcc, 0, v[196:197]
	global_load_lds_dwordx4 v[214:215], off
	v_lshl_add_u64 v[214:215], s[42:43], 0, v[200:201]
	s_add_i32 m0, s52, 0x2000
	v_lshl_add_u64 v[246:247], vcc, 0, v[198:199]
	global_load_lds_dwordx4 v[214:215], off
	s_mov_b32 m0, s46
	s_nop 0
	global_load_lds_dwordx4 v[236:237], off
	s_mov_b32 m0, s47
	s_nop 0
	global_load_lds_dwordx4 v[246:247], off
	s_waitcnt vmcnt(8)
	s_waitcnt lgkmcnt(0)
	s_setprio 1
	s_barrier
; #define PG8_STAGE(bufoff, gbase, voff) do { _Pragma("unroll") for (int _i = 0; _i < 2; ++_i) \
;         __builtin_amdgcn_global_load_lds((const unsigned*)((const char*)(gbase) + (voff)[_i]), (LAS unsigned*)(lds + (bufoff) + ldsw + _i * 8192), 16, 0, 0); } while (0)
; #define PG8_LDA(dst, b, h) do { _Pragma("unroll") for (int m = 0; m < 4; ++m) _Pragma("unroll") for (int k = 0; k < 2; ++k) dst[m][k] = *(const LAS bf16x8*)(lds + PG8_SA(b, h) + aoff + m * 2048 + k * 1024); } while (0)
; #define PG8_LDB(dst, b, h) do { _Pragma("unroll") for (int n = 0; n < 2; ++n) _Pragma("unroll") for (int k = 0; k < 2; ++k) dst[n][k] = *(const LAS bf16x8*)(lds + PG8_SB(b, h) + boff + n * 2048 + k * 1024); } while (0)
; #define PG8_MMA(ai, bj, At, Bt) do { __builtin_amdgcn_s_setprio(1); _Pragma("unroll") for (int m = 0; m < 4; ++m) _Pragma("unroll") for (int n = 0; n < 2; ++n) _Pragma("unroll") for (int k = 0; k < 2; ++k) \
;         acc[ai][bj][m][n] = __builtin_amdgcn_mfma_f32_16x16x32_bf16(Bt[n][k], At[m][k], acc[ai][bj][m][n], 0, 0, 0); __builtin_amdgcn_s_setprio(0); } while (0)
; #define PG8_WAIT_V(n) asm volatile("s_waitcnt vmcnt(" #n ")" ::: "memory")
; #define PG8_WAIT_L(n) asm volatile("s_waitcnt lgkmcnt(" #n ")" ::: "memory")
; #define PG8_BAR __builtin_amdgcn_s_barrier()
; #define PG8_SCHED __builtin_amdgcn_sched_barrier(0)
; template <class Epi, class Sched>
; __device__ __forceinline__ void gemm_phase(LAS unsigned char* lds, const Gemm g, const Sched& S, const Epi& E) {
;     ...
;             PG8_WAIT_V(8); PG8_WAIT_L(0); PG8_BAR; PG8_MMA(1, 0, At, B0); PG8_MMA(1, 1, At, B1); PG8_BAR; PG8_SCHED;
;             PG8_LDB(B0, 1, 0); PG8_LDB(B1, 1, 1); PG8_SCHED; PG8_LDA(At, 1, 0); PG8_STAGE(PG8_SA(0, 1), a2 + hstepA, voffA);
;             PG8_WAIT_V(8); PG8_WAIT_L(0); PG8_BAR; PG8_MMA(0, 0, At, B0); PG8_MMA(0, 1, At, B1); PG8_BAR; PG8_SCHED;
	v_mfma_f32_16x16x32_bf16 v[98:101], v[26:29], v[142:145], v[98:101]
	v_mfma_f32_16x16x32_bf16 v[86:89], v[34:37], v[142:145], v[86:89]
	v_mfma_f32_16x16x32_bf16 v[78:81], v[26:29], v[154:157], v[78:81]
	v_mfma_f32_16x16x32_bf16 v[66:69], v[34:37], v[154:157], v[66:69]
	v_mfma_f32_16x16x32_bf16 v[46:49], v[26:29], v[166:169], v[46:49]
	v_mfma_f32_16x16x32_bf16 v[22:25], v[34:37], v[166:169], v[22:25]
	v_mfma_f32_16x16x32_bf16 v[14:17], v[26:29], v[206:209], v[14:17]
	v_mfma_f32_16x16x32_bf16 v[6:9], v[34:37], v[206:209], v[6:9]
	v_mfma_f32_16x16x32_bf16 v[98:101], v[30:33], v[146:149], v[98:101]
	v_mfma_f32_16x16x32_bf16 v[86:89], v[38:41], v[146:149], v[86:89]
	v_mfma_f32_16x16x32_bf16 v[78:81], v[30:33], v[162:165], v[78:81]
	v_mfma_f32_16x16x32_bf16 v[66:69], v[38:41], v[162:165], v[66:69]
	v_mfma_f32_16x16x32_bf16 v[46:49], v[30:33], v[182:185], v[46:49]
	v_mfma_f32_16x16x32_bf16 v[22:25], v[38:41], v[182:185], v[22:25]
	v_mfma_f32_16x16x32_bf16 v[14:17], v[30:33], v[210:213], v[14:17]
	v_mfma_f32_16x16x32_bf16 v[6:9], v[38:41], v[210:213], v[6:9]
	v_mfma_f32_16x16x32_bf16 v[42:45], v[50:53], v[166:169], v[42:45]
	v_mfma_f32_16x16x32_bf16 v[18:21], v[58:61], v[166:169], v[18:21]
	v_mfma_f32_16x16x32_bf16 v[10:13], v[50:53], v[206:209], v[10:13]
	v_mfma_f32_16x16x32_bf16 v[2:5], v[58:61], v[206:209], v[2:5]
	v_mfma_f32_16x16x32_bf16 v[26:29], v[50:53], v[142:145], v[94:97]
	v_mfma_f32_16x16x32_bf16 v[30:33], v[58:61], v[142:145], v[82:85]
	v_mfma_f32_16x16x32_bf16 v[34:37], v[50:53], v[154:157], v[74:77]
	v_mfma_f32_16x16x32_bf16 v[38:41], v[58:61], v[154:157], v[62:65]
	v_mfma_f32_16x16x32_bf16 v[42:45], v[54:57], v[182:185], v[42:45]
	v_mfma_f32_16x16x32_bf16 v[18:21], v[70:73], v[182:185], v[18:21]
	v_mfma_f32_16x16x32_bf16 v[10:13], v[54:57], v[210:213], v[10:13]
	v_mfma_f32_16x16x32_bf16 v[2:5], v[70:73], v[210:213], v[2:5]
	v_mfma_f32_16x16x32_bf16 v[26:29], v[54:57], v[146:149], v[26:29]
	v_mfma_f32_16x16x32_bf16 v[30:33], v[70:73], v[146:149], v[30:33]
	v_mfma_f32_16x16x32_bf16 v[34:37], v[54:57], v[162:165], v[34:37]
	v_mfma_f32_16x16x32_bf16 v[38:41], v[70:73], v[162:165], v[38:41]
	s_barrier
	s_setprio 0
	s_add_i32 s52, 0, 0x18000
	s_add_i32 s53, 0, 0x1c000
	v_add_u32_e32 v62, s52, v251
	v_add_u32_e32 v74, s53, v251
	ds_read_b128 v[50:53], v62
	ds_read_b128 v[54:57], v62 offset:1024
	ds_read_b128 v[58:61], v62 offset:2048
	ds_read_b128 v[62:65], v62 offset:3072
	ds_read_b128 v[70:73], v74
	ds_read_b128 v[142:145], v74 offset:1024
	ds_read_b128 v[162:165], v74 offset:2048
	ds_read_b128 v[182:185], v74 offset:3072
	s_add_u32 s42, vcc_lo, 0x10000
	s_addc_u32 s43, vcc_hi, 0
	s_mov_b32 m0, s48
	v_lshl_add_u64 v[154:155], s[42:43], 0, v[196:197]
	ds_read_b128 v[74:77], v252 offset:32768
	ds_read_b128 v[82:85], v252 offset:33792
	ds_read_b128 v[94:97], v252 offset:34816
	ds_read_b128 v[146:149], v252 offset:35840
	ds_read_b128 v[206:209], v252 offset:36864
	ds_read_b128 v[210:213], v252 offset:37888
	ds_read_b128 v[214:217], v252 offset:38912
	ds_read_b128 v[218:221], v252 offset:39936
	global_load_lds_dwordx4 v[154:155], off
	v_lshl_add_u64 v[154:155], s[42:43], 0, v[198:199]
	s_mov_b32 m0, s65
	s_nop 0
	global_load_lds_dwordx4 v[154:155], off
	s_waitcnt vmcnt(8)
	s_waitcnt lgkmcnt(0)
	s_setprio 1
	s_barrier
	v_mfma_f32_16x16x32_bf16 v[154:157], v[50:53], v[74:77], v[178:181]
	v_mfma_f32_16x16x32_bf16 v[178:181], v[54:57], v[82:85], v[154:157]
	v_mfma_f32_16x16x32_bf16 v[154:157], v[58:61], v[74:77], v[170:173]
	v_mfma_f32_16x16x32_bf16 v[170:173], v[62:65], v[82:85], v[154:157]
	v_mfma_f32_16x16x32_bf16 v[154:157], v[50:53], v[94:97], v[158:161]
	v_mfma_f32_16x16x32_bf16 v[150:153], v[58:61], v[94:97], v[150:153]
	v_mfma_f32_16x16x32_bf16 v[138:141], v[50:53], v[206:209], v[138:141]
	v_mfma_f32_16x16x32_bf16 v[130:133], v[58:61], v[206:209], v[130:133]
	v_mfma_f32_16x16x32_bf16 v[118:121], v[50:53], v[214:217], v[118:121]
	v_mfma_f32_16x16x32_bf16 v[106:109], v[58:61], v[214:217], v[106:109]
	v_mfma_f32_16x16x32_bf16 v[158:161], v[54:57], v[146:149], v[154:157]
	v_mfma_f32_16x16x32_bf16 v[150:153], v[62:65], v[146:149], v[150:153]
	v_mfma_f32_16x16x32_bf16 v[138:141], v[54:57], v[210:213], v[138:141]
	v_mfma_f32_16x16x32_bf16 v[130:133], v[62:65], v[210:213], v[130:133]
	v_mfma_f32_16x16x32_bf16 v[118:121], v[54:57], v[218:221], v[118:121]
	v_mfma_f32_16x16x32_bf16 v[106:109], v[62:65], v[218:221], v[106:109]
	v_mfma_f32_16x16x32_bf16 v[154:157], v[70:73], v[74:77], v[174:177]
	v_mfma_f32_16x16x32_bf16 v[74:77], v[162:165], v[74:77], v[90:93]
	v_mfma_f32_16x16x32_bf16 v[166:169], v[182:185], v[82:85], v[74:77]
	v_mfma_f32_16x16x32_bf16 v[74:77], v[70:73], v[94:97], v[110:113]
	v_mfma_f32_16x16x32_bf16 v[174:177], v[142:145], v[82:85], v[154:157]
	v_mfma_f32_16x16x32_bf16 v[154:157], v[142:145], v[146:149], v[74:77]
	v_mfma_f32_16x16x32_bf16 v[74:77], v[162:165], v[94:97], v[126:129]
	v_mfma_f32_16x16x32_bf16 v[146:149], v[182:185], v[146:149], v[74:77]
	v_mfma_f32_16x16x32_bf16 v[74:77], v[70:73], v[206:209], v[134:137]
	v_mfma_f32_16x16x32_bf16 v[134:137], v[142:145], v[210:213], v[74:77]
	v_mfma_f32_16x16x32_bf16 v[74:77], v[162:165], v[206:209], v[122:125]
	v_mfma_f32_16x16x32_bf16 v[122:125], v[182:185], v[210:213], v[74:77]
	v_mfma_f32_16x16x32_bf16 v[74:77], v[70:73], v[214:217], v[114:117]
	v_mfma_f32_16x16x32_bf16 v[114:117], v[142:145], v[218:221], v[74:77]
	v_mfma_f32_16x16x32_bf16 v[74:77], v[162:165], v[214:217], v[102:105]
	v_mfma_f32_16x16x32_bf16 v[102:105], v[182:185], v[218:221], v[74:77]
	s_barrier
; #define PG8_STAGE(bufoff, gbase, voff) do { _Pragma("unroll") for (int _i = 0; _i < 2; ++_i) \
;         __builtin_amdgcn_global_load_lds((const unsigned*)((const char*)(gbase) + (voff)[_i]), (LAS unsigned*)(lds + (bufoff) + ldsw + _i * 8192), 16, 0, 0); } while (0)
; #define PG8_LDA(dst, b, h) do { _Pragma("unroll") for (int m = 0; m < 4; ++m) _Pragma("unroll") for (int k = 0; k < 2; ++k) dst[m][k] = *(const LAS bf16x8*)(lds + PG8_SA(b, h) + aoff + m * 2048 + k * 1024); } while (0)
; #define PG8_MMA(ai, bj, At, Bt) do { __builtin_amdgcn_s_setprio(1); _Pragma("unroll") for (int m = 0; m < 4; ++m) _Pragma("unroll") for (int n = 0; n < 2; ++n) _Pragma("unroll") for (int k = 0; k < 2; ++k) \
;         acc[ai][bj][m][n] = __builtin_amdgcn_mfma_f32_16x16x32_bf16(Bt[n][k], At[m][k], acc[ai][bj][m][n], 0, 0, 0); __builtin_amdgcn_s_setprio(0); } while (0)
; #define PG8_WAIT_V(n) asm volatile("s_waitcnt vmcnt(" #n ")" ::: "memory")
; #define PG8_WAIT_L(n) asm volatile("s_waitcnt lgkmcnt(" #n ")" ::: "memory")
; #define PG8_BAR __builtin_amdgcn_s_barrier()
; #define PG8_SCHED __builtin_amdgcn_sched_barrier(0)
; template <class Epi, class Sched>
; __device__ __forceinline__ void gemm_phase(LAS unsigned char* lds, const Gemm g, const Sched& S, const Epi& E) {
;     ...
;             PG8_LDA(At, 1, 1); PG8_STAGE(PG8_SB(1, 0), b3, voffB); PG8_STAGE(PG8_SB(1, 1), b3 + hstepB, voffB); PG8_STAGE(PG8_SA(1, 0), a3, voffA);
;             PG8_WAIT_V(8); PG8_WAIT_L(0); PG8_BAR; PG8_MMA(1, 0, At, B0); PG8_MMA(1, 1, At, B1); PG8_BAR; PG8_SCHED;
;         }
	s_setprio 0
	s_add_i32 s42, s52, s45
	v_lshl_add_u64 v[94:95], v[232:233], 0, s[26:27]
	s_mov_b32 m0, s42
	s_nop 1
	ds_read_b128 v[74:77], v252 offset:49152
	ds_read_b128 v[82:85], v252 offset:50176
	ds_read_b128 v[90:93], v252 offset:51200
	ds_read_b128 v[110:113], v252 offset:52224
	ds_read_b128 v[126:129], v252 offset:53248
	ds_read_b128 v[206:209], v252 offset:54272
	ds_read_b128 v[210:213], v252 offset:55296
	ds_read_b128 v[214:217], v252 offset:56320
	global_load_lds_dwordx4 v[94:95], off
	s_add_i32 m0, s42, 0x2000
	s_add_u32 s0, s0, 0x10080
	v_lshl_add_u64 v[94:95], v[234:235], 0, s[26:27]
	s_addc_u32 s1, s1, 0
	s_add_i32 s42, s53, s45
	global_load_lds_dwordx4 v[94:95], off
	v_lshl_add_u64 v[94:95], s[0:1], 0, v[0:1]
	s_mov_b32 m0, s42
	s_nop 0
	global_load_lds_dwordx4 v[94:95], off
	v_lshl_add_u64 v[94:95], s[0:1], 0, v[200:201]
	s_add_i32 m0, s42, 0x2000
	s_nop 0
	global_load_lds_dwordx4 v[94:95], off
	v_lshl_add_u64 v[94:95], v[236:237], 0, s[26:27]
	s_mov_b32 m0, s96
	s_nop 0
	global_load_lds_dwordx4 v[94:95], off
	v_lshl_add_u64 v[94:95], v[246:247], 0, s[26:27]
	s_mov_b32 m0, s97
	s_nop 0
	global_load_lds_dwordx4 v[94:95], off
	s_waitcnt vmcnt(8)
	s_waitcnt lgkmcnt(0)
	s_setprio 1
	s_barrier
	v_mfma_f32_16x16x32_bf16 v[94:97], v[50:53], v[74:77], v[98:101]
	v_mfma_f32_16x16x32_bf16 v[86:89], v[58:61], v[74:77], v[86:89]
	v_mfma_f32_16x16x32_bf16 v[78:81], v[50:53], v[90:93], v[78:81]
	v_mfma_f32_16x16x32_bf16 v[66:69], v[58:61], v[90:93], v[66:69]
	v_mfma_f32_16x16x32_bf16 v[46:49], v[50:53], v[126:129], v[46:49]
	v_mfma_f32_16x16x32_bf16 v[22:25], v[58:61], v[126:129], v[22:25]
	v_mfma_f32_16x16x32_bf16 v[14:17], v[50:53], v[210:213], v[14:17]
	v_mfma_f32_16x16x32_bf16 v[6:9], v[58:61], v[210:213], v[6:9]
	v_mfma_f32_16x16x32_bf16 v[98:101], v[54:57], v[82:85], v[94:97]
	v_mfma_f32_16x16x32_bf16 v[86:89], v[62:65], v[82:85], v[86:89]
	v_mfma_f32_16x16x32_bf16 v[78:81], v[54:57], v[110:113], v[78:81]
	v_mfma_f32_16x16x32_bf16 v[66:69], v[62:65], v[110:113], v[66:69]
	v_mfma_f32_16x16x32_bf16 v[46:49], v[54:57], v[206:209], v[46:49]
	v_mfma_f32_16x16x32_bf16 v[22:25], v[62:65], v[206:209], v[22:25]
	v_mfma_f32_16x16x32_bf16 v[14:17], v[54:57], v[214:217], v[14:17]
	v_mfma_f32_16x16x32_bf16 v[6:9], v[62:65], v[214:217], v[6:9]
	v_mfma_f32_16x16x32_bf16 v[26:29], v[70:73], v[74:77], v[26:29]
	v_mfma_f32_16x16x32_bf16 v[94:97], v[142:145], v[82:85], v[26:29]
	v_mfma_f32_16x16x32_bf16 v[26:29], v[162:165], v[74:77], v[30:33]
	v_mfma_f32_16x16x32_bf16 v[82:85], v[182:185], v[82:85], v[26:29]
	v_mfma_f32_16x16x32_bf16 v[26:29], v[70:73], v[90:93], v[34:37]
	v_mfma_f32_16x16x32_bf16 v[74:77], v[142:145], v[110:113], v[26:29]
	v_mfma_f32_16x16x32_bf16 v[26:29], v[162:165], v[90:93], v[38:41]
	v_mfma_f32_16x16x32_bf16 v[62:65], v[182:185], v[110:113], v[26:29]
	v_mfma_f32_16x16x32_bf16 v[26:29], v[70:73], v[126:129], v[42:45]
	v_mfma_f32_16x16x32_bf16 v[18:21], v[162:165], v[126:129], v[18:21]
	v_mfma_f32_16x16x32_bf16 v[10:13], v[70:73], v[210:213], v[10:13]
	v_mfma_f32_16x16x32_bf16 v[2:5], v[162:165], v[210:213], v[2:5]
	v_mfma_f32_16x16x32_bf16 v[42:45], v[142:145], v[206:209], v[26:29]
	v_mfma_f32_16x16x32_bf16 v[18:21], v[182:185], v[206:209], v[18:21]
	v_mfma_f32_16x16x32_bf16 v[10:13], v[142:145], v[214:217], v[10:13]
	v_mfma_f32_16x16x32_bf16 v[2:5], v[182:185], v[214:217], v[2:5]
	s_barrier
	s_setprio 0
	s_add_u32 s69, s69, 0x100
	s_addc_u32 s72, s72, 0
	s_add_u32 s20, s20, 0x100
	s_addc_u32 s21, s21, 0
	s_cmp_ge_i32 s62, s14
	s_mov_b32 s0, s62
	s_cbranch_scc0 .LBB0_551

; #define PG8_STAGE(bufoff, gbase, voff) do { _Pragma("unroll") for (int _i = 0; _i < 2; ++_i) \
;         __builtin_amdgcn_global_load_lds((const unsigned*)((const char*)(gbase) + (voff)[_i]), (LAS unsigned*)(lds + (bufoff) + ldsw + _i * 8192), 16, 0, 0); } while (0)
; #define PG8_LDA(dst, b, h) do { _Pragma("unroll") for (int m = 0; m < 4; ++m) _Pragma("unroll") for (int k = 0; k < 2; ++k) dst[m][k] = *(const LAS bf16x8*)(lds + PG8_SA(b, h) + aoff + m * 2048 + k * 1024); } while (0)
; #define PG8_LDB(dst, b, h) do { _Pragma("unroll") for (int n = 0; n < 2; ++n) _Pragma("unroll") for (int k = 0; k < 2; ++k) dst[n][k] = *(const LAS bf16x8*)(lds + PG8_SB(b, h) + boff + n * 2048 + k * 1024); } while (0)
; #define PG8_MMA(ai, bj, At, Bt) do { __builtin_amdgcn_s_setprio(1); _Pragma("unroll") for (int m = 0; m < 4; ++m) _Pragma("unroll") for (int n = 0; n < 2; ++n) _Pragma("unroll") for (int k = 0; k < 2; ++k) \
;         acc[ai][bj][m][n] = __builtin_amdgcn_mfma_f32_16x16x32_bf16(Bt[n][k], At[m][k], acc[ai][bj][m][n], 0, 0, 0); __builtin_amdgcn_s_setprio(0); } while (0)
; #define PG8_WAIT_V(n) asm volatile("s_waitcnt vmcnt(" #n ")" ::: "memory")
; template <class Epi, class Sched>
; __device__ __forceinline__ void gemm_phase(LAS unsigned char* lds, const Gemm g, const Sched& S, const Epi& E) {
;     ...
;         for (int t = 0; t < nt; t += 2) {
;             if constexpr (Epi::HOOKS) { if (cur.kind == 3 && (t == 4 || t == 12)) { int fr_ = fr, fq_ = fq; asm volatile("" : "+v"(fr_), "+v"(fq_)); E.hook(acc, cur, t == 4 ? 0 : 1, wr, wc, fr_, fq_); } }
;             const bool last = (t == nt - 2);
;             const char* a1 = cA + (size_t)(t + 1) * kstep;
;             const char* a2 = last ? nA : cA + (size_t)(t + 2) * kstep; const char* b2 = last ? nB : cB + (size_t)(t + 2) * kstep;
;             const char* a3 = a2 + kstep; const char* b3 = b2 + kstep;
;             PG8_LDB(B0, 0, 0); PG8_LDB(B1, 0, 1); PG8_SCHED; PG8_LDA(At, 0, 0); PG8_STAGE(PG8_SA(1, 1), a1 + hstepA, voffA);
;             PG8_WAIT_V(8); PG8_WAIT_L(0); PG8_BAR; PG8_MMA(0, 0, At, B0); PG8_MMA(0, 1, At, B1); PG8_BAR; PG8_SCHED;
;             PG8_LDA(At, 0, 1); PG8_STAGE(PG8_SB(0, 0), b2, voffB); PG8_STAGE(PG8_SB(0, 1), b2 + hstepB, voffB); PG8_STAGE(PG8_SA(0, 0), a2, voffA);
;             PG8_WAIT_V(8); PG8_WAIT_L(0); PG8_BAR; PG8_MMA(1, 0, At, B0); PG8_MMA(1, 1, At, B1); PG8_BAR; PG8_SCHED;
.LBB0_742:
	s_add_i32 s68, s0, 2
	s_add_u32 s1, s20, 0xfffc0080
	s_addc_u32 s44, s21, -1
	s_add_i32 s76, 0, 0x10000
	s_cmp_eq_u32 s69, s0
	s_cselect_b32 s45, s41, s44
	s_cselect_b32 s44, s43, s1
	s_cselect_b32 s1, s48, s77
	s_cselect_b32 s0, s53, s55
	s_add_i32 s82, 0, 0x14000
	v_add_u32_e32 v152, s76, v176
	v_add_u32_e32 v168, s82, v176
	ds_read_b128 v[140:143], v152
	ds_read_b128 v[144:147], v152 offset:1024
	ds_read_b128 v[148:151], v152 offset:2048
	ds_read_b128 v[152:155], v152 offset:3072
	ds_read_b128 v[156:159], v168
	ds_read_b128 v[160:163], v168 offset:1024
	ds_read_b128 v[164:167], v168 offset:2048
	ds_read_b128 v[168:171], v168 offset:3072
	v_lshl_add_u64 v[172:173], s[20:21], 0, v[138:139]
	s_add_i32 m0, s13, 0xc000
	ds_read_b128 v[178:181], v177
	ds_read_b128 v[182:185], v177 offset:1024
	ds_read_b128 v[196:199], v177 offset:2048
	ds_read_b128 v[200:203], v177 offset:3072
	ds_read_b128 v[204:207], v177 offset:4096
	ds_read_b128 v[208:211], v177 offset:5120
	ds_read_b128 v[212:215], v177 offset:6144
	ds_read_b128 v[216:219], v177 offset:7168
	global_load_lds_dwordx4 v[172:173], off
	v_lshl_add_u64 v[172:173], s[20:21], 0, v[136:137]
	s_add_i32 m0, s13, 0xe000
	s_nop 0
	global_load_lds_dwordx4 v[172:173], off
	s_waitcnt vmcnt(8)
	s_waitcnt lgkmcnt(0)
	s_setprio 1
	s_barrier
	v_mfma_f32_16x16x32_bf16 v[126:129], v[140:143], v[178:181], v[126:129]
	v_mfma_f32_16x16x32_bf16 v[122:125], v[148:151], v[178:181], v[122:125]
	v_mfma_f32_16x16x32_bf16 v[110:113], v[140:143], v[196:199], v[110:113]
	v_mfma_f32_16x16x32_bf16 v[106:109], v[148:151], v[196:199], v[106:109]
	v_mfma_f32_16x16x32_bf16 v[94:97], v[140:143], v[204:207], v[94:97]
	v_mfma_f32_16x16x32_bf16 v[90:93], v[148:151], v[204:207], v[90:93]
	v_mfma_f32_16x16x32_bf16 v[78:81], v[140:143], v[212:215], v[78:81]
	v_mfma_f32_16x16x32_bf16 v[74:77], v[148:151], v[212:215], v[74:77]
	v_mfma_f32_16x16x32_bf16 v[126:129], v[144:147], v[182:185], v[126:129]
	v_mfma_f32_16x16x32_bf16 v[122:125], v[152:155], v[182:185], v[122:125]
	v_mfma_f32_16x16x32_bf16 v[110:113], v[144:147], v[200:203], v[110:113]
	v_mfma_f32_16x16x32_bf16 v[106:109], v[152:155], v[200:203], v[106:109]
	v_mfma_f32_16x16x32_bf16 v[94:97], v[144:147], v[208:211], v[94:97]
	v_mfma_f32_16x16x32_bf16 v[90:93], v[152:155], v[208:211], v[90:93]
	v_mfma_f32_16x16x32_bf16 v[78:81], v[144:147], v[216:219], v[78:81]
	v_mfma_f32_16x16x32_bf16 v[74:77], v[152:155], v[216:219], v[74:77]
	v_mfma_f32_16x16x32_bf16 v[118:121], v[156:159], v[178:181], v[118:121]
	v_mfma_f32_16x16x32_bf16 v[114:117], v[164:167], v[178:181], v[114:117]
	v_mfma_f32_16x16x32_bf16 v[102:105], v[156:159], v[196:199], v[102:105]
	v_mfma_f32_16x16x32_bf16 v[98:101], v[164:167], v[196:199], v[98:101]
	v_mfma_f32_16x16x32_bf16 v[86:89], v[156:159], v[204:207], v[86:89]
	v_mfma_f32_16x16x32_bf16 v[82:85], v[164:167], v[204:207], v[82:85]
	v_mfma_f32_16x16x32_bf16 v[70:73], v[156:159], v[212:215], v[70:73]
	v_mfma_f32_16x16x32_bf16 v[66:69], v[164:167], v[212:215], v[66:69]
	v_mfma_f32_16x16x32_bf16 v[118:121], v[160:163], v[182:185], v[118:121]
	v_mfma_f32_16x16x32_bf16 v[114:117], v[168:171], v[182:185], v[114:117]
	v_mfma_f32_16x16x32_bf16 v[102:105], v[160:163], v[200:203], v[102:105]
	v_mfma_f32_16x16x32_bf16 v[98:101], v[168:171], v[200:203], v[98:101]
	v_mfma_f32_16x16x32_bf16 v[86:89], v[160:163], v[208:211], v[86:89]
	v_mfma_f32_16x16x32_bf16 v[82:85], v[168:171], v[208:211], v[82:85]
	v_mfma_f32_16x16x32_bf16 v[70:73], v[160:163], v[216:219], v[70:73]
	v_mfma_f32_16x16x32_bf16 v[66:69], v[168:171], v[216:219], v[66:69]
	s_barrier
	s_setprio 0
	s_add_i32 s76, s76, s12
	v_lshl_add_u64 v[172:173], s[0:1], 0, v[0:1]
	s_mov_b32 m0, s76
	ds_read_b128 v[178:181], v177 offset:16384
	ds_read_b128 v[182:185], v177 offset:17408
	ds_read_b128 v[196:199], v177 offset:18432
	ds_read_b128 v[200:203], v177 offset:19456
	ds_read_b128 v[204:207], v177 offset:20480
	ds_read_b128 v[208:211], v177 offset:21504
	ds_read_b128 v[212:215], v177 offset:22528
	ds_read_b128 v[216:219], v177 offset:23552
	global_load_lds_dwordx4 v[172:173], off
	s_add_i32 m0, s76, 0x2000
	s_add_u32 s80, s0, 0x40000
	v_lshl_add_u64 v[220:221], s[0:1], 0, v[134:135]
	s_addc_u32 s81, s1, 0
	s_add_i32 s76, s82, s12
	global_load_lds_dwordx4 v[220:221], off
	v_lshl_add_u64 v[232:233], s[80:81], 0, v[0:1]
	s_mov_b32 m0, s76
	v_lshl_add_u64 v[234:235], s[44:45], 0, v[132:133]
	global_load_lds_dwordx4 v[232:233], off
	v_lshl_add_u64 v[232:233], s[80:81], 0, v[134:135]
	s_add_i32 m0, s76, 0x2000
	s_nop 0
	global_load_lds_dwordx4 v[232:233], off
	v_lshl_add_u64 v[232:233], s[44:45], 0, v[130:131]
	s_mov_b32 m0, s13
	s_nop 0
	global_load_lds_dwordx4 v[232:233], off
	s_mov_b32 m0, s14
	s_nop 0
	global_load_lds_dwordx4 v[234:235], off
	s_waitcnt vmcnt(8)
	s_waitcnt lgkmcnt(0)
	s_setprio 1
	s_barrier
; #define PG8_STAGE(bufoff, gbase, voff) do { _Pragma("unroll") for (int _i = 0; _i < 2; ++_i) \
;         __builtin_amdgcn_global_load_lds((const unsigned*)((const char*)(gbase) + (voff)[_i]), (LAS unsigned*)(lds + (bufoff) + ldsw + _i * 8192), 16, 0, 0); } while (0)
; #define PG8_LDA(dst, b, h) do { _Pragma("unroll") for (int m = 0; m < 4; ++m) _Pragma("unroll") for (int k = 0; k < 2; ++k) dst[m][k] = *(const LAS bf16x8*)(lds + PG8_SA(b, h) + aoff + m * 2048 + k * 1024); } while (0)
; #define PG8_LDB(dst, b, h) do { _Pragma("unroll") for (int n = 0; n < 2; ++n) _Pragma("unroll") for (int k = 0; k < 2; ++k) dst[n][k] = *(const LAS bf16x8*)(lds + PG8_SB(b, h) + boff + n * 2048 + k * 1024); } while (0)
; #define PG8_MMA(ai, bj, At, Bt) do { __builtin_amdgcn_s_setprio(1); _Pragma("unroll") for (int m = 0; m < 4; ++m) _Pragma("unroll") for (int n = 0; n < 2; ++n) _Pragma("unroll") for (int k = 0; k < 2; ++k) \
;         acc[ai][bj][m][n] = __builtin_amdgcn_mfma_f32_16x16x32_bf16(Bt[n][k], At[m][k], acc[ai][bj][m][n], 0, 0, 0); __builtin_amdgcn_s_setprio(0); } while (0)
; #define PG8_WAIT_V(n) asm volatile("s_waitcnt vmcnt(" #n ")" ::: "memory")
; #define PG8_WAIT_L(n) asm volatile("s_waitcnt lgkmcnt(" #n ")" ::: "memory")
; #define PG8_BAR __builtin_amdgcn_s_barrier()
; #define PG8_SCHED __builtin_amdgcn_sched_barrier(0)
; template <class Epi, class Sched>
; __device__ __forceinline__ void gemm_phase(LAS unsigned char* lds, const Gemm g, const Sched& S, const Epi& E) {
;     ...
;             PG8_WAIT_V(8); PG8_WAIT_L(0); PG8_BAR; PG8_MMA(1, 0, At, B0); PG8_MMA(1, 1, At, B1); PG8_BAR; PG8_SCHED;
;             PG8_LDB(B0, 1, 0); PG8_LDB(B1, 1, 1); PG8_SCHED; PG8_LDA(At, 1, 0); PG8_STAGE(PG8_SA(0, 1), a2 + hstepA, voffA);
;             PG8_WAIT_V(8); PG8_WAIT_L(0); PG8_BAR; PG8_MMA(0, 0, At, B0); PG8_MMA(0, 1, At, B1); PG8_BAR; PG8_SCHED;
	v_mfma_f32_16x16x32_bf16 v[62:65], v[140:143], v[178:181], v[62:65]
	v_mfma_f32_16x16x32_bf16 v[58:61], v[148:151], v[178:181], v[58:61]
	v_mfma_f32_16x16x32_bf16 v[46:49], v[140:143], v[196:199], v[46:49]
	v_mfma_f32_16x16x32_bf16 v[42:45], v[148:151], v[196:199], v[42:45]
	v_mfma_f32_16x16x32_bf16 v[30:33], v[140:143], v[204:207], v[30:33]
	v_mfma_f32_16x16x32_bf16 v[26:29], v[148:151], v[204:207], v[26:29]
	v_mfma_f32_16x16x32_bf16 v[14:17], v[140:143], v[212:215], v[14:17]
	v_mfma_f32_16x16x32_bf16 v[10:13], v[148:151], v[212:215], v[10:13]
	v_mfma_f32_16x16x32_bf16 v[62:65], v[144:147], v[182:185], v[62:65]
	v_mfma_f32_16x16x32_bf16 v[58:61], v[152:155], v[182:185], v[58:61]
	v_mfma_f32_16x16x32_bf16 v[46:49], v[144:147], v[200:203], v[46:49]
	v_mfma_f32_16x16x32_bf16 v[42:45], v[152:155], v[200:203], v[42:45]
	v_mfma_f32_16x16x32_bf16 v[30:33], v[144:147], v[208:211], v[30:33]
	v_mfma_f32_16x16x32_bf16 v[26:29], v[152:155], v[208:211], v[26:29]
	v_mfma_f32_16x16x32_bf16 v[14:17], v[144:147], v[216:219], v[14:17]
	v_mfma_f32_16x16x32_bf16 v[10:13], v[152:155], v[216:219], v[10:13]
	v_mfma_f32_16x16x32_bf16 v[54:57], v[156:159], v[178:181], v[54:57]
	v_mfma_f32_16x16x32_bf16 v[50:53], v[164:167], v[178:181], v[50:53]
	v_mfma_f32_16x16x32_bf16 v[38:41], v[156:159], v[196:199], v[38:41]
	v_mfma_f32_16x16x32_bf16 v[34:37], v[164:167], v[196:199], v[34:37]
	v_mfma_f32_16x16x32_bf16 v[22:25], v[156:159], v[204:207], v[22:25]
	v_mfma_f32_16x16x32_bf16 v[18:21], v[164:167], v[204:207], v[18:21]
	v_mfma_f32_16x16x32_bf16 v[6:9], v[156:159], v[212:215], v[6:9]
	v_mfma_f32_16x16x32_bf16 v[2:5], v[164:167], v[212:215], v[2:5]
	v_mfma_f32_16x16x32_bf16 v[54:57], v[160:163], v[182:185], v[54:57]
	v_mfma_f32_16x16x32_bf16 v[50:53], v[168:171], v[182:185], v[50:53]
	v_mfma_f32_16x16x32_bf16 v[38:41], v[160:163], v[200:203], v[38:41]
	v_mfma_f32_16x16x32_bf16 v[34:37], v[168:171], v[200:203], v[34:37]
	v_mfma_f32_16x16x32_bf16 v[22:25], v[160:163], v[208:211], v[22:25]
	v_mfma_f32_16x16x32_bf16 v[18:21], v[168:171], v[208:211], v[18:21]
	v_mfma_f32_16x16x32_bf16 v[6:9], v[160:163], v[216:219], v[6:9]
	v_mfma_f32_16x16x32_bf16 v[2:5], v[168:171], v[216:219], v[2:5]
	s_barrier
	s_setprio 0
	s_add_i32 s76, 0, 0x18000
	s_add_i32 s80, 0, 0x1c000
	v_add_u32_e32 v152, s76, v176
	v_add_u32_e32 v168, s80, v176
	ds_read_b128 v[140:143], v152
	ds_read_b128 v[144:147], v152 offset:1024
	ds_read_b128 v[148:151], v152 offset:2048
	ds_read_b128 v[152:155], v152 offset:3072
	ds_read_b128 v[156:159], v168
	ds_read_b128 v[160:163], v168 offset:1024
	ds_read_b128 v[164:167], v168 offset:2048
	ds_read_b128 v[168:171], v168 offset:3072
	s_add_u32 s44, s44, 0x40000
	s_addc_u32 s45, s45, 0
	s_mov_b32 m0, s15
	v_lshl_add_u64 v[248:249], s[44:45], 0, v[130:131]
	ds_read_b128 v[178:181], v177 offset:32768
	ds_read_b128 v[182:185], v177 offset:33792
	ds_read_b128 v[196:199], v177 offset:34816
	ds_read_b128 v[200:203], v177 offset:35840
	ds_read_b128 v[204:207], v177 offset:36864
	ds_read_b128 v[208:211], v177 offset:37888
	ds_read_b128 v[212:215], v177 offset:38912
	ds_read_b128 v[216:219], v177 offset:39936
	global_load_lds_dwordx4 v[248:249], off
	v_lshl_add_u64 v[248:249], s[44:45], 0, v[132:133]
	s_mov_b32 m0, s16
	s_nop 0
	global_load_lds_dwordx4 v[248:249], off
	s_waitcnt vmcnt(8)
	s_waitcnt lgkmcnt(0)
	s_setprio 1
	s_barrier
	v_mfma_f32_16x16x32_bf16 v[126:129], v[140:143], v[178:181], v[126:129]
	v_mfma_f32_16x16x32_bf16 v[122:125], v[148:151], v[178:181], v[122:125]
	v_mfma_f32_16x16x32_bf16 v[110:113], v[140:143], v[196:199], v[110:113]
	v_mfma_f32_16x16x32_bf16 v[106:109], v[148:151], v[196:199], v[106:109]
	v_mfma_f32_16x16x32_bf16 v[94:97], v[140:143], v[204:207], v[94:97]
	v_mfma_f32_16x16x32_bf16 v[90:93], v[148:151], v[204:207], v[90:93]
	v_mfma_f32_16x16x32_bf16 v[78:81], v[140:143], v[212:215], v[78:81]
	v_mfma_f32_16x16x32_bf16 v[74:77], v[148:151], v[212:215], v[74:77]
	v_mfma_f32_16x16x32_bf16 v[126:129], v[144:147], v[182:185], v[126:129]
	v_mfma_f32_16x16x32_bf16 v[122:125], v[152:155], v[182:185], v[122:125]
	v_mfma_f32_16x16x32_bf16 v[110:113], v[144:147], v[200:203], v[110:113]
	v_mfma_f32_16x16x32_bf16 v[106:109], v[152:155], v[200:203], v[106:109]
	v_mfma_f32_16x16x32_bf16 v[94:97], v[144:147], v[208:211], v[94:97]
	v_mfma_f32_16x16x32_bf16 v[90:93], v[152:155], v[208:211], v[90:93]
	v_mfma_f32_16x16x32_bf16 v[78:81], v[144:147], v[216:219], v[78:81]
	v_mfma_f32_16x16x32_bf16 v[74:77], v[152:155], v[216:219], v[74:77]
	v_mfma_f32_16x16x32_bf16 v[118:121], v[156:159], v[178:181], v[118:121]
	v_mfma_f32_16x16x32_bf16 v[114:117], v[164:167], v[178:181], v[114:117]
	v_mfma_f32_16x16x32_bf16 v[102:105], v[156:159], v[196:199], v[102:105]
	v_mfma_f32_16x16x32_bf16 v[98:101], v[164:167], v[196:199], v[98:101]
	v_mfma_f32_16x16x32_bf16 v[86:89], v[156:159], v[204:207], v[86:89]
	v_mfma_f32_16x16x32_bf16 v[82:85], v[164:167], v[204:207], v[82:85]
	v_mfma_f32_16x16x32_bf16 v[70:73], v[156:159], v[212:215], v[70:73]
	v_mfma_f32_16x16x32_bf16 v[66:69], v[164:167], v[212:215], v[66:69]
	v_mfma_f32_16x16x32_bf16 v[118:121], v[160:163], v[182:185], v[118:121]
	v_mfma_f32_16x16x32_bf16 v[114:117], v[168:171], v[182:185], v[114:117]
	v_mfma_f32_16x16x32_bf16 v[102:105], v[160:163], v[200:203], v[102:105]
	v_mfma_f32_16x16x32_bf16 v[98:101], v[168:171], v[200:203], v[98:101]
	v_mfma_f32_16x16x32_bf16 v[86:89], v[160:163], v[208:211], v[86:89]
	v_mfma_f32_16x16x32_bf16 v[82:85], v[168:171], v[208:211], v[82:85]
	v_mfma_f32_16x16x32_bf16 v[70:73], v[160:163], v[216:219], v[70:73]
	v_mfma_f32_16x16x32_bf16 v[66:69], v[168:171], v[216:219], v[66:69]
	s_barrier
; #define PG8_STAGE(bufoff, gbase, voff) do { _Pragma("unroll") for (int _i = 0; _i < 2; ++_i) \
;         __builtin_amdgcn_global_load_lds((const unsigned*)((const char*)(gbase) + (voff)[_i]), (LAS unsigned*)(lds + (bufoff) + ldsw + _i * 8192), 16, 0, 0); } while (0)
; #define PG8_LDA(dst, b, h) do { _Pragma("unroll") for (int m = 0; m < 4; ++m) _Pragma("unroll") for (int k = 0; k < 2; ++k) dst[m][k] = *(const LAS bf16x8*)(lds + PG8_SA(b, h) + aoff + m * 2048 + k * 1024); } while (0)
; #define PG8_MMA(ai, bj, At, Bt) do { __builtin_amdgcn_s_setprio(1); _Pragma("unroll") for (int m = 0; m < 4; ++m) _Pragma("unroll") for (int n = 0; n < 2; ++n) _Pragma("unroll") for (int k = 0; k < 2; ++k) \
;         acc[ai][bj][m][n] = __builtin_amdgcn_mfma_f32_16x16x32_bf16(Bt[n][k], At[m][k], acc[ai][bj][m][n], 0, 0, 0); __builtin_amdgcn_s_setprio(0); } while (0)
; #define PG8_WAIT_V(n) asm volatile("s_waitcnt vmcnt(" #n ")" ::: "memory")
; #define PG8_WAIT_L(n) asm volatile("s_waitcnt lgkmcnt(" #n ")" ::: "memory")
; #define PG8_BAR __builtin_amdgcn_s_barrier()
; #define PG8_SCHED __builtin_amdgcn_sched_barrier(0)
; template <class Epi, class Sched>
; __device__ __forceinline__ void gemm_phase(LAS unsigned char* lds, const Gemm g, const Sched& S, const Epi& E) {
;     ...
;             PG8_LDA(At, 1, 1); PG8_STAGE(PG8_SB(1, 0), b3, voffB); PG8_STAGE(PG8_SB(1, 1), b3 + hstepB, voffB); PG8_STAGE(PG8_SA(1, 0), a3, voffA);
;             PG8_WAIT_V(8); PG8_WAIT_L(0); PG8_BAR; PG8_MMA(1, 0, At, B0); PG8_MMA(1, 1, At, B1); PG8_BAR; PG8_SCHED;
;         }
	s_setprio 0
	s_add_i32 s44, s76, s12
	v_lshl_add_u64 v[172:173], v[172:173], 0, s[26:27]
	s_mov_b32 m0, s44
	ds_read_b128 v[178:181], v177 offset:49152
	ds_read_b128 v[182:185], v177 offset:50176
	ds_read_b128 v[196:199], v177 offset:51200
	ds_read_b128 v[200:203], v177 offset:52224
	ds_read_b128 v[204:207], v177 offset:53248
	ds_read_b128 v[208:211], v177 offset:54272
	ds_read_b128 v[212:215], v177 offset:55296
	ds_read_b128 v[216:219], v177 offset:56320
	global_load_lds_dwordx4 v[172:173], off
	s_add_i32 m0, s44, 0x2000
	s_add_u32 s0, s0, 0x40080
	v_lshl_add_u64 v[172:173], v[220:221], 0, s[26:27]
	s_addc_u32 s1, s1, 0
	s_add_i32 s44, s80, s12
	global_load_lds_dwordx4 v[172:173], off
	v_lshl_add_u64 v[172:173], s[0:1], 0, v[0:1]
	s_mov_b32 m0, s44
	s_nop 0
	global_load_lds_dwordx4 v[172:173], off
	v_lshl_add_u64 v[172:173], s[0:1], 0, v[134:135]
	s_add_i32 m0, s44, 0x2000
	s_nop 0
	global_load_lds_dwordx4 v[172:173], off
	v_lshl_add_u64 v[172:173], v[232:233], 0, s[26:27]
	s_mov_b32 m0, s65
	s_nop 0
	global_load_lds_dwordx4 v[172:173], off
	v_lshl_add_u64 v[172:173], v[234:235], 0, s[26:27]
	s_mov_b32 m0, s67
	s_nop 0
	global_load_lds_dwordx4 v[172:173], off
	s_waitcnt vmcnt(8)
	s_waitcnt lgkmcnt(0)
	s_setprio 1
	s_barrier
	v_mfma_f32_16x16x32_bf16 v[62:65], v[140:143], v[178:181], v[62:65]
	v_mfma_f32_16x16x32_bf16 v[58:61], v[148:151], v[178:181], v[58:61]
	v_mfma_f32_16x16x32_bf16 v[46:49], v[140:143], v[196:199], v[46:49]
	v_mfma_f32_16x16x32_bf16 v[42:45], v[148:151], v[196:199], v[42:45]
	v_mfma_f32_16x16x32_bf16 v[30:33], v[140:143], v[204:207], v[30:33]
	v_mfma_f32_16x16x32_bf16 v[26:29], v[148:151], v[204:207], v[26:29]
	v_mfma_f32_16x16x32_bf16 v[14:17], v[140:143], v[212:215], v[14:17]
	v_mfma_f32_16x16x32_bf16 v[10:13], v[148:151], v[212:215], v[10:13]
	v_mfma_f32_16x16x32_bf16 v[62:65], v[144:147], v[182:185], v[62:65]
	v_mfma_f32_16x16x32_bf16 v[58:61], v[152:155], v[182:185], v[58:61]
	v_mfma_f32_16x16x32_bf16 v[46:49], v[144:147], v[200:203], v[46:49]
	v_mfma_f32_16x16x32_bf16 v[42:45], v[152:155], v[200:203], v[42:45]
	v_mfma_f32_16x16x32_bf16 v[30:33], v[144:147], v[208:211], v[30:33]
	v_mfma_f32_16x16x32_bf16 v[26:29], v[152:155], v[208:211], v[26:29]
	v_mfma_f32_16x16x32_bf16 v[14:17], v[144:147], v[216:219], v[14:17]
	v_mfma_f32_16x16x32_bf16 v[10:13], v[152:155], v[216:219], v[10:13]
	v_mfma_f32_16x16x32_bf16 v[54:57], v[156:159], v[178:181], v[54:57]
	v_mfma_f32_16x16x32_bf16 v[50:53], v[164:167], v[178:181], v[50:53]
	v_mfma_f32_16x16x32_bf16 v[38:41], v[156:159], v[196:199], v[38:41]
	v_mfma_f32_16x16x32_bf16 v[34:37], v[164:167], v[196:199], v[34:37]
	v_mfma_f32_16x16x32_bf16 v[22:25], v[156:159], v[204:207], v[22:25]
	v_mfma_f32_16x16x32_bf16 v[18:21], v[164:167], v[204:207], v[18:21]
	v_mfma_f32_16x16x32_bf16 v[6:9], v[156:159], v[212:215], v[6:9]
	v_mfma_f32_16x16x32_bf16 v[2:5], v[164:167], v[212:215], v[2:5]
	v_mfma_f32_16x16x32_bf16 v[54:57], v[160:163], v[182:185], v[54:57]
	v_mfma_f32_16x16x32_bf16 v[50:53], v[168:171], v[182:185], v[50:53]
	v_mfma_f32_16x16x32_bf16 v[38:41], v[160:163], v[200:203], v[38:41]
	v_mfma_f32_16x16x32_bf16 v[34:37], v[168:171], v[200:203], v[34:37]
	v_mfma_f32_16x16x32_bf16 v[22:25], v[160:163], v[208:211], v[22:25]
	v_mfma_f32_16x16x32_bf16 v[18:21], v[168:171], v[208:211], v[18:21]
	v_mfma_f32_16x16x32_bf16 v[6:9], v[160:163], v[216:219], v[6:9]
	v_mfma_f32_16x16x32_bf16 v[2:5], v[168:171], v[216:219], v[2:5]
	s_barrier
	s_setprio 0
	s_add_u32 s55, s55, 0x100
	s_addc_u32 s77, s77, 0
	s_add_u32 s20, s20, 0x100
	s_addc_u32 s21, s21, 0
	s_cmp_ge_i32 s68, s19
	s_mov_b32 s0, s68
	s_cbranch_scc0 .LBB0_742
